# baseline (speedup 1.0000x reference)
; #define PG8_STAGE(bufoff, gbase, voff) do { _Pragma("unroll") for (int _i = 0; _i < 2; ++_i) \
;         __builtin_amdgcn_global_load_lds((const unsigned*)((const char*)(gbase) + (voff)[_i]), (PG8_LAS unsigned*)(lds + (bufoff) + ldsw + _i * 8192), 16, 0, 0); } while (0)
; #define PG8_LDA(dst, b, h) do { _Pragma("unroll") for (int m = 0; m < 4; ++m) _Pragma("unroll") for (int k = 0; k < 2; ++k) dst[m][k] = *(const PG8_LAS bf16x8*)(lds + PG8_SA(b, h) + aoff + m * 2048 + k * 1024); } while (0)
; #define PG8_LDB(dst, b, h) do { _Pragma("unroll") for (int n = 0; n < 2; ++n) _Pragma("unroll") for (int k = 0; k < 2; ++k) dst[n][k] = *(const PG8_LAS bf16x8*)(lds + PG8_SB(b, h) + boff + n * 2048 + k * 1024); } while (0)
; #define PG8_WAIT_V(n) asm volatile("s_waitcnt vmcnt(" #n ")" ::: "memory")
; #define PG8_WAIT_L(n) asm volatile("s_waitcnt lgkmcnt(" #n ")" ::: "memory")
; #define PG8_BAR __builtin_amdgcn_s_barrier()
; template <class Epi, class Sched, bool ALIGN_EPI = false, bool SP2 = false>
; __device__ __forceinline__ void gemm_phase(PG8_LAS unsigned char* lds, const Gemm g, const Sched& S, const Epi& E) {
;     ...
;         const bool has_next = S.next(ui + 1, nxt);
;         const char* nA = has_next ? (const char*)g.A + (size_t)nxt.pm * tstep : cA; const char* nB = has_next ? (const char*)g.Bt + (size_t)nxt.pn * tstep : cB;
;         for (int t = 0; t < nt; t += 2) {
;             if constexpr (Epi::MID_HOOK) { if (t == Epi::MID_T) E.mid(acc, cur, wr, wc, fr, fq); }
;             const bool last = (t == nt - 2);
;             const char* a1 = cA + (size_t)(t + 1) * kstep;
;             const char* a2 = last ? nA : cA + (size_t)(t + 2) * kstep; const char* b2 = last ? nB : cB + (size_t)(t + 2) * kstep;
;             const char* a3 = a2 + kstep; const char* b3 = b2 + kstep;
;             if (last && has_next) S.a_ready(nxt);
;             if constexpr (SP2) {
;             PG8_LDB(B0, 0, 0); PG8_LDB(B1, 0, 1); PG8_SCHED; PG8_LDA(At, 0, 0); PG8_STAGE(PG8_SA(1, 1), a1 + hstep, voffA);
;             PG8_WAIT_V(8); PG8_WAIT_L(0); PG8_BAR; PG8_MMA(0, 0, At, B0); PG8_MMA(0, 1, At, B1); PG8_BAR; PG8_SCHED;
;             PG8_LDA(At, 0, 1); PG8_STAGE(PG8_SB(0, 0), b2, voffB); PG8_STAGE(PG8_SB(0, 1), b2 + hstep, voffB); PG8_STAGE(PG8_SA(0, 0), a2, voffA);
;             PG8_WAIT_V(8); PG8_WAIT_L(0); PG8_BAR; PG8_MMA(1, 0, At, B0); PG8_MMA(1, 1, At, B1); PG8_BAR; PG8_SCHED;
.LBB0_128:
	s_ashr_i32 s67, s66, 31
	s_lshl_b64 s[14:15], s[66:67], 20
	s_add_u32 s70, s37, s14
	s_addc_u32 s71, s38, s15
	s_and_b64 s[14:15], s[68:69], exec
	s_cselect_b32 s2, s71, s1
	s_cselect_b32 s11, s70, s0
	s_ashr_i32 s65, s64, 31
	s_lshl_b64 s[14:15], s[64:65], 20
	s_add_u32 s72, s31, s14
	s_addc_u32 s73, s36, s15
	s_and_b64 s[14:15], s[68:69], exec
	s_cselect_b32 s18, s73, s13
	s_cselect_b32 s19, s72, s12
	s_add_u32 s0, s0, 0x80080
	s_addc_u32 s1, s1, 0
	s_add_u32 s34, s12, 0x100
	s_addc_u32 s41, s13, 0
	s_mov_b32 s42, -2
	v_lshl_add_u64 v[194:195], s[0:1], 0, v[144:145]
	s_add_i32 m0, s74, 0xc000
	global_load_lds_dwordx4 v[194:195], off
	s_add_i32 m0, s74, 0xe000
	v_lshl_add_u64 v[194:195], s[0:1], 0, v[146:147]
	global_load_lds_dwordx4 v[194:195], off
	s_add_u32 s12, s0, 0xfff80080
	s_addc_u32 s13, s1, -1
	s_add_i32 s43, 0, 0x10000
	s_cmp_eq_u32 s42, 28
	s_cselect_b32 s15, s2, s13
	s_cselect_b32 s14, s11, s12
	s_cselect_b32 s13, s18, s41
	s_cselect_b32 s12, s19, s34
	s_add_i32 s65, 0, 0x14000
	s_waitcnt vmcnt(8)
	s_waitcnt lgkmcnt(0)
	s_barrier
	s_setprio 1
	s_waitcnt lgkmcnt(0)
	v_mfma_f32_16x16x32_bf16 v[124:127], v[128:131], v[172:175], 0
	v_mfma_f32_16x16x32_bf16 v[120:123], v[148:151], v[172:175], 0
	v_mfma_f32_16x16x32_bf16 v[108:111], v[128:131], v[184:187], 0
	v_mfma_f32_16x16x32_bf16 v[104:107], v[148:151], v[184:187], 0
	v_mfma_f32_16x16x32_bf16 v[92:95], v[128:131], v[206:209], 0
	v_mfma_f32_16x16x32_bf16 v[88:91], v[148:151], v[206:209], 0
	v_mfma_f32_16x16x32_bf16 v[76:79], v[128:131], v[214:217], 0
	v_mfma_f32_16x16x32_bf16 v[72:75], v[148:151], v[214:217], 0
	v_mfma_f32_16x16x32_bf16 v[124:127], v[132:135], v[180:183], v[124:127]
	v_mfma_f32_16x16x32_bf16 v[120:123], v[152:155], v[180:183], v[120:123]
	v_mfma_f32_16x16x32_bf16 v[108:111], v[132:135], v[188:191], v[108:111]
	v_mfma_f32_16x16x32_bf16 v[104:107], v[152:155], v[188:191], v[104:107]
	v_mfma_f32_16x16x32_bf16 v[92:95], v[132:135], v[210:213], v[92:95]
	v_mfma_f32_16x16x32_bf16 v[88:91], v[152:155], v[210:213], v[88:91]
	v_mfma_f32_16x16x32_bf16 v[76:79], v[132:135], v[218:221], v[76:79]
	v_mfma_f32_16x16x32_bf16 v[72:75], v[152:155], v[218:221], v[72:75]
	s_setprio 0
	s_setprio 1
	v_mfma_f32_16x16x32_bf16 v[116:119], v[156:159], v[172:175], 0
	v_mfma_f32_16x16x32_bf16 v[112:115], v[164:167], v[172:175], 0
	v_mfma_f32_16x16x32_bf16 v[100:103], v[156:159], v[184:187], 0
	v_mfma_f32_16x16x32_bf16 v[96:99], v[164:167], v[184:187], 0
	v_mfma_f32_16x16x32_bf16 v[84:87], v[156:159], v[206:209], 0
	v_mfma_f32_16x16x32_bf16 v[80:83], v[164:167], v[206:209], 0
	v_mfma_f32_16x16x32_bf16 v[68:71], v[156:159], v[214:217], 0
	v_mfma_f32_16x16x32_bf16 v[64:67], v[164:167], v[214:217], 0
	v_mfma_f32_16x16x32_bf16 v[116:119], v[160:163], v[180:183], v[116:119]
	v_mfma_f32_16x16x32_bf16 v[112:115], v[168:171], v[180:183], v[112:115]
	v_mfma_f32_16x16x32_bf16 v[100:103], v[160:163], v[188:191], v[100:103]
	v_mfma_f32_16x16x32_bf16 v[96:99], v[168:171], v[188:191], v[96:99]
	v_mfma_f32_16x16x32_bf16 v[84:87], v[160:163], v[210:213], v[84:87]
	s_barrier
	s_setprio 2
	v_mfma_f32_16x16x32_bf16 v[80:83], v[168:171], v[210:213], v[80:83]
	v_mfma_f32_16x16x32_bf16 v[68:71], v[160:163], v[218:221], v[68:71]
	v_mfma_f32_16x16x32_bf16 v[64:67], v[168:171], v[218:221], v[64:67]
	s_setprio 0
	s_add_i32 s43, s43, s39
	v_lshl_add_u64 v[194:195], s[12:13], 0, v[138:139]
	s_mov_b32 m0, s43
	s_nop 0
	global_load_lds_dwordx4 v[194:195], off
	s_add_i32 m0, s43, 0x2000
	s_add_u32 s86, s12, 0x80000
	v_lshl_add_u64 v[196:197], s[12:13], 0, v[142:143]
	s_addc_u32 s87, s13, 0
	s_add_i32 s43, s65, s39
	global_load_lds_dwordx4 v[196:197], off
	v_lshl_add_u64 v[202:203], s[86:87], 0, v[138:139]
	s_mov_b32 m0, s43
	v_lshl_add_u64 v[204:205], s[14:15], 0, v[140:141]
	global_load_lds_dwordx4 v[202:203], off
	s_add_i32 m0, s43, 0x2000
	v_lshl_add_u64 v[202:203], s[86:87], 0, v[142:143]
	global_load_lds_dwordx4 v[202:203], off
	s_mov_b32 m0, s74
	v_lshl_add_u64 v[202:203], s[14:15], 0, v[136:137]
	global_load_lds_dwordx4 v[202:203], off
	s_mov_b32 m0, s75
	s_nop 0
	global_load_lds_dwordx4 v[204:205], off
	ds_read_b128 v[172:175], v179 offset:16384
	ds_read_b128 v[180:183], v179 offset:17408
	ds_read_b128 v[184:187], v179 offset:18432
	ds_read_b128 v[188:191], v179 offset:19456
	ds_read_b128 v[206:209], v179 offset:20480
	ds_read_b128 v[210:213], v179 offset:21504
	ds_read_b128 v[214:217], v179 offset:22528
	ds_read_b128 v[218:221], v179 offset:23552
	s_waitcnt vmcnt(8)
	s_waitcnt lgkmcnt(0)
	s_barrier
	s_setprio 1
	s_waitcnt lgkmcnt(0)
	v_mfma_f32_16x16x32_bf16 v[60:63], v[128:131], v[172:175], 0
	v_mfma_f32_16x16x32_bf16 v[56:59], v[148:151], v[172:175], 0
	v_mfma_f32_16x16x32_bf16 v[44:47], v[128:131], v[184:187], 0
	v_mfma_f32_16x16x32_bf16 v[40:43], v[148:151], v[184:187], 0
	v_mfma_f32_16x16x32_bf16 v[28:31], v[128:131], v[206:209], 0
	v_mfma_f32_16x16x32_bf16 v[24:27], v[148:151], v[206:209], 0
	v_mfma_f32_16x16x32_bf16 v[12:15], v[128:131], v[214:217], 0
	v_mfma_f32_16x16x32_bf16 v[8:11], v[148:151], v[214:217], 0
	v_mfma_f32_16x16x32_bf16 v[60:63], v[132:135], v[180:183], v[60:63]
	v_mfma_f32_16x16x32_bf16 v[56:59], v[152:155], v[180:183], v[56:59]
	v_mfma_f32_16x16x32_bf16 v[44:47], v[132:135], v[188:191], v[44:47]
	v_mfma_f32_16x16x32_bf16 v[40:43], v[152:155], v[188:191], v[40:43]
	v_mfma_f32_16x16x32_bf16 v[28:31], v[132:135], v[210:213], v[28:31]
	v_mfma_f32_16x16x32_bf16 v[24:27], v[152:155], v[210:213], v[24:27]
	v_mfma_f32_16x16x32_bf16 v[12:15], v[132:135], v[218:221], v[12:15]
	v_mfma_f32_16x16x32_bf16 v[8:11], v[152:155], v[218:221], v[8:11]
	s_setprio 0
	s_setprio 1
	v_mfma_f32_16x16x32_bf16 v[52:55], v[156:159], v[172:175], 0
	v_mfma_f32_16x16x32_bf16 v[48:51], v[164:167], v[172:175], 0
	v_mfma_f32_16x16x32_bf16 v[36:39], v[156:159], v[184:187], 0
	v_mfma_f32_16x16x32_bf16 v[32:35], v[164:167], v[184:187], 0
	v_mfma_f32_16x16x32_bf16 v[20:23], v[156:159], v[206:209], 0
	v_mfma_f32_16x16x32_bf16 v[16:19], v[164:167], v[206:209], 0
	v_mfma_f32_16x16x32_bf16 v[4:7], v[156:159], v[214:217], 0
	v_mfma_f32_16x16x32_bf16 v[0:3], v[164:167], v[214:217], 0
	v_mfma_f32_16x16x32_bf16 v[52:55], v[160:163], v[180:183], v[52:55]
	v_mfma_f32_16x16x32_bf16 v[48:51], v[168:171], v[180:183], v[48:51]
	v_mfma_f32_16x16x32_bf16 v[36:39], v[160:163], v[188:191], v[36:39]
	v_mfma_f32_16x16x32_bf16 v[32:35], v[168:171], v[188:191], v[32:35]
	v_mfma_f32_16x16x32_bf16 v[20:23], v[160:163], v[210:213], v[20:23]
	s_barrier
; #define PG8_STAGE(bufoff, gbase, voff) do { _Pragma("unroll") for (int _i = 0; _i < 2; ++_i) \
;         __builtin_amdgcn_global_load_lds((const unsigned*)((const char*)(gbase) + (voff)[_i]), (PG8_LAS unsigned*)(lds + (bufoff) + ldsw + _i * 8192), 16, 0, 0); } while (0)
; #define PG8_LDA(dst, b, h) do { _Pragma("unroll") for (int m = 0; m < 4; ++m) _Pragma("unroll") for (int k = 0; k < 2; ++k) dst[m][k] = *(const PG8_LAS bf16x8*)(lds + PG8_SA(b, h) + aoff + m * 2048 + k * 1024); } while (0)
; #define PG8_LDB(dst, b, h) do { _Pragma("unroll") for (int n = 0; n < 2; ++n) _Pragma("unroll") for (int k = 0; k < 2; ++k) dst[n][k] = *(const PG8_LAS bf16x8*)(lds + PG8_SB(b, h) + boff + n * 2048 + k * 1024); } while (0)
; #define PG8_MMA(ai, bj, At, Bt) do { __builtin_amdgcn_s_setprio(1); _Pragma("unroll") for (int m = 0; m < 4; ++m) _Pragma("unroll") for (int n = 0; n < 2; ++n) _Pragma("unroll") for (int k = 0; k < 2; ++k) \
;         acc[ai][bj][m][n] = __builtin_amdgcn_mfma_f32_16x16x32_bf16(Bt[n][k], At[m][k], acc[ai][bj][m][n], 0, 0, 0); __builtin_amdgcn_s_setprio(0); } while (0)
; #define PG8_WAIT_V(n) asm volatile("s_waitcnt vmcnt(" #n ")" ::: "memory")
; #define PG8_WAIT_L(n) asm volatile("s_waitcnt lgkmcnt(" #n ")" ::: "memory")
; #define PG8_BAR __builtin_amdgcn_s_barrier()
; #define PG8_SCHED __builtin_amdgcn_sched_barrier(0)
; template <class Epi, class Sched, bool ALIGN_EPI = false, bool SP2 = false>
; __device__ __forceinline__ void gemm_phase(PG8_LAS unsigned char* lds, const Gemm g, const Sched& S, const Epi& E) {
;     ...
;             PG8_WAIT_V(8); PG8_WAIT_L(0); PG8_BAR; PG8_MMA(1, 0, At, B0); PG8_MMA(1, 1, At, B1); PG8_BAR; PG8_SCHED;
;             PG8_LDB(B0, 1, 0); PG8_LDB(B1, 1, 1); PG8_SCHED; PG8_LDA(At, 1, 0); PG8_STAGE(PG8_SA(0, 1), a2 + hstep, voffA);
;             PG8_WAIT_V(8); PG8_WAIT_L(0); PG8_BAR; PG8_MMA(0, 0, At, B0); PG8_MMA(0, 1, At, B1); PG8_BAR; PG8_SCHED;
;             PG8_LDA(At, 1, 1); PG8_STAGE(PG8_SB(1, 0), b3, voffB); PG8_STAGE(PG8_SB(1, 1), b3 + hstep, voffB); PG8_STAGE(PG8_SA(1, 0), a3, voffA);
	s_setprio 2
	v_mfma_f32_16x16x32_bf16 v[16:19], v[168:171], v[210:213], v[16:19]
	v_mfma_f32_16x16x32_bf16 v[4:7], v[160:163], v[218:221], v[4:7]
	v_mfma_f32_16x16x32_bf16 v[0:3], v[168:171], v[218:221], v[0:3]
	s_setprio 0
	s_add_i32 s43, 0, 0x18000
	s_add_i32 s65, 0, 0x1c000
	s_add_u32 s14, s14, 0x80000
	s_addc_u32 s15, s15, 0
	s_mov_b32 m0, s76
	v_lshl_add_u64 v[232:233], s[14:15], 0, v[136:137]
	global_load_lds_dwordx4 v[232:233], off
	s_mov_b32 m0, s77
	v_lshl_add_u64 v[232:233], s[14:15], 0, v[140:141]
	global_load_lds_dwordx4 v[232:233], off
	v_add_u32_e32 v152, 0x18000, v178
	v_add_u32_e32 v168, 0x1c000, v178
	ds_read_b128 v[128:131], v152
	ds_read_b128 v[132:135], v152 offset:1024
	ds_read_b128 v[148:151], v152 offset:2048
	ds_read_b128 v[152:155], v152 offset:3072
	ds_read_b128 v[156:159], v168
	ds_read_b128 v[160:163], v168 offset:1024
	ds_read_b128 v[164:167], v168 offset:2048
	ds_read_b128 v[168:171], v168 offset:3072
	ds_read_b128 v[172:175], v179 offset:32768
	ds_read_b128 v[180:183], v179 offset:33792
	ds_read_b128 v[184:187], v179 offset:34816
	ds_read_b128 v[188:191], v179 offset:35840
	ds_read_b128 v[206:209], v179 offset:36864
	ds_read_b128 v[210:213], v179 offset:37888
	ds_read_b128 v[214:217], v179 offset:38912
	ds_read_b128 v[218:221], v179 offset:39936
	s_waitcnt vmcnt(8)
	s_waitcnt lgkmcnt(0)
	s_barrier
	s_setprio 1
	s_waitcnt lgkmcnt(0)
	v_mfma_f32_16x16x32_bf16 v[124:127], v[128:131], v[172:175], v[124:127]
	v_mfma_f32_16x16x32_bf16 v[120:123], v[148:151], v[172:175], v[120:123]
	v_mfma_f32_16x16x32_bf16 v[108:111], v[128:131], v[184:187], v[108:111]
	v_mfma_f32_16x16x32_bf16 v[104:107], v[148:151], v[184:187], v[104:107]
	v_mfma_f32_16x16x32_bf16 v[92:95], v[128:131], v[206:209], v[92:95]
	v_mfma_f32_16x16x32_bf16 v[88:91], v[148:151], v[206:209], v[88:91]
	v_mfma_f32_16x16x32_bf16 v[76:79], v[128:131], v[214:217], v[76:79]
	v_mfma_f32_16x16x32_bf16 v[72:75], v[148:151], v[214:217], v[72:75]
	v_mfma_f32_16x16x32_bf16 v[124:127], v[132:135], v[180:183], v[124:127]
	v_mfma_f32_16x16x32_bf16 v[120:123], v[152:155], v[180:183], v[120:123]
	v_mfma_f32_16x16x32_bf16 v[108:111], v[132:135], v[188:191], v[108:111]
	v_mfma_f32_16x16x32_bf16 v[104:107], v[152:155], v[188:191], v[104:107]
	v_mfma_f32_16x16x32_bf16 v[92:95], v[132:135], v[210:213], v[92:95]
	v_mfma_f32_16x16x32_bf16 v[88:91], v[152:155], v[210:213], v[88:91]
	v_mfma_f32_16x16x32_bf16 v[76:79], v[132:135], v[218:221], v[76:79]
	v_mfma_f32_16x16x32_bf16 v[72:75], v[152:155], v[218:221], v[72:75]
	s_setprio 0
	s_setprio 1
	v_mfma_f32_16x16x32_bf16 v[116:119], v[156:159], v[172:175], v[116:119]
	v_mfma_f32_16x16x32_bf16 v[112:115], v[164:167], v[172:175], v[112:115]
	v_mfma_f32_16x16x32_bf16 v[100:103], v[156:159], v[184:187], v[100:103]
	v_mfma_f32_16x16x32_bf16 v[96:99], v[164:167], v[184:187], v[96:99]
	v_mfma_f32_16x16x32_bf16 v[84:87], v[156:159], v[206:209], v[84:87]
	v_mfma_f32_16x16x32_bf16 v[80:83], v[164:167], v[206:209], v[80:83]
	v_mfma_f32_16x16x32_bf16 v[68:71], v[156:159], v[214:217], v[68:71]
	v_mfma_f32_16x16x32_bf16 v[64:67], v[164:167], v[214:217], v[64:67]
	v_mfma_f32_16x16x32_bf16 v[116:119], v[160:163], v[180:183], v[116:119]
	v_mfma_f32_16x16x32_bf16 v[112:115], v[168:171], v[180:183], v[112:115]
	v_mfma_f32_16x16x32_bf16 v[100:103], v[160:163], v[188:191], v[100:103]
	v_mfma_f32_16x16x32_bf16 v[96:99], v[168:171], v[188:191], v[96:99]
	v_mfma_f32_16x16x32_bf16 v[84:87], v[160:163], v[210:213], v[84:87]
	s_barrier
	s_setprio 2
	v_mfma_f32_16x16x32_bf16 v[80:83], v[168:171], v[210:213], v[80:83]
	v_mfma_f32_16x16x32_bf16 v[68:71], v[160:163], v[218:221], v[68:71]
	v_mfma_f32_16x16x32_bf16 v[64:67], v[168:171], v[218:221], v[64:67]
	s_setprio 0
	s_add_i32 s14, s43, s39
	v_lshl_add_u64 v[194:195], v[194:195], 0, s[16:17]
	s_mov_b32 m0, s14
	s_nop 0
	global_load_lds_dwordx4 v[194:195], off
	s_add_i32 m0, s14, 0x2000
	s_add_u32 s12, s12, 0x80080
	v_lshl_add_u64 v[194:195], v[196:197], 0, s[16:17]
	s_addc_u32 s13, s13, 0
	s_add_i32 s14, s65, s39
	global_load_lds_dwordx4 v[194:195], off
	s_mov_b32 m0, s14
	v_lshl_add_u64 v[194:195], s[12:13], 0, v[138:139]
	global_load_lds_dwordx4 v[194:195], off
	s_add_i32 m0, s14, 0x2000
	v_lshl_add_u64 v[194:195], s[12:13], 0, v[142:143]
	global_load_lds_dwordx4 v[194:195], off
	s_mov_b32 m0, s80
	v_lshl_add_u64 v[194:195], v[202:203], 0, s[16:17]
	global_load_lds_dwordx4 v[194:195], off
	s_mov_b32 m0, s81
	v_lshl_add_u64 v[194:195], v[204:205], 0, s[16:17]
	global_load_lds_dwordx4 v[194:195], off
	ds_read_b128 v[172:175], v179 offset:49152
	ds_read_b128 v[180:183], v179 offset:50176
	ds_read_b128 v[184:187], v179 offset:51200
	ds_read_b128 v[188:191], v179 offset:52224
	ds_read_b128 v[206:209], v179 offset:53248
	ds_read_b128 v[210:213], v179 offset:54272
	ds_read_b128 v[214:217], v179 offset:55296
	ds_read_b128 v[218:221], v179 offset:56320
	s_waitcnt vmcnt(8)
	s_waitcnt lgkmcnt(0)
	s_barrier
; #define PG8_STAGE(bufoff, gbase, voff) do { _Pragma("unroll") for (int _i = 0; _i < 2; ++_i) \
;         __builtin_amdgcn_global_load_lds((const unsigned*)((const char*)(gbase) + (voff)[_i]), (PG8_LAS unsigned*)(lds + (bufoff) + ldsw + _i * 8192), 16, 0, 0); } while (0)
; #define PG8_LDA(dst, b, h) do { _Pragma("unroll") for (int m = 0; m < 4; ++m) _Pragma("unroll") for (int k = 0; k < 2; ++k) dst[m][k] = *(const PG8_LAS bf16x8*)(lds + PG8_SA(b, h) + aoff + m * 2048 + k * 1024); } while (0)
; #define PG8_LDB(dst, b, h) do { _Pragma("unroll") for (int n = 0; n < 2; ++n) _Pragma("unroll") for (int k = 0; k < 2; ++k) dst[n][k] = *(const PG8_LAS bf16x8*)(lds + PG8_SB(b, h) + boff + n * 2048 + k * 1024); } while (0)
; #define PG8_MMA(ai, bj, At, Bt) do { __builtin_amdgcn_s_setprio(1); _Pragma("unroll") for (int m = 0; m < 4; ++m) _Pragma("unroll") for (int n = 0; n < 2; ++n) _Pragma("unroll") for (int k = 0; k < 2; ++k) \
;         acc[ai][bj][m][n] = __builtin_amdgcn_mfma_f32_16x16x32_bf16(Bt[n][k], At[m][k], acc[ai][bj][m][n], 0, 0, 0); __builtin_amdgcn_s_setprio(0); } while (0)
; #define PG8_WAIT_V(n) asm volatile("s_waitcnt vmcnt(" #n ")" ::: "memory")
; template <class Epi, class Sched, bool ALIGN_EPI = false, bool SP2 = false>
; __device__ __forceinline__ void gemm_phase(PG8_LAS unsigned char* lds, const Gemm g, const Sched& S, const Epi& E) {
;     ...
;             PG8_LDB(B0, 0, 0); PG8_LDB(B1, 0, 1); PG8_SCHED; PG8_LDA(At, 0, 0); PG8_STAGE(PG8_SA(1, 1), a1 + hstep, voffA);
;             PG8_WAIT_V(8); PG8_WAIT_L(0); PG8_BAR; PG8_MMA(0, 0, At, B0); PG8_MMA(0, 1, At, B1); PG8_BAR; PG8_SCHED;
;             PG8_LDA(At, 0, 1); PG8_STAGE(PG8_SB(0, 0), b2, voffB); PG8_STAGE(PG8_SB(0, 1), b2 + hstep, voffB); PG8_STAGE(PG8_SA(0, 0), a2, voffA);
;             PG8_WAIT_V(8); PG8_WAIT_L(0); PG8_BAR; PG8_MMA(1, 0, At, B0); PG8_MMA(1, 1, At, B1); PG8_BAR; PG8_SCHED;
;             PG8_LDB(B0, 1, 0); PG8_LDB(B1, 1, 1); PG8_SCHED; PG8_LDA(At, 1, 0); PG8_STAGE(PG8_SA(0, 1), a2 + hstep, voffA);
;             PG8_WAIT_V(8); PG8_WAIT_L(0); PG8_BAR; PG8_MMA(0, 0, At, B0); PG8_MMA(0, 1, At, B1); PG8_BAR; PG8_SCHED;
;             PG8_LDA(At, 1, 1); PG8_STAGE(PG8_SB(1, 0), b3, voffB); PG8_STAGE(PG8_SB(1, 1), b3 + hstep, voffB); PG8_STAGE(PG8_SA(1, 0), a3, voffA);
;             PG8_WAIT_V(8); PG8_WAIT_L(0); PG8_BAR; PG8_MMA(1, 0, At, B0); PG8_MMA(1, 1, At, B1); PG8_BAR; PG8_SCHED;
	s_setprio 1
	s_waitcnt lgkmcnt(0)
	v_mfma_f32_16x16x32_bf16 v[60:63], v[128:131], v[172:175], v[60:63]
	v_mfma_f32_16x16x32_bf16 v[56:59], v[148:151], v[172:175], v[56:59]
	v_mfma_f32_16x16x32_bf16 v[44:47], v[128:131], v[184:187], v[44:47]
	v_mfma_f32_16x16x32_bf16 v[40:43], v[148:151], v[184:187], v[40:43]
	v_mfma_f32_16x16x32_bf16 v[28:31], v[128:131], v[206:209], v[28:31]
	v_mfma_f32_16x16x32_bf16 v[24:27], v[148:151], v[206:209], v[24:27]
	v_mfma_f32_16x16x32_bf16 v[12:15], v[128:131], v[214:217], v[12:15]
	v_mfma_f32_16x16x32_bf16 v[8:11], v[148:151], v[214:217], v[8:11]
	v_mfma_f32_16x16x32_bf16 v[60:63], v[132:135], v[180:183], v[60:63]
	v_mfma_f32_16x16x32_bf16 v[56:59], v[152:155], v[180:183], v[56:59]
	v_mfma_f32_16x16x32_bf16 v[44:47], v[132:135], v[188:191], v[44:47]
	v_mfma_f32_16x16x32_bf16 v[40:43], v[152:155], v[188:191], v[40:43]
	v_mfma_f32_16x16x32_bf16 v[28:31], v[132:135], v[210:213], v[28:31]
	v_mfma_f32_16x16x32_bf16 v[24:27], v[152:155], v[210:213], v[24:27]
	v_mfma_f32_16x16x32_bf16 v[12:15], v[132:135], v[218:221], v[12:15]
	v_mfma_f32_16x16x32_bf16 v[8:11], v[152:155], v[218:221], v[8:11]
	s_setprio 0
	s_setprio 1
	v_mfma_f32_16x16x32_bf16 v[52:55], v[156:159], v[172:175], v[52:55]
	v_mfma_f32_16x16x32_bf16 v[48:51], v[164:167], v[172:175], v[48:51]
	v_mfma_f32_16x16x32_bf16 v[36:39], v[156:159], v[184:187], v[36:39]
	v_mfma_f32_16x16x32_bf16 v[32:35], v[164:167], v[184:187], v[32:35]
	v_mfma_f32_16x16x32_bf16 v[20:23], v[156:159], v[206:209], v[20:23]
	v_mfma_f32_16x16x32_bf16 v[16:19], v[164:167], v[206:209], v[16:19]
	v_mfma_f32_16x16x32_bf16 v[4:7], v[156:159], v[214:217], v[4:7]
	v_mfma_f32_16x16x32_bf16 v[0:3], v[164:167], v[214:217], v[0:3]
	v_mfma_f32_16x16x32_bf16 v[52:55], v[160:163], v[180:183], v[52:55]
	v_mfma_f32_16x16x32_bf16 v[48:51], v[168:171], v[180:183], v[48:51]
	v_mfma_f32_16x16x32_bf16 v[36:39], v[160:163], v[188:191], v[36:39]
	v_mfma_f32_16x16x32_bf16 v[32:35], v[168:171], v[188:191], v[32:35]
	v_mfma_f32_16x16x32_bf16 v[20:23], v[160:163], v[210:213], v[20:23]
	s_barrier
	s_setprio 2
	v_mfma_f32_16x16x32_bf16 v[16:19], v[168:171], v[210:213], v[16:19]
	v_mfma_f32_16x16x32_bf16 v[4:7], v[160:163], v[218:221], v[4:7]
	v_mfma_f32_16x16x32_bf16 v[0:3], v[168:171], v[218:221], v[0:3]
	s_setprio 0
	s_add_i32 s42, s42, 2
	s_add_u32 s0, s0, 0x100
	s_addc_u32 s1, s1, 0
	s_add_u32 s34, s34, 0x100
	s_addc_u32 s41, s41, 0
	s_cmp_gt_u32 s42, 29
	s_branch .LBB0_129
.LBB0_129:
	v_lshl_add_u64 v[194:195], s[0:1], 0, v[144:145]
	s_add_i32 m0, s74, 0xc000
	s_nop 0
	global_load_lds_dwordx4 v[194:195], off
	s_add_i32 m0, s74, 0xe000
	v_lshl_add_u64 v[194:195], s[0:1], 0, v[146:147]
	global_load_lds_dwordx4 v[194:195], off
	s_add_u32 s12, s0, 0xfff80080
	s_addc_u32 s13, s1, -1
	s_add_i32 s43, 0, 0x10000
	s_cmp_eq_u32 s42, 28
	s_cselect_b32 s15, s2, s13
	s_cselect_b32 s14, s11, s12
	s_cselect_b32 s13, s18, s41
	s_cselect_b32 s12, s19, s34
	s_add_i32 s65, 0, 0x14000
	v_add_u32_e32 v152, 0x10000, v178
	v_add_u32_e32 v168, 0x14000, v178
	ds_read_b128 v[128:131], v152
	ds_read_b128 v[132:135], v152 offset:1024
	ds_read_b128 v[148:151], v152 offset:2048
	ds_read_b128 v[152:155], v152 offset:3072
	ds_read_b128 v[156:159], v168
	ds_read_b128 v[160:163], v168 offset:1024
	ds_read_b128 v[164:167], v168 offset:2048
	ds_read_b128 v[168:171], v168 offset:3072
	ds_read_b128 v[172:175], v179
	ds_read_b128 v[180:183], v179 offset:1024
	ds_read_b128 v[184:187], v179 offset:2048
	ds_read_b128 v[188:191], v179 offset:3072
	ds_read_b128 v[206:209], v179 offset:4096
	ds_read_b128 v[210:213], v179 offset:5120
	ds_read_b128 v[214:217], v179 offset:6144
	ds_read_b128 v[218:221], v179 offset:7168
	s_waitcnt vmcnt(8)
	s_waitcnt lgkmcnt(0)
	s_barrier
	s_setprio 1
	s_waitcnt lgkmcnt(0)
	v_mfma_f32_16x16x32_bf16 v[124:127], v[128:131], v[172:175], v[124:127]
	v_mfma_f32_16x16x32_bf16 v[120:123], v[148:151], v[172:175], v[120:123]
	v_mfma_f32_16x16x32_bf16 v[108:111], v[128:131], v[184:187], v[108:111]
	v_mfma_f32_16x16x32_bf16 v[104:107], v[148:151], v[184:187], v[104:107]
	v_mfma_f32_16x16x32_bf16 v[92:95], v[128:131], v[206:209], v[92:95]
	v_mfma_f32_16x16x32_bf16 v[88:91], v[148:151], v[206:209], v[88:91]
	v_mfma_f32_16x16x32_bf16 v[76:79], v[128:131], v[214:217], v[76:79]
	v_mfma_f32_16x16x32_bf16 v[72:75], v[148:151], v[214:217], v[72:75]
	v_mfma_f32_16x16x32_bf16 v[124:127], v[132:135], v[180:183], v[124:127]
	v_mfma_f32_16x16x32_bf16 v[120:123], v[152:155], v[180:183], v[120:123]
	v_mfma_f32_16x16x32_bf16 v[108:111], v[132:135], v[188:191], v[108:111]
	v_mfma_f32_16x16x32_bf16 v[104:107], v[152:155], v[188:191], v[104:107]
	v_mfma_f32_16x16x32_bf16 v[92:95], v[132:135], v[210:213], v[92:95]
	v_mfma_f32_16x16x32_bf16 v[88:91], v[152:155], v[210:213], v[88:91]
	v_mfma_f32_16x16x32_bf16 v[76:79], v[132:135], v[218:221], v[76:79]
	v_mfma_f32_16x16x32_bf16 v[72:75], v[152:155], v[218:221], v[72:75]
	s_setprio 0
	s_setprio 1
	v_mfma_f32_16x16x32_bf16 v[116:119], v[156:159], v[172:175], v[116:119]
	v_mfma_f32_16x16x32_bf16 v[112:115], v[164:167], v[172:175], v[112:115]
	v_mfma_f32_16x16x32_bf16 v[100:103], v[156:159], v[184:187], v[100:103]
	v_mfma_f32_16x16x32_bf16 v[96:99], v[164:167], v[184:187], v[96:99]
	v_mfma_f32_16x16x32_bf16 v[84:87], v[156:159], v[206:209], v[84:87]
	v_mfma_f32_16x16x32_bf16 v[80:83], v[164:167], v[206:209], v[80:83]
	v_mfma_f32_16x16x32_bf16 v[68:71], v[156:159], v[214:217], v[68:71]
	v_mfma_f32_16x16x32_bf16 v[64:67], v[164:167], v[214:217], v[64:67]
	v_mfma_f32_16x16x32_bf16 v[116:119], v[160:163], v[180:183], v[116:119]
	v_mfma_f32_16x16x32_bf16 v[112:115], v[168:171], v[180:183], v[112:115]
	v_mfma_f32_16x16x32_bf16 v[100:103], v[160:163], v[188:191], v[100:103]
	v_mfma_f32_16x16x32_bf16 v[96:99], v[168:171], v[188:191], v[96:99]
	v_mfma_f32_16x16x32_bf16 v[84:87], v[160:163], v[210:213], v[84:87]
	s_barrier
; #define PG8_STAGE(bufoff, gbase, voff) do { _Pragma("unroll") for (int _i = 0; _i < 2; ++_i) \
;         __builtin_amdgcn_global_load_lds((const unsigned*)((const char*)(gbase) + (voff)[_i]), (PG8_LAS unsigned*)(lds + (bufoff) + ldsw + _i * 8192), 16, 0, 0); } while (0)
; #define PG8_LDA(dst, b, h) do { _Pragma("unroll") for (int m = 0; m < 4; ++m) _Pragma("unroll") for (int k = 0; k < 2; ++k) dst[m][k] = *(const PG8_LAS bf16x8*)(lds + PG8_SA(b, h) + aoff + m * 2048 + k * 1024); } while (0)
; #define PG8_LDB(dst, b, h) do { _Pragma("unroll") for (int n = 0; n < 2; ++n) _Pragma("unroll") for (int k = 0; k < 2; ++k) dst[n][k] = *(const PG8_LAS bf16x8*)(lds + PG8_SB(b, h) + boff + n * 2048 + k * 1024); } while (0)
; #define PG8_MMA(ai, bj, At, Bt) do { __builtin_amdgcn_s_setprio(1); _Pragma("unroll") for (int m = 0; m < 4; ++m) _Pragma("unroll") for (int n = 0; n < 2; ++n) _Pragma("unroll") for (int k = 0; k < 2; ++k) \
;         acc[ai][bj][m][n] = __builtin_amdgcn_mfma_f32_16x16x32_bf16(Bt[n][k], At[m][k], acc[ai][bj][m][n], 0, 0, 0); __builtin_amdgcn_s_setprio(0); } while (0)
; #define PG8_WAIT_V(n) asm volatile("s_waitcnt vmcnt(" #n ")" ::: "memory")
; #define PG8_WAIT_L(n) asm volatile("s_waitcnt lgkmcnt(" #n ")" ::: "memory")
; #define PG8_BAR __builtin_amdgcn_s_barrier()
; #define PG8_SCHED __builtin_amdgcn_sched_barrier(0)
; template <class Epi, class Sched, bool ALIGN_EPI = false, bool SP2 = false>
; __device__ __forceinline__ void gemm_phase(PG8_LAS unsigned char* lds, const Gemm g, const Sched& S, const Epi& E) {
;     ...
;             PG8_WAIT_V(8); PG8_WAIT_L(0); PG8_BAR; PG8_MMA(0, 0, At, B0); PG8_MMA(0, 1, At, B1); PG8_BAR; PG8_SCHED;
;             PG8_LDA(At, 0, 1); PG8_STAGE(PG8_SB(0, 0), b2, voffB); PG8_STAGE(PG8_SB(0, 1), b2 + hstep, voffB); PG8_STAGE(PG8_SA(0, 0), a2, voffA);
;             PG8_WAIT_V(8); PG8_WAIT_L(0); PG8_BAR; PG8_MMA(1, 0, At, B0); PG8_MMA(1, 1, At, B1); PG8_BAR; PG8_SCHED;
;             PG8_LDB(B0, 1, 0); PG8_LDB(B1, 1, 1); PG8_SCHED; PG8_LDA(At, 1, 0); PG8_STAGE(PG8_SA(0, 1), a2 + hstep, voffA);
;             PG8_WAIT_V(8); PG8_WAIT_L(0); PG8_BAR; PG8_MMA(0, 0, At, B0); PG8_MMA(0, 1, At, B1); PG8_BAR; PG8_SCHED;
	s_setprio 2
	v_mfma_f32_16x16x32_bf16 v[80:83], v[168:171], v[210:213], v[80:83]
	v_mfma_f32_16x16x32_bf16 v[68:71], v[160:163], v[218:221], v[68:71]
	v_mfma_f32_16x16x32_bf16 v[64:67], v[168:171], v[218:221], v[64:67]
	s_setprio 0
	s_add_i32 s43, s43, s39
	v_lshl_add_u64 v[194:195], s[12:13], 0, v[138:139]
	s_mov_b32 m0, s43
	s_nop 0
	global_load_lds_dwordx4 v[194:195], off
	s_add_i32 m0, s43, 0x2000
	s_add_u32 s86, s12, 0x80000
	v_lshl_add_u64 v[196:197], s[12:13], 0, v[142:143]
	s_addc_u32 s87, s13, 0
	s_add_i32 s43, s65, s39
	global_load_lds_dwordx4 v[196:197], off
	v_lshl_add_u64 v[202:203], s[86:87], 0, v[138:139]
	s_mov_b32 m0, s43
	v_lshl_add_u64 v[204:205], s[14:15], 0, v[140:141]
	global_load_lds_dwordx4 v[202:203], off
	s_add_i32 m0, s43, 0x2000
	v_lshl_add_u64 v[202:203], s[86:87], 0, v[142:143]
	global_load_lds_dwordx4 v[202:203], off
	s_mov_b32 m0, s74
	v_lshl_add_u64 v[202:203], s[14:15], 0, v[136:137]
	global_load_lds_dwordx4 v[202:203], off
	s_mov_b32 m0, s75
	s_nop 0
	global_load_lds_dwordx4 v[204:205], off
	ds_read_b128 v[172:175], v179 offset:16384
	ds_read_b128 v[180:183], v179 offset:17408
	ds_read_b128 v[184:187], v179 offset:18432
	ds_read_b128 v[188:191], v179 offset:19456
	ds_read_b128 v[206:209], v179 offset:20480
	ds_read_b128 v[210:213], v179 offset:21504
	ds_read_b128 v[214:217], v179 offset:22528
	ds_read_b128 v[218:221], v179 offset:23552
	s_waitcnt vmcnt(8)
	s_waitcnt lgkmcnt(0)
	s_barrier
	s_setprio 1
	s_waitcnt lgkmcnt(0)
	v_mfma_f32_16x16x32_bf16 v[60:63], v[128:131], v[172:175], v[60:63]
	v_mfma_f32_16x16x32_bf16 v[56:59], v[148:151], v[172:175], v[56:59]
	v_mfma_f32_16x16x32_bf16 v[44:47], v[128:131], v[184:187], v[44:47]
	v_mfma_f32_16x16x32_bf16 v[40:43], v[148:151], v[184:187], v[40:43]
	v_mfma_f32_16x16x32_bf16 v[28:31], v[128:131], v[206:209], v[28:31]
	v_mfma_f32_16x16x32_bf16 v[24:27], v[148:151], v[206:209], v[24:27]
	v_mfma_f32_16x16x32_bf16 v[12:15], v[128:131], v[214:217], v[12:15]
	v_mfma_f32_16x16x32_bf16 v[8:11], v[148:151], v[214:217], v[8:11]
	v_mfma_f32_16x16x32_bf16 v[60:63], v[132:135], v[180:183], v[60:63]
	v_mfma_f32_16x16x32_bf16 v[56:59], v[152:155], v[180:183], v[56:59]
	v_mfma_f32_16x16x32_bf16 v[44:47], v[132:135], v[188:191], v[44:47]
	v_mfma_f32_16x16x32_bf16 v[40:43], v[152:155], v[188:191], v[40:43]
	v_mfma_f32_16x16x32_bf16 v[28:31], v[132:135], v[210:213], v[28:31]
	v_mfma_f32_16x16x32_bf16 v[24:27], v[152:155], v[210:213], v[24:27]
	v_mfma_f32_16x16x32_bf16 v[12:15], v[132:135], v[218:221], v[12:15]
	v_mfma_f32_16x16x32_bf16 v[8:11], v[152:155], v[218:221], v[8:11]
	s_setprio 0
	s_setprio 1
	v_mfma_f32_16x16x32_bf16 v[52:55], v[156:159], v[172:175], v[52:55]
	v_mfma_f32_16x16x32_bf16 v[48:51], v[164:167], v[172:175], v[48:51]
	v_mfma_f32_16x16x32_bf16 v[36:39], v[156:159], v[184:187], v[36:39]
	v_mfma_f32_16x16x32_bf16 v[32:35], v[164:167], v[184:187], v[32:35]
	v_mfma_f32_16x16x32_bf16 v[20:23], v[156:159], v[206:209], v[20:23]
	v_mfma_f32_16x16x32_bf16 v[16:19], v[164:167], v[206:209], v[16:19]
	v_mfma_f32_16x16x32_bf16 v[4:7], v[156:159], v[214:217], v[4:7]
	v_mfma_f32_16x16x32_bf16 v[0:3], v[164:167], v[214:217], v[0:3]
	v_mfma_f32_16x16x32_bf16 v[52:55], v[160:163], v[180:183], v[52:55]
	v_mfma_f32_16x16x32_bf16 v[48:51], v[168:171], v[180:183], v[48:51]
	v_mfma_f32_16x16x32_bf16 v[36:39], v[160:163], v[188:191], v[36:39]
	v_mfma_f32_16x16x32_bf16 v[32:35], v[168:171], v[188:191], v[32:35]
	v_mfma_f32_16x16x32_bf16 v[20:23], v[160:163], v[210:213], v[20:23]
	s_barrier
	s_setprio 2
	v_mfma_f32_16x16x32_bf16 v[16:19], v[168:171], v[210:213], v[16:19]
	v_mfma_f32_16x16x32_bf16 v[4:7], v[160:163], v[218:221], v[4:7]
	v_mfma_f32_16x16x32_bf16 v[0:3], v[168:171], v[218:221], v[0:3]
	s_setprio 0
	s_add_i32 s43, 0, 0x18000
	s_add_i32 s65, 0, 0x1c000
	s_add_u32 s14, s14, 0x80000
	s_addc_u32 s15, s15, 0
	s_mov_b32 m0, s76
	v_lshl_add_u64 v[232:233], s[14:15], 0, v[136:137]
	global_load_lds_dwordx4 v[232:233], off
	s_mov_b32 m0, s77
	v_lshl_add_u64 v[232:233], s[14:15], 0, v[140:141]
	global_load_lds_dwordx4 v[232:233], off
	v_add_u32_e32 v152, 0x18000, v178
	v_add_u32_e32 v168, 0x1c000, v178
	ds_read_b128 v[128:131], v152
	ds_read_b128 v[132:135], v152 offset:1024
	ds_read_b128 v[148:151], v152 offset:2048
	ds_read_b128 v[152:155], v152 offset:3072
	ds_read_b128 v[156:159], v168
	ds_read_b128 v[160:163], v168 offset:1024
	ds_read_b128 v[164:167], v168 offset:2048
	ds_read_b128 v[168:171], v168 offset:3072
	ds_read_b128 v[172:175], v179 offset:32768
	ds_read_b128 v[180:183], v179 offset:33792
	ds_read_b128 v[184:187], v179 offset:34816
	ds_read_b128 v[188:191], v179 offset:35840
	ds_read_b128 v[206:209], v179 offset:36864
	ds_read_b128 v[210:213], v179 offset:37888
	ds_read_b128 v[214:217], v179 offset:38912
	ds_read_b128 v[218:221], v179 offset:39936
	s_waitcnt vmcnt(8)
	s_waitcnt lgkmcnt(0)
	s_barrier
; #define PG8_STAGE(bufoff, gbase, voff) do { _Pragma("unroll") for (int _i = 0; _i < 2; ++_i) \
;         __builtin_amdgcn_global_load_lds((const unsigned*)((const char*)(gbase) + (voff)[_i]), (PG8_LAS unsigned*)(lds + (bufoff) + ldsw + _i * 8192), 16, 0, 0); } while (0)
; #define PG8_LDA(dst, b, h) do { _Pragma("unroll") for (int m = 0; m < 4; ++m) _Pragma("unroll") for (int k = 0; k < 2; ++k) dst[m][k] = *(const PG8_LAS bf16x8*)(lds + PG8_SA(b, h) + aoff + m * 2048 + k * 1024); } while (0)
; #define PG8_MMA(ai, bj, At, Bt) do { __builtin_amdgcn_s_setprio(1); _Pragma("unroll") for (int m = 0; m < 4; ++m) _Pragma("unroll") for (int n = 0; n < 2; ++n) _Pragma("unroll") for (int k = 0; k < 2; ++k) \
;         acc[ai][bj][m][n] = __builtin_amdgcn_mfma_f32_16x16x32_bf16(Bt[n][k], At[m][k], acc[ai][bj][m][n], 0, 0, 0); __builtin_amdgcn_s_setprio(0); } while (0)
; #define PG8_WAIT_V(n) asm volatile("s_waitcnt vmcnt(" #n ")" ::: "memory")
; #define PG8_WAIT_L(n) asm volatile("s_waitcnt lgkmcnt(" #n ")" ::: "memory")
; #define PG8_BAR __builtin_amdgcn_s_barrier()
; #define PG8_SCHED __builtin_amdgcn_sched_barrier(0)
; template <class Epi, class Sched, bool ALIGN_EPI = false, bool SP2 = false>
; __device__ __forceinline__ void gemm_phase(PG8_LAS unsigned char* lds, const Gemm g, const Sched& S, const Epi& E) {
;     ...
;             PG8_WAIT_V(8); PG8_WAIT_L(0); PG8_BAR; PG8_MMA(0, 0, At, B0); PG8_MMA(0, 1, At, B1); PG8_BAR; PG8_SCHED;
;             PG8_LDA(At, 1, 1); PG8_STAGE(PG8_SB(1, 0), b3, voffB); PG8_STAGE(PG8_SB(1, 1), b3 + hstep, voffB); PG8_STAGE(PG8_SA(1, 0), a3, voffA);
;             PG8_WAIT_V(8); PG8_WAIT_L(0); PG8_BAR; PG8_MMA(1, 0, At, B0); PG8_MMA(1, 1, At, B1); PG8_BAR; PG8_SCHED;
	s_setprio 1
	s_waitcnt lgkmcnt(0)
	v_mfma_f32_16x16x32_bf16 v[124:127], v[128:131], v[172:175], v[124:127]
	v_mfma_f32_16x16x32_bf16 v[120:123], v[148:151], v[172:175], v[120:123]
	v_mfma_f32_16x16x32_bf16 v[108:111], v[128:131], v[184:187], v[108:111]
	v_mfma_f32_16x16x32_bf16 v[104:107], v[148:151], v[184:187], v[104:107]
	v_mfma_f32_16x16x32_bf16 v[92:95], v[128:131], v[206:209], v[92:95]
	v_mfma_f32_16x16x32_bf16 v[88:91], v[148:151], v[206:209], v[88:91]
	v_mfma_f32_16x16x32_bf16 v[76:79], v[128:131], v[214:217], v[76:79]
	v_mfma_f32_16x16x32_bf16 v[72:75], v[148:151], v[214:217], v[72:75]
	v_mfma_f32_16x16x32_bf16 v[124:127], v[132:135], v[180:183], v[124:127]
	v_mfma_f32_16x16x32_bf16 v[120:123], v[152:155], v[180:183], v[120:123]
	v_mfma_f32_16x16x32_bf16 v[108:111], v[132:135], v[188:191], v[108:111]
	v_mfma_f32_16x16x32_bf16 v[104:107], v[152:155], v[188:191], v[104:107]
	v_mfma_f32_16x16x32_bf16 v[92:95], v[132:135], v[210:213], v[92:95]
	v_mfma_f32_16x16x32_bf16 v[88:91], v[152:155], v[210:213], v[88:91]
	v_mfma_f32_16x16x32_bf16 v[76:79], v[132:135], v[218:221], v[76:79]
	v_mfma_f32_16x16x32_bf16 v[72:75], v[152:155], v[218:221], v[72:75]
	s_setprio 0
	s_setprio 1
	v_mfma_f32_16x16x32_bf16 v[116:119], v[156:159], v[172:175], v[116:119]
	v_mfma_f32_16x16x32_bf16 v[112:115], v[164:167], v[172:175], v[112:115]
	v_mfma_f32_16x16x32_bf16 v[100:103], v[156:159], v[184:187], v[100:103]
	v_mfma_f32_16x16x32_bf16 v[96:99], v[164:167], v[184:187], v[96:99]
	v_mfma_f32_16x16x32_bf16 v[84:87], v[156:159], v[206:209], v[84:87]
	v_mfma_f32_16x16x32_bf16 v[80:83], v[164:167], v[206:209], v[80:83]
	v_mfma_f32_16x16x32_bf16 v[68:71], v[156:159], v[214:217], v[68:71]
	v_mfma_f32_16x16x32_bf16 v[64:67], v[164:167], v[214:217], v[64:67]
	v_mfma_f32_16x16x32_bf16 v[116:119], v[160:163], v[180:183], v[116:119]
	v_mfma_f32_16x16x32_bf16 v[112:115], v[168:171], v[180:183], v[112:115]
	v_mfma_f32_16x16x32_bf16 v[100:103], v[160:163], v[188:191], v[100:103]
	v_mfma_f32_16x16x32_bf16 v[96:99], v[168:171], v[188:191], v[96:99]
	v_mfma_f32_16x16x32_bf16 v[84:87], v[160:163], v[210:213], v[84:87]
	s_barrier
	s_setprio 2
	v_mfma_f32_16x16x32_bf16 v[80:83], v[168:171], v[210:213], v[80:83]
	v_mfma_f32_16x16x32_bf16 v[68:71], v[160:163], v[218:221], v[68:71]
	v_mfma_f32_16x16x32_bf16 v[64:67], v[168:171], v[218:221], v[64:67]
	s_setprio 0
	s_add_i32 s14, s43, s39
	v_lshl_add_u64 v[194:195], v[194:195], 0, s[16:17]
	s_mov_b32 m0, s14
	s_nop 0
	global_load_lds_dwordx4 v[194:195], off
	s_add_i32 m0, s14, 0x2000
	s_add_u32 s12, s12, 0x80080
	v_lshl_add_u64 v[194:195], v[196:197], 0, s[16:17]
	s_addc_u32 s13, s13, 0
	s_add_i32 s14, s65, s39
	global_load_lds_dwordx4 v[194:195], off
	s_mov_b32 m0, s14
	v_lshl_add_u64 v[194:195], s[12:13], 0, v[138:139]
	global_load_lds_dwordx4 v[194:195], off
	s_add_i32 m0, s14, 0x2000
	v_lshl_add_u64 v[194:195], s[12:13], 0, v[142:143]
	global_load_lds_dwordx4 v[194:195], off
	s_mov_b32 m0, s80
	v_lshl_add_u64 v[194:195], v[202:203], 0, s[16:17]
	global_load_lds_dwordx4 v[194:195], off
	s_mov_b32 m0, s81
	v_lshl_add_u64 v[194:195], v[204:205], 0, s[16:17]
	global_load_lds_dwordx4 v[194:195], off
	ds_read_b128 v[172:175], v179 offset:49152
	ds_read_b128 v[180:183], v179 offset:50176
	ds_read_b128 v[184:187], v179 offset:51200
	ds_read_b128 v[188:191], v179 offset:52224
	ds_read_b128 v[206:209], v179 offset:53248
	ds_read_b128 v[210:213], v179 offset:54272
	ds_read_b128 v[214:217], v179 offset:55296
	ds_read_b128 v[218:221], v179 offset:56320
	s_waitcnt vmcnt(8)
	s_waitcnt lgkmcnt(0)
	s_barrier
	s_setprio 1
	s_waitcnt lgkmcnt(0)
	v_mfma_f32_16x16x32_bf16 v[60:63], v[128:131], v[172:175], v[60:63]
	v_mfma_f32_16x16x32_bf16 v[56:59], v[148:151], v[172:175], v[56:59]
	v_mfma_f32_16x16x32_bf16 v[44:47], v[128:131], v[184:187], v[44:47]
	v_mfma_f32_16x16x32_bf16 v[40:43], v[148:151], v[184:187], v[40:43]
	v_mfma_f32_16x16x32_bf16 v[28:31], v[128:131], v[206:209], v[28:31]
	v_mfma_f32_16x16x32_bf16 v[24:27], v[148:151], v[206:209], v[24:27]
	v_mfma_f32_16x16x32_bf16 v[12:15], v[128:131], v[214:217], v[12:15]
	v_mfma_f32_16x16x32_bf16 v[8:11], v[148:151], v[214:217], v[8:11]
	v_mfma_f32_16x16x32_bf16 v[60:63], v[132:135], v[180:183], v[60:63]
	v_mfma_f32_16x16x32_bf16 v[56:59], v[152:155], v[180:183], v[56:59]
	v_mfma_f32_16x16x32_bf16 v[44:47], v[132:135], v[188:191], v[44:47]
	v_mfma_f32_16x16x32_bf16 v[40:43], v[152:155], v[188:191], v[40:43]
	v_mfma_f32_16x16x32_bf16 v[28:31], v[132:135], v[210:213], v[28:31]
	v_mfma_f32_16x16x32_bf16 v[24:27], v[152:155], v[210:213], v[24:27]
	v_mfma_f32_16x16x32_bf16 v[12:15], v[132:135], v[218:221], v[12:15]
	v_mfma_f32_16x16x32_bf16 v[8:11], v[152:155], v[218:221], v[8:11]
	s_setprio 0
	s_setprio 1
	v_mfma_f32_16x16x32_bf16 v[52:55], v[156:159], v[172:175], v[52:55]
	v_mfma_f32_16x16x32_bf16 v[48:51], v[164:167], v[172:175], v[48:51]
	v_mfma_f32_16x16x32_bf16 v[36:39], v[156:159], v[184:187], v[36:39]
	v_mfma_f32_16x16x32_bf16 v[32:35], v[164:167], v[184:187], v[32:35]
	v_mfma_f32_16x16x32_bf16 v[20:23], v[156:159], v[206:209], v[20:23]
	v_mfma_f32_16x16x32_bf16 v[16:19], v[164:167], v[206:209], v[16:19]
	v_mfma_f32_16x16x32_bf16 v[4:7], v[156:159], v[214:217], v[4:7]
	v_mfma_f32_16x16x32_bf16 v[0:3], v[164:167], v[214:217], v[0:3]
	v_mfma_f32_16x16x32_bf16 v[52:55], v[160:163], v[180:183], v[52:55]
	v_mfma_f32_16x16x32_bf16 v[48:51], v[168:171], v[180:183], v[48:51]
	v_mfma_f32_16x16x32_bf16 v[36:39], v[160:163], v[188:191], v[36:39]
	v_mfma_f32_16x16x32_bf16 v[32:35], v[168:171], v[188:191], v[32:35]
	v_mfma_f32_16x16x32_bf16 v[20:23], v[160:163], v[210:213], v[20:23]
	s_barrier
	s_setprio 2
	v_mfma_f32_16x16x32_bf16 v[16:19], v[168:171], v[210:213], v[16:19]
	v_mfma_f32_16x16x32_bf16 v[4:7], v[160:163], v[218:221], v[4:7]
	v_mfma_f32_16x16x32_bf16 v[0:3], v[168:171], v[218:221], v[0:3]
	s_setprio 0
	s_add_i32 s42, s42, 2
	s_add_u32 s0, s0, 0x100
	s_addc_u32 s1, s1, 0
	s_add_u32 s34, s34, 0x100
	s_addc_u32 s41, s41, 0
	s_cmp_gt_u32 s42, 29
	s_cbranch_scc0 .LBB0_129
	s_and_b64 vcc, exec, s[62:63]
	s_cbranch_vccz .LBB0_132
	s_barrier

; #define PG8_STAGE(bufoff, gbase, voff) do { _Pragma("unroll") for (int _i = 0; _i < 2; ++_i) \
;         __builtin_amdgcn_global_load_lds((const unsigned*)((const char*)(gbase) + (voff)[_i]), (PG8_LAS unsigned*)(lds + (bufoff) + ldsw + _i * 8192), 16, 0, 0); } while (0)
; #define PG8_LDA(dst, b, h) do { _Pragma("unroll") for (int m = 0; m < 4; ++m) _Pragma("unroll") for (int k = 0; k < 2; ++k) dst[m][k] = *(const PG8_LAS bf16x8*)(lds + PG8_SA(b, h) + aoff + m * 2048 + k * 1024); } while (0)
; #define PG8_LDB(dst, b, h) do { _Pragma("unroll") for (int n = 0; n < 2; ++n) _Pragma("unroll") for (int k = 0; k < 2; ++k) dst[n][k] = *(const PG8_LAS bf16x8*)(lds + PG8_SB(b, h) + boff + n * 2048 + k * 1024); } while (0)
; #define PG8_WAIT_V(n) asm volatile("s_waitcnt vmcnt(" #n ")" ::: "memory")
; #define PG8_WAIT_L(n) asm volatile("s_waitcnt lgkmcnt(" #n ")" ::: "memory")
; #define PG8_BAR __builtin_amdgcn_s_barrier()
; template <class Epi, class Sched, bool ALIGN_EPI = false, bool SP2 = false>
; __device__ __forceinline__ void gemm_phase(PG8_LAS unsigned char* lds, const Gemm g, const Sched& S, const Epi& E) {
;     ...
;         const bool has_next = S.next(ui + 1, nxt);
;         const char* nA = has_next ? (const char*)g.A + (size_t)nxt.pm * tstep : cA; const char* nB = has_next ? (const char*)g.Bt + (size_t)nxt.pn * tstep : cB;
;         for (int t = 0; t < nt; t += 2) {
;             if constexpr (Epi::MID_HOOK) { if (t == Epi::MID_T) E.mid(acc, cur, wr, wc, fr, fq); }
;             const bool last = (t == nt - 2);
;             const char* a1 = cA + (size_t)(t + 1) * kstep;
;             const char* a2 = last ? nA : cA + (size_t)(t + 2) * kstep; const char* b2 = last ? nB : cB + (size_t)(t + 2) * kstep;
;             const char* a3 = a2 + kstep; const char* b3 = b2 + kstep;
;             if (last && has_next) S.a_ready(nxt);
;             if constexpr (SP2) {
;             PG8_LDB(B0, 0, 0); PG8_LDB(B1, 0, 1); PG8_SCHED; PG8_LDA(At, 0, 0); PG8_STAGE(PG8_SA(1, 1), a1 + hstep, voffA);
;             PG8_WAIT_V(8); PG8_WAIT_L(0); PG8_BAR; PG8_MMA(0, 0, At, B0); PG8_MMA(0, 1, At, B1); PG8_BAR; PG8_SCHED;
;             PG8_LDA(At, 0, 1); PG8_STAGE(PG8_SB(0, 0), b2, voffB); PG8_STAGE(PG8_SB(0, 1), b2 + hstep, voffB); PG8_STAGE(PG8_SA(0, 0), a2, voffA);
;             PG8_WAIT_V(8); PG8_WAIT_L(0); PG8_BAR; PG8_MMA(1, 0, At, B0); PG8_MMA(1, 1, At, B1); PG8_BAR; PG8_SCHED;
.LBB0_634:
	s_ashr_i32 s15, s14, 31
	s_lshl_b64 s[18:19], s[14:15], 20
	s_add_u32 s18, s45, s18
	s_addc_u32 s19, s46, s19
	s_and_b64 s[30:31], s[0:1], exec
	s_cselect_b32 s15, s19, s37
	s_cselect_b32 s61, s18, s36
	s_ashr_i32 s13, s12, 31
	s_lshl_b64 s[30:31], s[12:13], 20
	s_add_u32 s30, s34, s30
	s_addc_u32 s31, s44, s31
	s_and_b64 s[42:43], s[0:1], exec
	s_cselect_b32 s13, s31, s39
	s_cselect_b32 s62, s30, s38
	s_add_u32 s36, s36, 0x80080
	s_addc_u32 s37, s37, 0
	s_add_u32 s63, s38, 0x100
	s_addc_u32 s64, s39, 0
	s_mov_b32 s65, -2
	s_waitcnt lgkmcnt(0)
	v_lshl_add_u64 v[168:169], s[36:37], 0, v[160:161]
	s_add_i32 m0, s2, 0xc000
	global_load_lds_dwordx4 v[168:169], off
	s_add_i32 m0, s2, 0xe000
	v_lshl_add_u64 v[168:169], s[36:37], 0, v[162:163]
	global_load_lds_dwordx4 v[168:169], off
	s_add_u32 s24, s36, 0xfff80080
	s_addc_u32 s25, s37, -1
	s_add_i32 s33, 0, 0x10000
	s_cmp_eq_u32 s65, 28
	s_cselect_b32 s43, s15, s25
	s_cselect_b32 s42, s61, s24
	s_cselect_b32 s39, s13, s64
	s_cselect_b32 s38, s62, s63
	s_add_i32 s24, 0, 0x14000
	s_waitcnt vmcnt(8)
	s_waitcnt lgkmcnt(0)
	s_barrier
	s_setprio 1
	s_waitcnt lgkmcnt(0)
	v_mfma_f32_16x16x32_bf16 v[124:127], v[128:131], v[178:181], 0
	v_mfma_f32_16x16x32_bf16 v[120:123], v[136:139], v[178:181], 0
	v_mfma_f32_16x16x32_bf16 v[108:111], v[128:131], v[186:189], 0
	v_mfma_f32_16x16x32_bf16 v[104:107], v[136:139], v[186:189], 0
	v_mfma_f32_16x16x32_bf16 v[92:95], v[128:131], v[202:205], 0
	v_mfma_f32_16x16x32_bf16 v[88:91], v[136:139], v[202:205], 0
	v_mfma_f32_16x16x32_bf16 v[76:79], v[128:131], v[210:213], 0
	v_mfma_f32_16x16x32_bf16 v[72:75], v[136:139], v[210:213], 0
	v_mfma_f32_16x16x32_bf16 v[124:127], v[132:135], v[182:185], v[124:127]
	v_mfma_f32_16x16x32_bf16 v[120:123], v[140:143], v[182:185], v[120:123]
	v_mfma_f32_16x16x32_bf16 v[108:111], v[132:135], v[194:197], v[108:111]
	v_mfma_f32_16x16x32_bf16 v[104:107], v[140:143], v[194:197], v[104:107]
	v_mfma_f32_16x16x32_bf16 v[92:95], v[132:135], v[206:209], v[92:95]
	v_mfma_f32_16x16x32_bf16 v[88:91], v[140:143], v[206:209], v[88:91]
	v_mfma_f32_16x16x32_bf16 v[76:79], v[132:135], v[214:217], v[76:79]
	v_mfma_f32_16x16x32_bf16 v[72:75], v[140:143], v[214:217], v[72:75]
	s_setprio 0
	s_setprio 1
	v_mfma_f32_16x16x32_bf16 v[116:119], v[144:147], v[178:181], 0
	v_mfma_f32_16x16x32_bf16 v[112:115], v[164:167], v[178:181], 0
	v_mfma_f32_16x16x32_bf16 v[100:103], v[144:147], v[186:189], 0
	v_mfma_f32_16x16x32_bf16 v[96:99], v[164:167], v[186:189], 0
	v_mfma_f32_16x16x32_bf16 v[84:87], v[144:147], v[202:205], 0
	v_mfma_f32_16x16x32_bf16 v[80:83], v[164:167], v[202:205], 0
	v_mfma_f32_16x16x32_bf16 v[68:71], v[144:147], v[210:213], 0
	v_mfma_f32_16x16x32_bf16 v[64:67], v[164:167], v[210:213], 0
	v_mfma_f32_16x16x32_bf16 v[116:119], v[148:151], v[182:185], v[116:119]
	v_mfma_f32_16x16x32_bf16 v[112:115], v[174:177], v[182:185], v[112:115]
	v_mfma_f32_16x16x32_bf16 v[100:103], v[148:151], v[194:197], v[100:103]
	v_mfma_f32_16x16x32_bf16 v[96:99], v[174:177], v[194:197], v[96:99]
	v_mfma_f32_16x16x32_bf16 v[84:87], v[148:151], v[206:209], v[84:87]
	s_barrier
	s_setprio 2
	v_mfma_f32_16x16x32_bf16 v[80:83], v[174:177], v[206:209], v[80:83]
	v_mfma_f32_16x16x32_bf16 v[68:71], v[148:151], v[214:217], v[68:71]
	v_mfma_f32_16x16x32_bf16 v[64:67], v[174:177], v[214:217], v[64:67]
	s_setprio 0
	s_add_i32 s25, s33, s47
	v_lshl_add_u64 v[168:169], s[38:39], 0, v[156:157]
	s_mov_b32 m0, s25
	s_nop 0
	global_load_lds_dwordx4 v[168:169], off
	s_add_i32 m0, s25, 0x2000
	s_add_u32 s66, s38, 0x80000
	v_lshl_add_u64 v[190:191], s[38:39], 0, v[152:153]
	s_addc_u32 s67, s39, 0
	s_add_i32 s24, s24, s47
	global_load_lds_dwordx4 v[190:191], off
	v_lshl_add_u64 v[218:219], s[66:67], 0, v[156:157]
	s_mov_b32 m0, s24
	v_lshl_add_u64 v[220:221], s[42:43], 0, v[154:155]
	global_load_lds_dwordx4 v[218:219], off
	s_add_i32 m0, s24, 0x2000
	v_lshl_add_u64 v[218:219], s[66:67], 0, v[152:153]
	global_load_lds_dwordx4 v[218:219], off
	s_mov_b32 m0, s2
	v_lshl_add_u64 v[218:219], s[42:43], 0, v[158:159]
	global_load_lds_dwordx4 v[218:219], off
	s_mov_b32 m0, s48
	s_nop 0
	global_load_lds_dwordx4 v[220:221], off
	ds_read_b128 v[178:181], v173 offset:16384
	ds_read_b128 v[182:185], v173 offset:17408
	ds_read_b128 v[186:189], v173 offset:18432
	ds_read_b128 v[194:197], v173 offset:19456
	ds_read_b128 v[202:205], v173 offset:20480
	ds_read_b128 v[206:209], v173 offset:21504
	ds_read_b128 v[210:213], v173 offset:22528
	ds_read_b128 v[214:217], v173 offset:23552
	s_waitcnt vmcnt(8)
	s_waitcnt lgkmcnt(0)
	s_barrier
	s_setprio 1
	s_waitcnt lgkmcnt(0)
	v_mfma_f32_16x16x32_bf16 v[60:63], v[128:131], v[178:181], 0
	v_mfma_f32_16x16x32_bf16 v[56:59], v[136:139], v[178:181], 0
	v_mfma_f32_16x16x32_bf16 v[44:47], v[128:131], v[186:189], 0
	v_mfma_f32_16x16x32_bf16 v[40:43], v[136:139], v[186:189], 0
	v_mfma_f32_16x16x32_bf16 v[28:31], v[128:131], v[202:205], 0
	v_mfma_f32_16x16x32_bf16 v[24:27], v[136:139], v[202:205], 0
	v_mfma_f32_16x16x32_bf16 v[12:15], v[128:131], v[210:213], 0
	v_mfma_f32_16x16x32_bf16 v[8:11], v[136:139], v[210:213], 0
	v_mfma_f32_16x16x32_bf16 v[60:63], v[132:135], v[182:185], v[60:63]
	v_mfma_f32_16x16x32_bf16 v[56:59], v[140:143], v[182:185], v[56:59]
	v_mfma_f32_16x16x32_bf16 v[44:47], v[132:135], v[194:197], v[44:47]
	v_mfma_f32_16x16x32_bf16 v[40:43], v[140:143], v[194:197], v[40:43]
	v_mfma_f32_16x16x32_bf16 v[28:31], v[132:135], v[206:209], v[28:31]
	v_mfma_f32_16x16x32_bf16 v[24:27], v[140:143], v[206:209], v[24:27]
	v_mfma_f32_16x16x32_bf16 v[12:15], v[132:135], v[214:217], v[12:15]
	v_mfma_f32_16x16x32_bf16 v[8:11], v[140:143], v[214:217], v[8:11]
	s_setprio 0
	s_setprio 1
	v_mfma_f32_16x16x32_bf16 v[52:55], v[144:147], v[178:181], 0
	v_mfma_f32_16x16x32_bf16 v[48:51], v[164:167], v[178:181], 0
	v_mfma_f32_16x16x32_bf16 v[36:39], v[144:147], v[186:189], 0
	v_mfma_f32_16x16x32_bf16 v[32:35], v[164:167], v[186:189], 0
	v_mfma_f32_16x16x32_bf16 v[20:23], v[144:147], v[202:205], 0
	v_mfma_f32_16x16x32_bf16 v[16:19], v[164:167], v[202:205], 0
	v_mfma_f32_16x16x32_bf16 v[4:7], v[144:147], v[210:213], 0
	v_mfma_f32_16x16x32_bf16 v[0:3], v[164:167], v[210:213], 0
	v_mfma_f32_16x16x32_bf16 v[52:55], v[148:151], v[182:185], v[52:55]
	v_mfma_f32_16x16x32_bf16 v[48:51], v[174:177], v[182:185], v[48:51]
	v_mfma_f32_16x16x32_bf16 v[36:39], v[148:151], v[194:197], v[36:39]
	v_mfma_f32_16x16x32_bf16 v[32:35], v[174:177], v[194:197], v[32:35]
	v_mfma_f32_16x16x32_bf16 v[20:23], v[148:151], v[206:209], v[20:23]
	s_barrier
; #define PG8_STAGE(bufoff, gbase, voff) do { _Pragma("unroll") for (int _i = 0; _i < 2; ++_i) \
;         __builtin_amdgcn_global_load_lds((const unsigned*)((const char*)(gbase) + (voff)[_i]), (PG8_LAS unsigned*)(lds + (bufoff) + ldsw + _i * 8192), 16, 0, 0); } while (0)
; #define PG8_LDA(dst, b, h) do { _Pragma("unroll") for (int m = 0; m < 4; ++m) _Pragma("unroll") for (int k = 0; k < 2; ++k) dst[m][k] = *(const PG8_LAS bf16x8*)(lds + PG8_SA(b, h) + aoff + m * 2048 + k * 1024); } while (0)
; #define PG8_LDB(dst, b, h) do { _Pragma("unroll") for (int n = 0; n < 2; ++n) _Pragma("unroll") for (int k = 0; k < 2; ++k) dst[n][k] = *(const PG8_LAS bf16x8*)(lds + PG8_SB(b, h) + boff + n * 2048 + k * 1024); } while (0)
; #define PG8_MMA(ai, bj, At, Bt) do { __builtin_amdgcn_s_setprio(1); _Pragma("unroll") for (int m = 0; m < 4; ++m) _Pragma("unroll") for (int n = 0; n < 2; ++n) _Pragma("unroll") for (int k = 0; k < 2; ++k) \
;         acc[ai][bj][m][n] = __builtin_amdgcn_mfma_f32_16x16x32_bf16(Bt[n][k], At[m][k], acc[ai][bj][m][n], 0, 0, 0); __builtin_amdgcn_s_setprio(0); } while (0)
; #define PG8_WAIT_V(n) asm volatile("s_waitcnt vmcnt(" #n ")" ::: "memory")
; #define PG8_WAIT_L(n) asm volatile("s_waitcnt lgkmcnt(" #n ")" ::: "memory")
; #define PG8_BAR __builtin_amdgcn_s_barrier()
; #define PG8_SCHED __builtin_amdgcn_sched_barrier(0)
; template <class Epi, class Sched, bool ALIGN_EPI = false, bool SP2 = false>
; __device__ __forceinline__ void gemm_phase(PG8_LAS unsigned char* lds, const Gemm g, const Sched& S, const Epi& E) {
;     ...
;             PG8_WAIT_V(8); PG8_WAIT_L(0); PG8_BAR; PG8_MMA(1, 0, At, B0); PG8_MMA(1, 1, At, B1); PG8_BAR; PG8_SCHED;
;             PG8_LDB(B0, 1, 0); PG8_LDB(B1, 1, 1); PG8_SCHED; PG8_LDA(At, 1, 0); PG8_STAGE(PG8_SA(0, 1), a2 + hstep, voffA);
;             PG8_WAIT_V(8); PG8_WAIT_L(0); PG8_BAR; PG8_MMA(0, 0, At, B0); PG8_MMA(0, 1, At, B1); PG8_BAR; PG8_SCHED;
;             PG8_LDA(At, 1, 1); PG8_STAGE(PG8_SB(1, 0), b3, voffB); PG8_STAGE(PG8_SB(1, 1), b3 + hstep, voffB); PG8_STAGE(PG8_SA(1, 0), a3, voffA);
	s_setprio 2
	v_mfma_f32_16x16x32_bf16 v[16:19], v[174:177], v[206:209], v[16:19]
	v_mfma_f32_16x16x32_bf16 v[4:7], v[148:151], v[214:217], v[4:7]
	v_mfma_f32_16x16x32_bf16 v[0:3], v[174:177], v[214:217], v[0:3]
	s_setprio 0
	s_add_i32 s24, 0, 0x18000
	s_add_i32 s25, 0, 0x1c000
	s_add_u32 s42, s42, 0x80000
	s_addc_u32 s43, s43, 0
	s_mov_b32 m0, s49
	v_lshl_add_u64 v[230:231], s[42:43], 0, v[158:159]
	global_load_lds_dwordx4 v[230:231], off
	s_mov_b32 m0, s50
	v_lshl_add_u64 v[230:231], s[42:43], 0, v[154:155]
	global_load_lds_dwordx4 v[230:231], off
	v_add_u32_e32 v140, 0x18000, v172
	v_add_u32_e32 v174, 0x1c000, v172
	ds_read_b128 v[128:131], v140
	ds_read_b128 v[132:135], v140 offset:1024
	ds_read_b128 v[136:139], v140 offset:2048
	ds_read_b128 v[140:143], v140 offset:3072
	ds_read_b128 v[144:147], v174
	ds_read_b128 v[148:151], v174 offset:1024
	ds_read_b128 v[164:167], v174 offset:2048
	ds_read_b128 v[174:177], v174 offset:3072
	ds_read_b128 v[178:181], v173 offset:32768
	ds_read_b128 v[182:185], v173 offset:33792
	ds_read_b128 v[186:189], v173 offset:34816
	ds_read_b128 v[194:197], v173 offset:35840
	ds_read_b128 v[202:205], v173 offset:36864
	ds_read_b128 v[206:209], v173 offset:37888
	ds_read_b128 v[210:213], v173 offset:38912
	ds_read_b128 v[214:217], v173 offset:39936
	s_waitcnt vmcnt(8)
	s_waitcnt lgkmcnt(0)
	s_barrier
	s_setprio 1
	s_waitcnt lgkmcnt(0)
	v_mfma_f32_16x16x32_bf16 v[124:127], v[128:131], v[178:181], v[124:127]
	v_mfma_f32_16x16x32_bf16 v[120:123], v[136:139], v[178:181], v[120:123]
	v_mfma_f32_16x16x32_bf16 v[108:111], v[128:131], v[186:189], v[108:111]
	v_mfma_f32_16x16x32_bf16 v[104:107], v[136:139], v[186:189], v[104:107]
	v_mfma_f32_16x16x32_bf16 v[92:95], v[128:131], v[202:205], v[92:95]
	v_mfma_f32_16x16x32_bf16 v[88:91], v[136:139], v[202:205], v[88:91]
	v_mfma_f32_16x16x32_bf16 v[76:79], v[128:131], v[210:213], v[76:79]
	v_mfma_f32_16x16x32_bf16 v[72:75], v[136:139], v[210:213], v[72:75]
	v_mfma_f32_16x16x32_bf16 v[124:127], v[132:135], v[182:185], v[124:127]
	v_mfma_f32_16x16x32_bf16 v[120:123], v[140:143], v[182:185], v[120:123]
	v_mfma_f32_16x16x32_bf16 v[108:111], v[132:135], v[194:197], v[108:111]
	v_mfma_f32_16x16x32_bf16 v[104:107], v[140:143], v[194:197], v[104:107]
	v_mfma_f32_16x16x32_bf16 v[92:95], v[132:135], v[206:209], v[92:95]
	v_mfma_f32_16x16x32_bf16 v[88:91], v[140:143], v[206:209], v[88:91]
	v_mfma_f32_16x16x32_bf16 v[76:79], v[132:135], v[214:217], v[76:79]
	v_mfma_f32_16x16x32_bf16 v[72:75], v[140:143], v[214:217], v[72:75]
	s_setprio 0
	s_setprio 1
	v_mfma_f32_16x16x32_bf16 v[116:119], v[144:147], v[178:181], v[116:119]
	v_mfma_f32_16x16x32_bf16 v[112:115], v[164:167], v[178:181], v[112:115]
	v_mfma_f32_16x16x32_bf16 v[100:103], v[144:147], v[186:189], v[100:103]
	v_mfma_f32_16x16x32_bf16 v[96:99], v[164:167], v[186:189], v[96:99]
	v_mfma_f32_16x16x32_bf16 v[84:87], v[144:147], v[202:205], v[84:87]
	v_mfma_f32_16x16x32_bf16 v[80:83], v[164:167], v[202:205], v[80:83]
	v_mfma_f32_16x16x32_bf16 v[68:71], v[144:147], v[210:213], v[68:71]
	v_mfma_f32_16x16x32_bf16 v[64:67], v[164:167], v[210:213], v[64:67]
	v_mfma_f32_16x16x32_bf16 v[116:119], v[148:151], v[182:185], v[116:119]
	v_mfma_f32_16x16x32_bf16 v[112:115], v[174:177], v[182:185], v[112:115]
	v_mfma_f32_16x16x32_bf16 v[100:103], v[148:151], v[194:197], v[100:103]
	v_mfma_f32_16x16x32_bf16 v[96:99], v[174:177], v[194:197], v[96:99]
	v_mfma_f32_16x16x32_bf16 v[84:87], v[148:151], v[206:209], v[84:87]
	s_barrier
	s_setprio 2
	v_mfma_f32_16x16x32_bf16 v[80:83], v[174:177], v[206:209], v[80:83]
	v_mfma_f32_16x16x32_bf16 v[68:71], v[148:151], v[214:217], v[68:71]
	v_mfma_f32_16x16x32_bf16 v[64:67], v[174:177], v[214:217], v[64:67]
	s_setprio 0
	s_add_i32 s24, s24, s47
	v_lshl_add_u64 v[168:169], v[168:169], 0, s[16:17]
	s_mov_b32 m0, s24
	s_nop 0
	global_load_lds_dwordx4 v[168:169], off
	s_add_i32 m0, s24, 0x2000
	s_add_u32 s38, s38, 0x80080
	v_lshl_add_u64 v[168:169], v[190:191], 0, s[16:17]
	s_addc_u32 s39, s39, 0
	s_add_i32 s24, s25, s47
	global_load_lds_dwordx4 v[168:169], off
	s_mov_b32 m0, s24
	v_lshl_add_u64 v[168:169], s[38:39], 0, v[156:157]
	global_load_lds_dwordx4 v[168:169], off
	s_add_i32 m0, s24, 0x2000
	v_lshl_add_u64 v[168:169], s[38:39], 0, v[152:153]
	global_load_lds_dwordx4 v[168:169], off
	s_mov_b32 m0, s55
	v_lshl_add_u64 v[168:169], v[218:219], 0, s[16:17]
	global_load_lds_dwordx4 v[168:169], off
	s_mov_b32 m0, s56
	v_lshl_add_u64 v[168:169], v[220:221], 0, s[16:17]
	global_load_lds_dwordx4 v[168:169], off
	ds_read_b128 v[178:181], v173 offset:49152
	ds_read_b128 v[182:185], v173 offset:50176
	ds_read_b128 v[186:189], v173 offset:51200
	ds_read_b128 v[194:197], v173 offset:52224
	ds_read_b128 v[202:205], v173 offset:53248
	ds_read_b128 v[206:209], v173 offset:54272
	ds_read_b128 v[210:213], v173 offset:55296
	ds_read_b128 v[214:217], v173 offset:56320
	s_waitcnt vmcnt(8)
	s_waitcnt lgkmcnt(0)
	s_barrier
; #define PG8_STAGE(bufoff, gbase, voff) do { _Pragma("unroll") for (int _i = 0; _i < 2; ++_i) \
;         __builtin_amdgcn_global_load_lds((const unsigned*)((const char*)(gbase) + (voff)[_i]), (PG8_LAS unsigned*)(lds + (bufoff) + ldsw + _i * 8192), 16, 0, 0); } while (0)
; #define PG8_LDA(dst, b, h) do { _Pragma("unroll") for (int m = 0; m < 4; ++m) _Pragma("unroll") for (int k = 0; k < 2; ++k) dst[m][k] = *(const PG8_LAS bf16x8*)(lds + PG8_SA(b, h) + aoff + m * 2048 + k * 1024); } while (0)
; #define PG8_LDB(dst, b, h) do { _Pragma("unroll") for (int n = 0; n < 2; ++n) _Pragma("unroll") for (int k = 0; k < 2; ++k) dst[n][k] = *(const PG8_LAS bf16x8*)(lds + PG8_SB(b, h) + boff + n * 2048 + k * 1024); } while (0)
; #define PG8_MMA(ai, bj, At, Bt) do { __builtin_amdgcn_s_setprio(1); _Pragma("unroll") for (int m = 0; m < 4; ++m) _Pragma("unroll") for (int n = 0; n < 2; ++n) _Pragma("unroll") for (int k = 0; k < 2; ++k) \
;         acc[ai][bj][m][n] = __builtin_amdgcn_mfma_f32_16x16x32_bf16(Bt[n][k], At[m][k], acc[ai][bj][m][n], 0, 0, 0); __builtin_amdgcn_s_setprio(0); } while (0)
; #define PG8_WAIT_V(n) asm volatile("s_waitcnt vmcnt(" #n ")" ::: "memory")
; template <class Epi, class Sched, bool ALIGN_EPI = false, bool SP2 = false>
; __device__ __forceinline__ void gemm_phase(PG8_LAS unsigned char* lds, const Gemm g, const Sched& S, const Epi& E) {
;     ...
;             PG8_LDB(B0, 0, 0); PG8_LDB(B1, 0, 1); PG8_SCHED; PG8_LDA(At, 0, 0); PG8_STAGE(PG8_SA(1, 1), a1 + hstep, voffA);
;             PG8_WAIT_V(8); PG8_WAIT_L(0); PG8_BAR; PG8_MMA(0, 0, At, B0); PG8_MMA(0, 1, At, B1); PG8_BAR; PG8_SCHED;
;             PG8_LDA(At, 0, 1); PG8_STAGE(PG8_SB(0, 0), b2, voffB); PG8_STAGE(PG8_SB(0, 1), b2 + hstep, voffB); PG8_STAGE(PG8_SA(0, 0), a2, voffA);
;             PG8_WAIT_V(8); PG8_WAIT_L(0); PG8_BAR; PG8_MMA(1, 0, At, B0); PG8_MMA(1, 1, At, B1); PG8_BAR; PG8_SCHED;
;             PG8_LDB(B0, 1, 0); PG8_LDB(B1, 1, 1); PG8_SCHED; PG8_LDA(At, 1, 0); PG8_STAGE(PG8_SA(0, 1), a2 + hstep, voffA);
;             PG8_WAIT_V(8); PG8_WAIT_L(0); PG8_BAR; PG8_MMA(0, 0, At, B0); PG8_MMA(0, 1, At, B1); PG8_BAR; PG8_SCHED;
;             PG8_LDA(At, 1, 1); PG8_STAGE(PG8_SB(1, 0), b3, voffB); PG8_STAGE(PG8_SB(1, 1), b3 + hstep, voffB); PG8_STAGE(PG8_SA(1, 0), a3, voffA);
;             PG8_WAIT_V(8); PG8_WAIT_L(0); PG8_BAR; PG8_MMA(1, 0, At, B0); PG8_MMA(1, 1, At, B1); PG8_BAR; PG8_SCHED;
	s_setprio 1
	s_waitcnt lgkmcnt(0)
	v_mfma_f32_16x16x32_bf16 v[60:63], v[128:131], v[178:181], v[60:63]
	v_mfma_f32_16x16x32_bf16 v[56:59], v[136:139], v[178:181], v[56:59]
	v_mfma_f32_16x16x32_bf16 v[44:47], v[128:131], v[186:189], v[44:47]
	v_mfma_f32_16x16x32_bf16 v[40:43], v[136:139], v[186:189], v[40:43]
	v_mfma_f32_16x16x32_bf16 v[28:31], v[128:131], v[202:205], v[28:31]
	v_mfma_f32_16x16x32_bf16 v[24:27], v[136:139], v[202:205], v[24:27]
	v_mfma_f32_16x16x32_bf16 v[12:15], v[128:131], v[210:213], v[12:15]
	v_mfma_f32_16x16x32_bf16 v[8:11], v[136:139], v[210:213], v[8:11]
	v_mfma_f32_16x16x32_bf16 v[60:63], v[132:135], v[182:185], v[60:63]
	v_mfma_f32_16x16x32_bf16 v[56:59], v[140:143], v[182:185], v[56:59]
	v_mfma_f32_16x16x32_bf16 v[44:47], v[132:135], v[194:197], v[44:47]
	v_mfma_f32_16x16x32_bf16 v[40:43], v[140:143], v[194:197], v[40:43]
	v_mfma_f32_16x16x32_bf16 v[28:31], v[132:135], v[206:209], v[28:31]
	v_mfma_f32_16x16x32_bf16 v[24:27], v[140:143], v[206:209], v[24:27]
	v_mfma_f32_16x16x32_bf16 v[12:15], v[132:135], v[214:217], v[12:15]
	v_mfma_f32_16x16x32_bf16 v[8:11], v[140:143], v[214:217], v[8:11]
	s_setprio 0
	s_setprio 1
	v_mfma_f32_16x16x32_bf16 v[52:55], v[144:147], v[178:181], v[52:55]
	v_mfma_f32_16x16x32_bf16 v[48:51], v[164:167], v[178:181], v[48:51]
	v_mfma_f32_16x16x32_bf16 v[36:39], v[144:147], v[186:189], v[36:39]
	v_mfma_f32_16x16x32_bf16 v[32:35], v[164:167], v[186:189], v[32:35]
	v_mfma_f32_16x16x32_bf16 v[20:23], v[144:147], v[202:205], v[20:23]
	v_mfma_f32_16x16x32_bf16 v[16:19], v[164:167], v[202:205], v[16:19]
	v_mfma_f32_16x16x32_bf16 v[4:7], v[144:147], v[210:213], v[4:7]
	v_mfma_f32_16x16x32_bf16 v[0:3], v[164:167], v[210:213], v[0:3]
	v_mfma_f32_16x16x32_bf16 v[52:55], v[148:151], v[182:185], v[52:55]
	v_mfma_f32_16x16x32_bf16 v[48:51], v[174:177], v[182:185], v[48:51]
	v_mfma_f32_16x16x32_bf16 v[36:39], v[148:151], v[194:197], v[36:39]
	v_mfma_f32_16x16x32_bf16 v[32:35], v[174:177], v[194:197], v[32:35]
	v_mfma_f32_16x16x32_bf16 v[20:23], v[148:151], v[206:209], v[20:23]
	s_barrier
	s_setprio 2
	v_mfma_f32_16x16x32_bf16 v[16:19], v[174:177], v[206:209], v[16:19]
	v_mfma_f32_16x16x32_bf16 v[4:7], v[148:151], v[214:217], v[4:7]
	v_mfma_f32_16x16x32_bf16 v[0:3], v[174:177], v[214:217], v[0:3]
	s_setprio 0
	s_add_i32 s65, s65, 2
	s_add_u32 s36, s36, 0x100
	s_addc_u32 s37, s37, 0
	s_add_u32 s63, s63, 0x100
	s_addc_u32 s64, s64, 0
	s_cmp_gt_u32 s65, 29
	s_branch .LBB0_635
.LBB0_635:
	v_add_u32_e32 v140, 0x10000, v172
	v_add_u32_e32 v168, 0x14000, v172
	ds_read_b128 v[128:131], v140
	ds_read_b128 v[132:135], v140 offset:1024
	ds_read_b128 v[136:139], v140 offset:2048
	ds_read_b128 v[140:143], v140 offset:3072
	ds_read_b128 v[144:147], v168
	ds_read_b128 v[148:151], v168 offset:1024
	ds_read_b128 v[164:167], v168 offset:2048
	ds_read_b128 v[174:177], v168 offset:3072
	v_lshl_add_u64 v[168:169], s[36:37], 0, v[160:161]
	s_add_i32 m0, s2, 0xc000
	ds_read_b128 v[178:181], v173
	ds_read_b128 v[182:185], v173 offset:1024
	ds_read_b128 v[186:189], v173 offset:2048
	ds_read_b128 v[194:197], v173 offset:3072
	ds_read_b128 v[202:205], v173 offset:4096
	ds_read_b128 v[206:209], v173 offset:5120
	ds_read_b128 v[210:213], v173 offset:6144
	ds_read_b128 v[214:217], v173 offset:7168
	global_load_lds_dwordx4 v[168:169], off
	s_add_i32 m0, s2, 0xe000
	v_lshl_add_u64 v[168:169], s[36:37], 0, v[162:163]
	global_load_lds_dwordx4 v[168:169], off
	s_add_u32 s24, s36, 0xfff80080
	s_addc_u32 s25, s37, -1
	s_add_i32 s33, 0, 0x10000
	s_cmp_eq_u32 s65, 28
	s_cselect_b32 s43, s15, s25
	s_cselect_b32 s42, s61, s24
	s_cselect_b32 s39, s13, s64
	s_cselect_b32 s38, s62, s63
	s_add_i32 s24, 0, 0x14000
	s_waitcnt vmcnt(8)
	s_waitcnt lgkmcnt(0)
	s_barrier
	s_setprio 1
	s_waitcnt lgkmcnt(0)
	v_mfma_f32_16x16x32_bf16 v[124:127], v[128:131], v[178:181], v[124:127]
	v_mfma_f32_16x16x32_bf16 v[120:123], v[136:139], v[178:181], v[120:123]
	v_mfma_f32_16x16x32_bf16 v[108:111], v[128:131], v[186:189], v[108:111]
	v_mfma_f32_16x16x32_bf16 v[104:107], v[136:139], v[186:189], v[104:107]
	v_mfma_f32_16x16x32_bf16 v[92:95], v[128:131], v[202:205], v[92:95]
	v_mfma_f32_16x16x32_bf16 v[88:91], v[136:139], v[202:205], v[88:91]
	v_mfma_f32_16x16x32_bf16 v[76:79], v[128:131], v[210:213], v[76:79]
	v_mfma_f32_16x16x32_bf16 v[72:75], v[136:139], v[210:213], v[72:75]
	v_mfma_f32_16x16x32_bf16 v[124:127], v[132:135], v[182:185], v[124:127]
	v_mfma_f32_16x16x32_bf16 v[120:123], v[140:143], v[182:185], v[120:123]
	v_mfma_f32_16x16x32_bf16 v[108:111], v[132:135], v[194:197], v[108:111]
	v_mfma_f32_16x16x32_bf16 v[104:107], v[140:143], v[194:197], v[104:107]
	v_mfma_f32_16x16x32_bf16 v[92:95], v[132:135], v[206:209], v[92:95]
	v_mfma_f32_16x16x32_bf16 v[88:91], v[140:143], v[206:209], v[88:91]
	v_mfma_f32_16x16x32_bf16 v[76:79], v[132:135], v[214:217], v[76:79]
	v_mfma_f32_16x16x32_bf16 v[72:75], v[140:143], v[214:217], v[72:75]
	s_setprio 0
	s_setprio 1
	v_mfma_f32_16x16x32_bf16 v[116:119], v[144:147], v[178:181], v[116:119]
	v_mfma_f32_16x16x32_bf16 v[112:115], v[164:167], v[178:181], v[112:115]
	v_mfma_f32_16x16x32_bf16 v[100:103], v[144:147], v[186:189], v[100:103]
	v_mfma_f32_16x16x32_bf16 v[96:99], v[164:167], v[186:189], v[96:99]
	v_mfma_f32_16x16x32_bf16 v[84:87], v[144:147], v[202:205], v[84:87]
	v_mfma_f32_16x16x32_bf16 v[80:83], v[164:167], v[202:205], v[80:83]
	v_mfma_f32_16x16x32_bf16 v[68:71], v[144:147], v[210:213], v[68:71]
	v_mfma_f32_16x16x32_bf16 v[64:67], v[164:167], v[210:213], v[64:67]
	v_mfma_f32_16x16x32_bf16 v[116:119], v[148:151], v[182:185], v[116:119]
	v_mfma_f32_16x16x32_bf16 v[112:115], v[174:177], v[182:185], v[112:115]
	v_mfma_f32_16x16x32_bf16 v[100:103], v[148:151], v[194:197], v[100:103]
	v_mfma_f32_16x16x32_bf16 v[96:99], v[174:177], v[194:197], v[96:99]
	v_mfma_f32_16x16x32_bf16 v[84:87], v[148:151], v[206:209], v[84:87]
	s_barrier
; #define PG8_STAGE(bufoff, gbase, voff) do { _Pragma("unroll") for (int _i = 0; _i < 2; ++_i) \
;         __builtin_amdgcn_global_load_lds((const unsigned*)((const char*)(gbase) + (voff)[_i]), (PG8_LAS unsigned*)(lds + (bufoff) + ldsw + _i * 8192), 16, 0, 0); } while (0)
; #define PG8_LDA(dst, b, h) do { _Pragma("unroll") for (int m = 0; m < 4; ++m) _Pragma("unroll") for (int k = 0; k < 2; ++k) dst[m][k] = *(const PG8_LAS bf16x8*)(lds + PG8_SA(b, h) + aoff + m * 2048 + k * 1024); } while (0)
; #define PG8_LDB(dst, b, h) do { _Pragma("unroll") for (int n = 0; n < 2; ++n) _Pragma("unroll") for (int k = 0; k < 2; ++k) dst[n][k] = *(const PG8_LAS bf16x8*)(lds + PG8_SB(b, h) + boff + n * 2048 + k * 1024); } while (0)
; #define PG8_MMA(ai, bj, At, Bt) do { __builtin_amdgcn_s_setprio(1); _Pragma("unroll") for (int m = 0; m < 4; ++m) _Pragma("unroll") for (int n = 0; n < 2; ++n) _Pragma("unroll") for (int k = 0; k < 2; ++k) \
;         acc[ai][bj][m][n] = __builtin_amdgcn_mfma_f32_16x16x32_bf16(Bt[n][k], At[m][k], acc[ai][bj][m][n], 0, 0, 0); __builtin_amdgcn_s_setprio(0); } while (0)
; #define PG8_WAIT_V(n) asm volatile("s_waitcnt vmcnt(" #n ")" ::: "memory")
; #define PG8_WAIT_L(n) asm volatile("s_waitcnt lgkmcnt(" #n ")" ::: "memory")
; #define PG8_BAR __builtin_amdgcn_s_barrier()
; #define PG8_SCHED __builtin_amdgcn_sched_barrier(0)
; template <class Epi, class Sched, bool ALIGN_EPI = false, bool SP2 = false>
; __device__ __forceinline__ void gemm_phase(PG8_LAS unsigned char* lds, const Gemm g, const Sched& S, const Epi& E) {
;     ...
;             PG8_WAIT_V(8); PG8_WAIT_L(0); PG8_BAR; PG8_MMA(0, 0, At, B0); PG8_MMA(0, 1, At, B1); PG8_BAR; PG8_SCHED;
;             PG8_LDA(At, 0, 1); PG8_STAGE(PG8_SB(0, 0), b2, voffB); PG8_STAGE(PG8_SB(0, 1), b2 + hstep, voffB); PG8_STAGE(PG8_SA(0, 0), a2, voffA);
;             PG8_WAIT_V(8); PG8_WAIT_L(0); PG8_BAR; PG8_MMA(1, 0, At, B0); PG8_MMA(1, 1, At, B1); PG8_BAR; PG8_SCHED;
;             PG8_LDB(B0, 1, 0); PG8_LDB(B1, 1, 1); PG8_SCHED; PG8_LDA(At, 1, 0); PG8_STAGE(PG8_SA(0, 1), a2 + hstep, voffA);
;             PG8_WAIT_V(8); PG8_WAIT_L(0); PG8_BAR; PG8_MMA(0, 0, At, B0); PG8_MMA(0, 1, At, B1); PG8_BAR; PG8_SCHED;
	s_setprio 2
	v_mfma_f32_16x16x32_bf16 v[80:83], v[174:177], v[206:209], v[80:83]
	v_mfma_f32_16x16x32_bf16 v[68:71], v[148:151], v[214:217], v[68:71]
	v_mfma_f32_16x16x32_bf16 v[64:67], v[174:177], v[214:217], v[64:67]
	s_setprio 0
	s_add_i32 s25, s33, s47
	v_lshl_add_u64 v[168:169], s[38:39], 0, v[156:157]
	s_mov_b32 m0, s25
	s_nop 0
	global_load_lds_dwordx4 v[168:169], off
	s_add_i32 m0, s25, 0x2000
	s_add_u32 s66, s38, 0x80000
	v_lshl_add_u64 v[190:191], s[38:39], 0, v[152:153]
	s_addc_u32 s67, s39, 0
	s_add_i32 s24, s24, s47
	global_load_lds_dwordx4 v[190:191], off
	v_lshl_add_u64 v[218:219], s[66:67], 0, v[156:157]
	s_mov_b32 m0, s24
	v_lshl_add_u64 v[220:221], s[42:43], 0, v[154:155]
	global_load_lds_dwordx4 v[218:219], off
	s_add_i32 m0, s24, 0x2000
	v_lshl_add_u64 v[218:219], s[66:67], 0, v[152:153]
	global_load_lds_dwordx4 v[218:219], off
	s_mov_b32 m0, s2
	v_lshl_add_u64 v[218:219], s[42:43], 0, v[158:159]
	global_load_lds_dwordx4 v[218:219], off
	s_mov_b32 m0, s48
	s_nop 0
	global_load_lds_dwordx4 v[220:221], off
	ds_read_b128 v[178:181], v173 offset:16384
	ds_read_b128 v[182:185], v173 offset:17408
	ds_read_b128 v[186:189], v173 offset:18432
	ds_read_b128 v[194:197], v173 offset:19456
	ds_read_b128 v[202:205], v173 offset:20480
	ds_read_b128 v[206:209], v173 offset:21504
	ds_read_b128 v[210:213], v173 offset:22528
	ds_read_b128 v[214:217], v173 offset:23552
	s_waitcnt vmcnt(8)
	s_waitcnt lgkmcnt(0)
	s_barrier
	s_setprio 1
	s_waitcnt lgkmcnt(0)
	v_mfma_f32_16x16x32_bf16 v[60:63], v[128:131], v[178:181], v[60:63]
	v_mfma_f32_16x16x32_bf16 v[56:59], v[136:139], v[178:181], v[56:59]
	v_mfma_f32_16x16x32_bf16 v[44:47], v[128:131], v[186:189], v[44:47]
	v_mfma_f32_16x16x32_bf16 v[40:43], v[136:139], v[186:189], v[40:43]
	v_mfma_f32_16x16x32_bf16 v[28:31], v[128:131], v[202:205], v[28:31]
	v_mfma_f32_16x16x32_bf16 v[24:27], v[136:139], v[202:205], v[24:27]
	v_mfma_f32_16x16x32_bf16 v[12:15], v[128:131], v[210:213], v[12:15]
	v_mfma_f32_16x16x32_bf16 v[8:11], v[136:139], v[210:213], v[8:11]
	v_mfma_f32_16x16x32_bf16 v[60:63], v[132:135], v[182:185], v[60:63]
	v_mfma_f32_16x16x32_bf16 v[56:59], v[140:143], v[182:185], v[56:59]
	v_mfma_f32_16x16x32_bf16 v[44:47], v[132:135], v[194:197], v[44:47]
	v_mfma_f32_16x16x32_bf16 v[40:43], v[140:143], v[194:197], v[40:43]
	v_mfma_f32_16x16x32_bf16 v[28:31], v[132:135], v[206:209], v[28:31]
	v_mfma_f32_16x16x32_bf16 v[24:27], v[140:143], v[206:209], v[24:27]
	v_mfma_f32_16x16x32_bf16 v[12:15], v[132:135], v[214:217], v[12:15]
	v_mfma_f32_16x16x32_bf16 v[8:11], v[140:143], v[214:217], v[8:11]
	s_setprio 0
	s_setprio 1
	v_mfma_f32_16x16x32_bf16 v[52:55], v[144:147], v[178:181], v[52:55]
	v_mfma_f32_16x16x32_bf16 v[48:51], v[164:167], v[178:181], v[48:51]
	v_mfma_f32_16x16x32_bf16 v[36:39], v[144:147], v[186:189], v[36:39]
	v_mfma_f32_16x16x32_bf16 v[32:35], v[164:167], v[186:189], v[32:35]
	v_mfma_f32_16x16x32_bf16 v[20:23], v[144:147], v[202:205], v[20:23]
	v_mfma_f32_16x16x32_bf16 v[16:19], v[164:167], v[202:205], v[16:19]
	v_mfma_f32_16x16x32_bf16 v[4:7], v[144:147], v[210:213], v[4:7]
	v_mfma_f32_16x16x32_bf16 v[0:3], v[164:167], v[210:213], v[0:3]
	v_mfma_f32_16x16x32_bf16 v[52:55], v[148:151], v[182:185], v[52:55]
	v_mfma_f32_16x16x32_bf16 v[48:51], v[174:177], v[182:185], v[48:51]
	v_mfma_f32_16x16x32_bf16 v[36:39], v[148:151], v[194:197], v[36:39]
	v_mfma_f32_16x16x32_bf16 v[32:35], v[174:177], v[194:197], v[32:35]
	v_mfma_f32_16x16x32_bf16 v[20:23], v[148:151], v[206:209], v[20:23]
	s_barrier
	s_setprio 2
	v_mfma_f32_16x16x32_bf16 v[16:19], v[174:177], v[206:209], v[16:19]
	v_mfma_f32_16x16x32_bf16 v[4:7], v[148:151], v[214:217], v[4:7]
	v_mfma_f32_16x16x32_bf16 v[0:3], v[174:177], v[214:217], v[0:3]
	s_setprio 0
	s_add_i32 s24, 0, 0x18000
	s_add_i32 s25, 0, 0x1c000
	s_add_u32 s42, s42, 0x80000
	s_addc_u32 s43, s43, 0
	s_mov_b32 m0, s49
	v_lshl_add_u64 v[230:231], s[42:43], 0, v[158:159]
	global_load_lds_dwordx4 v[230:231], off
	s_mov_b32 m0, s50
	v_lshl_add_u64 v[230:231], s[42:43], 0, v[154:155]
	global_load_lds_dwordx4 v[230:231], off
	v_add_u32_e32 v140, 0x18000, v172
	v_add_u32_e32 v174, 0x1c000, v172
	ds_read_b128 v[128:131], v140
	ds_read_b128 v[132:135], v140 offset:1024
	ds_read_b128 v[136:139], v140 offset:2048
	ds_read_b128 v[140:143], v140 offset:3072
	ds_read_b128 v[144:147], v174
	ds_read_b128 v[148:151], v174 offset:1024
	ds_read_b128 v[164:167], v174 offset:2048
	ds_read_b128 v[174:177], v174 offset:3072
	ds_read_b128 v[178:181], v173 offset:32768
	ds_read_b128 v[182:185], v173 offset:33792
	ds_read_b128 v[186:189], v173 offset:34816
	ds_read_b128 v[194:197], v173 offset:35840
	ds_read_b128 v[202:205], v173 offset:36864
	ds_read_b128 v[206:209], v173 offset:37888
	ds_read_b128 v[210:213], v173 offset:38912
	ds_read_b128 v[214:217], v173 offset:39936
	s_waitcnt vmcnt(8)
	s_waitcnt lgkmcnt(0)
	s_barrier
; #define PG8_STAGE(bufoff, gbase, voff) do { _Pragma("unroll") for (int _i = 0; _i < 2; ++_i) \
;         __builtin_amdgcn_global_load_lds((const unsigned*)((const char*)(gbase) + (voff)[_i]), (PG8_LAS unsigned*)(lds + (bufoff) + ldsw + _i * 8192), 16, 0, 0); } while (0)
; #define PG8_LDA(dst, b, h) do { _Pragma("unroll") for (int m = 0; m < 4; ++m) _Pragma("unroll") for (int k = 0; k < 2; ++k) dst[m][k] = *(const PG8_LAS bf16x8*)(lds + PG8_SA(b, h) + aoff + m * 2048 + k * 1024); } while (0)
; #define PG8_MMA(ai, bj, At, Bt) do { __builtin_amdgcn_s_setprio(1); _Pragma("unroll") for (int m = 0; m < 4; ++m) _Pragma("unroll") for (int n = 0; n < 2; ++n) _Pragma("unroll") for (int k = 0; k < 2; ++k) \
;         acc[ai][bj][m][n] = __builtin_amdgcn_mfma_f32_16x16x32_bf16(Bt[n][k], At[m][k], acc[ai][bj][m][n], 0, 0, 0); __builtin_amdgcn_s_setprio(0); } while (0)
; #define PG8_WAIT_V(n) asm volatile("s_waitcnt vmcnt(" #n ")" ::: "memory")
; #define PG8_WAIT_L(n) asm volatile("s_waitcnt lgkmcnt(" #n ")" ::: "memory")
; #define PG8_BAR __builtin_amdgcn_s_barrier()
; #define PG8_SCHED __builtin_amdgcn_sched_barrier(0)
; template <class Epi, class Sched, bool ALIGN_EPI = false, bool SP2 = false>
; __device__ __forceinline__ void gemm_phase(PG8_LAS unsigned char* lds, const Gemm g, const Sched& S, const Epi& E) {
;     ...
;             PG8_WAIT_V(8); PG8_WAIT_L(0); PG8_BAR; PG8_MMA(0, 0, At, B0); PG8_MMA(0, 1, At, B1); PG8_BAR; PG8_SCHED;
;             PG8_LDA(At, 1, 1); PG8_STAGE(PG8_SB(1, 0), b3, voffB); PG8_STAGE(PG8_SB(1, 1), b3 + hstep, voffB); PG8_STAGE(PG8_SA(1, 0), a3, voffA);
;             PG8_WAIT_V(8); PG8_WAIT_L(0); PG8_BAR; PG8_MMA(1, 0, At, B0); PG8_MMA(1, 1, At, B1); PG8_BAR; PG8_SCHED;
	s_setprio 1
	s_waitcnt lgkmcnt(0)
	v_mfma_f32_16x16x32_bf16 v[124:127], v[128:131], v[178:181], v[124:127]
	v_mfma_f32_16x16x32_bf16 v[120:123], v[136:139], v[178:181], v[120:123]
	v_mfma_f32_16x16x32_bf16 v[108:111], v[128:131], v[186:189], v[108:111]
	v_mfma_f32_16x16x32_bf16 v[104:107], v[136:139], v[186:189], v[104:107]
	v_mfma_f32_16x16x32_bf16 v[92:95], v[128:131], v[202:205], v[92:95]
	v_mfma_f32_16x16x32_bf16 v[88:91], v[136:139], v[202:205], v[88:91]
	v_mfma_f32_16x16x32_bf16 v[76:79], v[128:131], v[210:213], v[76:79]
	v_mfma_f32_16x16x32_bf16 v[72:75], v[136:139], v[210:213], v[72:75]
	v_mfma_f32_16x16x32_bf16 v[124:127], v[132:135], v[182:185], v[124:127]
	v_mfma_f32_16x16x32_bf16 v[120:123], v[140:143], v[182:185], v[120:123]
	v_mfma_f32_16x16x32_bf16 v[108:111], v[132:135], v[194:197], v[108:111]
	v_mfma_f32_16x16x32_bf16 v[104:107], v[140:143], v[194:197], v[104:107]
	v_mfma_f32_16x16x32_bf16 v[92:95], v[132:135], v[206:209], v[92:95]
	v_mfma_f32_16x16x32_bf16 v[88:91], v[140:143], v[206:209], v[88:91]
	v_mfma_f32_16x16x32_bf16 v[76:79], v[132:135], v[214:217], v[76:79]
	v_mfma_f32_16x16x32_bf16 v[72:75], v[140:143], v[214:217], v[72:75]
	s_setprio 0
	s_setprio 1
	v_mfma_f32_16x16x32_bf16 v[116:119], v[144:147], v[178:181], v[116:119]
	v_mfma_f32_16x16x32_bf16 v[112:115], v[164:167], v[178:181], v[112:115]
	v_mfma_f32_16x16x32_bf16 v[100:103], v[144:147], v[186:189], v[100:103]
	v_mfma_f32_16x16x32_bf16 v[96:99], v[164:167], v[186:189], v[96:99]
	v_mfma_f32_16x16x32_bf16 v[84:87], v[144:147], v[202:205], v[84:87]
	v_mfma_f32_16x16x32_bf16 v[80:83], v[164:167], v[202:205], v[80:83]
	v_mfma_f32_16x16x32_bf16 v[68:71], v[144:147], v[210:213], v[68:71]
	v_mfma_f32_16x16x32_bf16 v[64:67], v[164:167], v[210:213], v[64:67]
	v_mfma_f32_16x16x32_bf16 v[116:119], v[148:151], v[182:185], v[116:119]
	v_mfma_f32_16x16x32_bf16 v[112:115], v[174:177], v[182:185], v[112:115]
	v_mfma_f32_16x16x32_bf16 v[100:103], v[148:151], v[194:197], v[100:103]
	v_mfma_f32_16x16x32_bf16 v[96:99], v[174:177], v[194:197], v[96:99]
	v_mfma_f32_16x16x32_bf16 v[84:87], v[148:151], v[206:209], v[84:87]
	s_barrier
	s_setprio 2
	v_mfma_f32_16x16x32_bf16 v[80:83], v[174:177], v[206:209], v[80:83]
	v_mfma_f32_16x16x32_bf16 v[68:71], v[148:151], v[214:217], v[68:71]
	v_mfma_f32_16x16x32_bf16 v[64:67], v[174:177], v[214:217], v[64:67]
	s_setprio 0
	s_add_i32 s24, s24, s47
	v_lshl_add_u64 v[168:169], v[168:169], 0, s[16:17]
	s_mov_b32 m0, s24
	s_nop 0
	global_load_lds_dwordx4 v[168:169], off
	s_add_i32 m0, s24, 0x2000
	s_add_u32 s38, s38, 0x80080
	v_lshl_add_u64 v[168:169], v[190:191], 0, s[16:17]
	s_addc_u32 s39, s39, 0
	s_add_i32 s24, s25, s47
	global_load_lds_dwordx4 v[168:169], off
	s_mov_b32 m0, s24
	v_lshl_add_u64 v[168:169], s[38:39], 0, v[156:157]
	global_load_lds_dwordx4 v[168:169], off
	s_add_i32 m0, s24, 0x2000
	v_lshl_add_u64 v[168:169], s[38:39], 0, v[152:153]
	global_load_lds_dwordx4 v[168:169], off
	s_mov_b32 m0, s55
	v_lshl_add_u64 v[168:169], v[218:219], 0, s[16:17]
	global_load_lds_dwordx4 v[168:169], off
	s_mov_b32 m0, s56
	v_lshl_add_u64 v[168:169], v[220:221], 0, s[16:17]
	global_load_lds_dwordx4 v[168:169], off
	ds_read_b128 v[178:181], v173 offset:49152
	ds_read_b128 v[182:185], v173 offset:50176
	ds_read_b128 v[186:189], v173 offset:51200
	ds_read_b128 v[194:197], v173 offset:52224
	ds_read_b128 v[202:205], v173 offset:53248
	ds_read_b128 v[206:209], v173 offset:54272
	ds_read_b128 v[210:213], v173 offset:55296
	ds_read_b128 v[214:217], v173 offset:56320
	s_waitcnt vmcnt(8)
	s_waitcnt lgkmcnt(0)
	s_barrier
	s_setprio 1
	s_waitcnt lgkmcnt(0)
	v_mfma_f32_16x16x32_bf16 v[60:63], v[128:131], v[178:181], v[60:63]
	v_mfma_f32_16x16x32_bf16 v[56:59], v[136:139], v[178:181], v[56:59]
	v_mfma_f32_16x16x32_bf16 v[44:47], v[128:131], v[186:189], v[44:47]
	v_mfma_f32_16x16x32_bf16 v[40:43], v[136:139], v[186:189], v[40:43]
	v_mfma_f32_16x16x32_bf16 v[28:31], v[128:131], v[202:205], v[28:31]
	v_mfma_f32_16x16x32_bf16 v[24:27], v[136:139], v[202:205], v[24:27]
	v_mfma_f32_16x16x32_bf16 v[12:15], v[128:131], v[210:213], v[12:15]
	v_mfma_f32_16x16x32_bf16 v[8:11], v[136:139], v[210:213], v[8:11]
	v_mfma_f32_16x16x32_bf16 v[60:63], v[132:135], v[182:185], v[60:63]
	v_mfma_f32_16x16x32_bf16 v[56:59], v[140:143], v[182:185], v[56:59]
	v_mfma_f32_16x16x32_bf16 v[44:47], v[132:135], v[194:197], v[44:47]
	v_mfma_f32_16x16x32_bf16 v[40:43], v[140:143], v[194:197], v[40:43]
	v_mfma_f32_16x16x32_bf16 v[28:31], v[132:135], v[206:209], v[28:31]
	v_mfma_f32_16x16x32_bf16 v[24:27], v[140:143], v[206:209], v[24:27]
	v_mfma_f32_16x16x32_bf16 v[12:15], v[132:135], v[214:217], v[12:15]
	v_mfma_f32_16x16x32_bf16 v[8:11], v[140:143], v[214:217], v[8:11]
	s_setprio 0
	s_setprio 1
	v_mfma_f32_16x16x32_bf16 v[52:55], v[144:147], v[178:181], v[52:55]
	v_mfma_f32_16x16x32_bf16 v[48:51], v[164:167], v[178:181], v[48:51]
	v_mfma_f32_16x16x32_bf16 v[36:39], v[144:147], v[186:189], v[36:39]
	v_mfma_f32_16x16x32_bf16 v[32:35], v[164:167], v[186:189], v[32:35]
	v_mfma_f32_16x16x32_bf16 v[20:23], v[144:147], v[202:205], v[20:23]
	v_mfma_f32_16x16x32_bf16 v[16:19], v[164:167], v[202:205], v[16:19]
	v_mfma_f32_16x16x32_bf16 v[4:7], v[144:147], v[210:213], v[4:7]
	v_mfma_f32_16x16x32_bf16 v[0:3], v[164:167], v[210:213], v[0:3]
	v_mfma_f32_16x16x32_bf16 v[52:55], v[148:151], v[182:185], v[52:55]
	v_mfma_f32_16x16x32_bf16 v[48:51], v[174:177], v[182:185], v[48:51]
	v_mfma_f32_16x16x32_bf16 v[36:39], v[148:151], v[194:197], v[36:39]
	v_mfma_f32_16x16x32_bf16 v[32:35], v[174:177], v[194:197], v[32:35]
	v_mfma_f32_16x16x32_bf16 v[20:23], v[148:151], v[206:209], v[20:23]
	s_barrier
	s_setprio 2
	v_mfma_f32_16x16x32_bf16 v[16:19], v[174:177], v[206:209], v[16:19]
	v_mfma_f32_16x16x32_bf16 v[4:7], v[148:151], v[214:217], v[4:7]
	v_mfma_f32_16x16x32_bf16 v[0:3], v[174:177], v[214:217], v[0:3]
	s_setprio 0
	s_add_i32 s65, s65, 2
	s_add_u32 s36, s36, 0x100
	s_addc_u32 s37, s37, 0
	s_add_u32 s63, s63, 0x100
	s_addc_u32 s64, s64, 0
	s_cmp_gt_u32 s65, 29
	s_cbranch_scc0 .LBB0_635
	s_and_b64 vcc, exec, s[10:11]
	s_cbranch_vccz .LBB0_638
	s_barrier

; #define PG8_STAGE(bufoff, gbase, voff) do { _Pragma("unroll") for (int _i = 0; _i < 2; ++_i) \
;         __builtin_amdgcn_global_load_lds((const unsigned*)((const char*)(gbase) + (voff)[_i]), (PG8_LAS unsigned*)(lds + (bufoff) + ldsw + _i * 8192), 16, 0, 0); } while (0)
; #define PG8_LDA(dst, b, h) do { _Pragma("unroll") for (int m = 0; m < 4; ++m) _Pragma("unroll") for (int k = 0; k < 2; ++k) dst[m][k] = *(const PG8_LAS bf16x8*)(lds + PG8_SA(b, h) + aoff + m * 2048 + k * 1024); } while (0)
; #define PG8_LDB(dst, b, h) do { _Pragma("unroll") for (int n = 0; n < 2; ++n) _Pragma("unroll") for (int k = 0; k < 2; ++k) dst[n][k] = *(const PG8_LAS bf16x8*)(lds + PG8_SB(b, h) + boff + n * 2048 + k * 1024); } while (0)
; #define PG8_WAIT_V(n) asm volatile("s_waitcnt vmcnt(" #n ")" ::: "memory")
; #define PG8_WAIT_L(n) asm volatile("s_waitcnt lgkmcnt(" #n ")" ::: "memory")
; #define PG8_BAR __builtin_amdgcn_s_barrier()
; template <class Epi, class Sched, bool ALIGN_EPI = false, bool SP2 = false>
; __device__ __forceinline__ void gemm_phase(PG8_LAS unsigned char* lds, const Gemm g, const Sched& S, const Epi& E) {
;     ...
;         const bool has_next = S.next(ui + 1, nxt);
;         const char* nA = has_next ? (const char*)g.A + (size_t)nxt.pm * tstep : cA; const char* nB = has_next ? (const char*)g.Bt + (size_t)nxt.pn * tstep : cB;
;         for (int t = 0; t < nt; t += 2) {
;             if constexpr (Epi::MID_HOOK) { if (t == Epi::MID_T) E.mid(acc, cur, wr, wc, fr, fq); }
;             const bool last = (t == nt - 2);
;             const char* a1 = cA + (size_t)(t + 1) * kstep;
;             const char* a2 = last ? nA : cA + (size_t)(t + 2) * kstep; const char* b2 = last ? nB : cB + (size_t)(t + 2) * kstep;
;             const char* a3 = a2 + kstep; const char* b3 = b2 + kstep;
;             if (last && has_next) S.a_ready(nxt);
;             if constexpr (SP2) {
;             PG8_LDB(B0, 0, 0); PG8_LDB(B1, 0, 1); PG8_SCHED; PG8_LDA(At, 0, 0); PG8_STAGE(PG8_SA(1, 1), a1 + hstep, voffA);
;             PG8_WAIT_V(8); PG8_WAIT_L(0); PG8_BAR; PG8_MMA(0, 0, At, B0); PG8_MMA(0, 1, At, B1); PG8_BAR; PG8_SCHED;
;             PG8_LDA(At, 0, 1); PG8_STAGE(PG8_SB(0, 0), b2, voffB); PG8_STAGE(PG8_SB(0, 1), b2 + hstep, voffB); PG8_STAGE(PG8_SA(0, 0), a2, voffA);
;             PG8_WAIT_V(8); PG8_WAIT_L(0); PG8_BAR; PG8_MMA(1, 0, At, B0); PG8_MMA(1, 1, At, B1); PG8_BAR; PG8_SCHED;
.LBB0_729:
	s_ashr_i32 s49, s48, 31
	s_lshl_b64 s[12:13], s[48:49], 20
	s_add_u32 s50, s18, s12
	s_addc_u32 s51, s19, s13
	s_and_b64 s[12:13], s[42:43], exec
	s_cselect_b32 s49, s51, s1
	s_cselect_b32 s60, s50, s0
	s_ashr_i32 s47, s46, 31
	s_lshl_b64 s[12:13], s[46:47], 20
	s_add_u32 s52, s14, s12
	s_addc_u32 s53, s15, s13
	s_and_b64 s[12:13], s[42:43], exec
	s_cselect_b32 s47, s53, s11
	s_cselect_b32 s61, s52, s10
	s_add_u32 s0, s0, 0x80080
	s_addc_u32 s1, s1, 0
	s_add_u32 s62, s10, 0x100
	s_addc_u32 s63, s11, 0
	s_mov_b32 s64, -2
	v_lshl_add_u64 v[190:191], s[0:1], 0, v[136:137]
	s_add_i32 m0, s31, 0xc000
	global_load_lds_dwordx4 v[190:191], off
	s_add_i32 m0, s31, 0xe000
	v_lshl_add_u64 v[190:191], s[0:1], 0, v[138:139]
	global_load_lds_dwordx4 v[190:191], off
	s_add_u32 s10, s0, 0xfff80080
	s_addc_u32 s11, s1, -1
	s_add_i32 s24, 0, 0x10000
	s_cmp_eq_u32 s64, 28
	s_cselect_b32 s13, s49, s11
	s_cselect_b32 s12, s60, s10
	s_cselect_b32 s11, s47, s63
	s_cselect_b32 s10, s61, s62
	s_add_i32 s25, 0, 0x14000
	s_waitcnt vmcnt(8)
	s_waitcnt lgkmcnt(0)
	s_barrier
	s_setprio 1
	s_waitcnt lgkmcnt(0)
	v_mfma_f32_16x16x32_bf16 v[124:127], v[140:143], v[178:181], 0
	v_mfma_f32_16x16x32_bf16 v[112:115], v[154:157], v[178:181], 0
	v_mfma_f32_16x16x32_bf16 v[108:111], v[140:143], v[186:189], 0
	v_mfma_f32_16x16x32_bf16 v[100:103], v[154:157], v[186:189], 0
	v_mfma_f32_16x16x32_bf16 v[92:95], v[140:143], v[202:205], 0
	v_mfma_f32_16x16x32_bf16 v[84:87], v[154:157], v[202:205], 0
	v_mfma_f32_16x16x32_bf16 v[76:79], v[140:143], v[210:213], 0
	v_mfma_f32_16x16x32_bf16 v[68:71], v[154:157], v[210:213], 0
	v_mfma_f32_16x16x32_bf16 v[124:127], v[144:147], v[182:185], v[124:127]
	v_mfma_f32_16x16x32_bf16 v[112:115], v[158:161], v[182:185], v[112:115]
	v_mfma_f32_16x16x32_bf16 v[108:111], v[144:147], v[194:197], v[108:111]
	v_mfma_f32_16x16x32_bf16 v[100:103], v[158:161], v[194:197], v[100:103]
	v_mfma_f32_16x16x32_bf16 v[92:95], v[144:147], v[206:209], v[92:95]
	v_mfma_f32_16x16x32_bf16 v[84:87], v[158:161], v[206:209], v[84:87]
	v_mfma_f32_16x16x32_bf16 v[76:79], v[144:147], v[214:217], v[76:79]
	v_mfma_f32_16x16x32_bf16 v[68:71], v[158:161], v[214:217], v[68:71]
	s_setprio 0
	s_setprio 1
	v_mfma_f32_16x16x32_bf16 v[120:123], v[162:165], v[178:181], 0
	v_mfma_f32_16x16x32_bf16 v[116:119], v[170:173], v[178:181], 0
	v_mfma_f32_16x16x32_bf16 v[104:107], v[162:165], v[186:189], 0
	v_mfma_f32_16x16x32_bf16 v[96:99], v[170:173], v[186:189], 0
	v_mfma_f32_16x16x32_bf16 v[88:91], v[162:165], v[202:205], 0
	v_mfma_f32_16x16x32_bf16 v[80:83], v[170:173], v[202:205], 0
	v_mfma_f32_16x16x32_bf16 v[72:75], v[162:165], v[210:213], 0
	v_mfma_f32_16x16x32_bf16 v[64:67], v[170:173], v[210:213], 0
	v_mfma_f32_16x16x32_bf16 v[120:123], v[166:169], v[182:185], v[120:123]
	v_mfma_f32_16x16x32_bf16 v[116:119], v[174:177], v[182:185], v[116:119]
	v_mfma_f32_16x16x32_bf16 v[104:107], v[166:169], v[194:197], v[104:107]
	v_mfma_f32_16x16x32_bf16 v[96:99], v[174:177], v[194:197], v[96:99]
	v_mfma_f32_16x16x32_bf16 v[88:91], v[166:169], v[206:209], v[88:91]
	s_barrier
	s_setprio 2
	v_mfma_f32_16x16x32_bf16 v[80:83], v[174:177], v[206:209], v[80:83]
	v_mfma_f32_16x16x32_bf16 v[72:75], v[166:169], v[214:217], v[72:75]
	v_mfma_f32_16x16x32_bf16 v[64:67], v[174:177], v[214:217], v[64:67]
	s_setprio 0
	s_add_i32 s24, s24, s30
	v_lshl_add_u64 v[190:191], s[10:11], 0, v[132:133]
	s_mov_b32 m0, s24
	s_nop 0
	global_load_lds_dwordx4 v[190:191], off
	s_add_i32 m0, s24, 0x2000
	s_add_u32 s66, s10, 0x80000
	v_lshl_add_u64 v[218:219], s[10:11], 0, v[128:129]
	s_addc_u32 s67, s11, 0
	s_add_i32 s24, s25, s30
	global_load_lds_dwordx4 v[218:219], off
	v_lshl_add_u64 v[220:221], s[66:67], 0, v[132:133]
	s_mov_b32 m0, s24
	v_lshl_add_u64 v[230:231], s[12:13], 0, v[130:131]
	global_load_lds_dwordx4 v[220:221], off
	s_add_i32 m0, s24, 0x2000
	v_lshl_add_u64 v[220:221], s[66:67], 0, v[128:129]
	global_load_lds_dwordx4 v[220:221], off
	s_mov_b32 m0, s31
	v_lshl_add_u64 v[220:221], s[12:13], 0, v[134:135]
	global_load_lds_dwordx4 v[220:221], off
	s_mov_b32 m0, s34
	s_nop 0
	global_load_lds_dwordx4 v[230:231], off
	ds_read_b128 v[178:181], v152 offset:16384
	ds_read_b128 v[182:185], v152 offset:17408
	ds_read_b128 v[186:189], v152 offset:18432
	ds_read_b128 v[194:197], v152 offset:19456
	ds_read_b128 v[202:205], v152 offset:20480
	ds_read_b128 v[206:209], v152 offset:21504
	ds_read_b128 v[210:213], v152 offset:22528
	ds_read_b128 v[214:217], v152 offset:23552
	s_waitcnt vmcnt(8)
	s_waitcnt lgkmcnt(0)
	s_barrier
	s_setprio 1
	s_waitcnt lgkmcnt(0)
	v_mfma_f32_16x16x32_bf16 v[60:63], v[140:143], v[178:181], 0
	v_mfma_f32_16x16x32_bf16 v[52:55], v[154:157], v[178:181], 0
	v_mfma_f32_16x16x32_bf16 v[44:47], v[140:143], v[186:189], 0
	v_mfma_f32_16x16x32_bf16 v[36:39], v[154:157], v[186:189], 0
	v_mfma_f32_16x16x32_bf16 v[28:31], v[140:143], v[202:205], 0
	v_mfma_f32_16x16x32_bf16 v[20:23], v[154:157], v[202:205], 0
	v_mfma_f32_16x16x32_bf16 v[12:15], v[140:143], v[210:213], 0
	v_mfma_f32_16x16x32_bf16 v[4:7], v[154:157], v[210:213], 0
	v_mfma_f32_16x16x32_bf16 v[60:63], v[144:147], v[182:185], v[60:63]
	v_mfma_f32_16x16x32_bf16 v[52:55], v[158:161], v[182:185], v[52:55]
	v_mfma_f32_16x16x32_bf16 v[44:47], v[144:147], v[194:197], v[44:47]
	v_mfma_f32_16x16x32_bf16 v[36:39], v[158:161], v[194:197], v[36:39]
	v_mfma_f32_16x16x32_bf16 v[28:31], v[144:147], v[206:209], v[28:31]
	v_mfma_f32_16x16x32_bf16 v[20:23], v[158:161], v[206:209], v[20:23]
	v_mfma_f32_16x16x32_bf16 v[12:15], v[144:147], v[214:217], v[12:15]
	v_mfma_f32_16x16x32_bf16 v[4:7], v[158:161], v[214:217], v[4:7]
	s_setprio 0
	s_setprio 1
	v_mfma_f32_16x16x32_bf16 v[56:59], v[162:165], v[178:181], 0
	v_mfma_f32_16x16x32_bf16 v[48:51], v[170:173], v[178:181], 0
	v_mfma_f32_16x16x32_bf16 v[40:43], v[162:165], v[186:189], 0
	v_mfma_f32_16x16x32_bf16 v[32:35], v[170:173], v[186:189], 0
	v_mfma_f32_16x16x32_bf16 v[24:27], v[162:165], v[202:205], 0
	v_mfma_f32_16x16x32_bf16 v[16:19], v[170:173], v[202:205], 0
	v_mfma_f32_16x16x32_bf16 v[8:11], v[162:165], v[210:213], 0
	v_mfma_f32_16x16x32_bf16 v[0:3], v[170:173], v[210:213], 0
	v_mfma_f32_16x16x32_bf16 v[56:59], v[166:169], v[182:185], v[56:59]
	v_mfma_f32_16x16x32_bf16 v[48:51], v[174:177], v[182:185], v[48:51]
	v_mfma_f32_16x16x32_bf16 v[40:43], v[166:169], v[194:197], v[40:43]
	v_mfma_f32_16x16x32_bf16 v[32:35], v[174:177], v[194:197], v[32:35]
	v_mfma_f32_16x16x32_bf16 v[24:27], v[166:169], v[206:209], v[24:27]
	s_barrier
; #define PG8_STAGE(bufoff, gbase, voff) do { _Pragma("unroll") for (int _i = 0; _i < 2; ++_i) \
;         __builtin_amdgcn_global_load_lds((const unsigned*)((const char*)(gbase) + (voff)[_i]), (PG8_LAS unsigned*)(lds + (bufoff) + ldsw + _i * 8192), 16, 0, 0); } while (0)
; #define PG8_LDA(dst, b, h) do { _Pragma("unroll") for (int m = 0; m < 4; ++m) _Pragma("unroll") for (int k = 0; k < 2; ++k) dst[m][k] = *(const PG8_LAS bf16x8*)(lds + PG8_SA(b, h) + aoff + m * 2048 + k * 1024); } while (0)
; #define PG8_LDB(dst, b, h) do { _Pragma("unroll") for (int n = 0; n < 2; ++n) _Pragma("unroll") for (int k = 0; k < 2; ++k) dst[n][k] = *(const PG8_LAS bf16x8*)(lds + PG8_SB(b, h) + boff + n * 2048 + k * 1024); } while (0)
; #define PG8_MMA(ai, bj, At, Bt) do { __builtin_amdgcn_s_setprio(1); _Pragma("unroll") for (int m = 0; m < 4; ++m) _Pragma("unroll") for (int n = 0; n < 2; ++n) _Pragma("unroll") for (int k = 0; k < 2; ++k) \
;         acc[ai][bj][m][n] = __builtin_amdgcn_mfma_f32_16x16x32_bf16(Bt[n][k], At[m][k], acc[ai][bj][m][n], 0, 0, 0); __builtin_amdgcn_s_setprio(0); } while (0)
; #define PG8_WAIT_V(n) asm volatile("s_waitcnt vmcnt(" #n ")" ::: "memory")
; #define PG8_WAIT_L(n) asm volatile("s_waitcnt lgkmcnt(" #n ")" ::: "memory")
; #define PG8_BAR __builtin_amdgcn_s_barrier()
; #define PG8_SCHED __builtin_amdgcn_sched_barrier(0)
; template <class Epi, class Sched, bool ALIGN_EPI = false, bool SP2 = false>
; __device__ __forceinline__ void gemm_phase(PG8_LAS unsigned char* lds, const Gemm g, const Sched& S, const Epi& E) {
;     ...
;             PG8_WAIT_V(8); PG8_WAIT_L(0); PG8_BAR; PG8_MMA(1, 0, At, B0); PG8_MMA(1, 1, At, B1); PG8_BAR; PG8_SCHED;
;             PG8_LDB(B0, 1, 0); PG8_LDB(B1, 1, 1); PG8_SCHED; PG8_LDA(At, 1, 0); PG8_STAGE(PG8_SA(0, 1), a2 + hstep, voffA);
;             PG8_WAIT_V(8); PG8_WAIT_L(0); PG8_BAR; PG8_MMA(0, 0, At, B0); PG8_MMA(0, 1, At, B1); PG8_BAR; PG8_SCHED;
;             PG8_LDA(At, 1, 1); PG8_STAGE(PG8_SB(1, 0), b3, voffB); PG8_STAGE(PG8_SB(1, 1), b3 + hstep, voffB); PG8_STAGE(PG8_SA(1, 0), a3, voffA);
	s_setprio 2
	v_mfma_f32_16x16x32_bf16 v[16:19], v[174:177], v[206:209], v[16:19]
	v_mfma_f32_16x16x32_bf16 v[8:11], v[166:169], v[214:217], v[8:11]
	v_mfma_f32_16x16x32_bf16 v[0:3], v[174:177], v[214:217], v[0:3]
	s_setprio 0
	s_add_i32 s24, 0, 0x18000
	s_add_i32 s25, 0, 0x1c000
	s_add_u32 s12, s12, 0x80000
	s_addc_u32 s13, s13, 0
	s_mov_b32 m0, s36
	v_lshl_add_u64 v[232:233], s[12:13], 0, v[134:135]
	global_load_lds_dwordx4 v[232:233], off
	s_mov_b32 m0, s37
	v_lshl_add_u64 v[232:233], s[12:13], 0, v[130:131]
	global_load_lds_dwordx4 v[232:233], off
	v_add_u32_e32 v148, 0x18000, v151
	ds_read_b128 v[140:143], v148
	ds_read_b128 v[144:147], v148 offset:1024
	ds_read_b128 v[154:157], v148 offset:2048
	ds_read_b128 v[158:161], v148 offset:3072
	v_add_u32_e32 v148, 0x1c000, v151
	ds_read_b128 v[162:165], v148
	ds_read_b128 v[166:169], v148 offset:1024
	ds_read_b128 v[170:173], v148 offset:2048
	ds_read_b128 v[174:177], v148 offset:3072
	ds_read_b128 v[178:181], v152 offset:32768
	ds_read_b128 v[182:185], v152 offset:33792
	ds_read_b128 v[186:189], v152 offset:34816
	ds_read_b128 v[194:197], v152 offset:35840
	ds_read_b128 v[202:205], v152 offset:36864
	ds_read_b128 v[206:209], v152 offset:37888
	ds_read_b128 v[210:213], v152 offset:38912
	ds_read_b128 v[214:217], v152 offset:39936
	s_waitcnt vmcnt(8)
	s_waitcnt lgkmcnt(0)
	s_barrier
	s_setprio 1
	s_waitcnt lgkmcnt(0)
	v_mfma_f32_16x16x32_bf16 v[124:127], v[140:143], v[178:181], v[124:127]
	v_mfma_f32_16x16x32_bf16 v[112:115], v[154:157], v[178:181], v[112:115]
	v_mfma_f32_16x16x32_bf16 v[108:111], v[140:143], v[186:189], v[108:111]
	v_mfma_f32_16x16x32_bf16 v[100:103], v[154:157], v[186:189], v[100:103]
	v_mfma_f32_16x16x32_bf16 v[92:95], v[140:143], v[202:205], v[92:95]
	v_mfma_f32_16x16x32_bf16 v[84:87], v[154:157], v[202:205], v[84:87]
	v_mfma_f32_16x16x32_bf16 v[76:79], v[140:143], v[210:213], v[76:79]
	v_mfma_f32_16x16x32_bf16 v[68:71], v[154:157], v[210:213], v[68:71]
	v_mfma_f32_16x16x32_bf16 v[124:127], v[144:147], v[182:185], v[124:127]
	v_mfma_f32_16x16x32_bf16 v[112:115], v[158:161], v[182:185], v[112:115]
	v_mfma_f32_16x16x32_bf16 v[108:111], v[144:147], v[194:197], v[108:111]
	v_mfma_f32_16x16x32_bf16 v[100:103], v[158:161], v[194:197], v[100:103]
	v_mfma_f32_16x16x32_bf16 v[92:95], v[144:147], v[206:209], v[92:95]
	v_mfma_f32_16x16x32_bf16 v[84:87], v[158:161], v[206:209], v[84:87]
	v_mfma_f32_16x16x32_bf16 v[76:79], v[144:147], v[214:217], v[76:79]
	v_mfma_f32_16x16x32_bf16 v[68:71], v[158:161], v[214:217], v[68:71]
	s_setprio 0
	s_setprio 1
	v_mfma_f32_16x16x32_bf16 v[120:123], v[162:165], v[178:181], v[120:123]
	v_mfma_f32_16x16x32_bf16 v[116:119], v[170:173], v[178:181], v[116:119]
	v_mfma_f32_16x16x32_bf16 v[104:107], v[162:165], v[186:189], v[104:107]
	v_mfma_f32_16x16x32_bf16 v[96:99], v[170:173], v[186:189], v[96:99]
	v_mfma_f32_16x16x32_bf16 v[88:91], v[162:165], v[202:205], v[88:91]
	v_mfma_f32_16x16x32_bf16 v[80:83], v[170:173], v[202:205], v[80:83]
	v_mfma_f32_16x16x32_bf16 v[72:75], v[162:165], v[210:213], v[72:75]
	v_mfma_f32_16x16x32_bf16 v[64:67], v[170:173], v[210:213], v[64:67]
	v_mfma_f32_16x16x32_bf16 v[120:123], v[166:169], v[182:185], v[120:123]
	v_mfma_f32_16x16x32_bf16 v[116:119], v[174:177], v[182:185], v[116:119]
	v_mfma_f32_16x16x32_bf16 v[104:107], v[166:169], v[194:197], v[104:107]
	v_mfma_f32_16x16x32_bf16 v[96:99], v[174:177], v[194:197], v[96:99]
	v_mfma_f32_16x16x32_bf16 v[88:91], v[166:169], v[206:209], v[88:91]
	s_barrier
	s_setprio 2
	v_mfma_f32_16x16x32_bf16 v[80:83], v[174:177], v[206:209], v[80:83]
	v_mfma_f32_16x16x32_bf16 v[72:75], v[166:169], v[214:217], v[72:75]
	v_mfma_f32_16x16x32_bf16 v[64:67], v[174:177], v[214:217], v[64:67]
	s_setprio 0
	s_add_i32 s12, s24, s30
	v_lshl_add_u64 v[190:191], v[190:191], 0, s[16:17]
	s_mov_b32 m0, s12
	s_nop 0
	global_load_lds_dwordx4 v[190:191], off
	s_add_i32 m0, s12, 0x2000
	s_add_u32 s10, s10, 0x80080
	v_lshl_add_u64 v[190:191], v[218:219], 0, s[16:17]
	s_addc_u32 s11, s11, 0
	s_add_i32 s12, s25, s30
	global_load_lds_dwordx4 v[190:191], off
	s_mov_b32 m0, s12
	v_lshl_add_u64 v[190:191], s[10:11], 0, v[132:133]
	global_load_lds_dwordx4 v[190:191], off
	s_add_i32 m0, s12, 0x2000
	v_lshl_add_u64 v[190:191], s[10:11], 0, v[128:129]
	global_load_lds_dwordx4 v[190:191], off
	s_mov_b32 m0, s56
	v_lshl_add_u64 v[190:191], v[220:221], 0, s[16:17]
	global_load_lds_dwordx4 v[190:191], off
	s_mov_b32 m0, s57
	v_lshl_add_u64 v[190:191], v[230:231], 0, s[16:17]
	global_load_lds_dwordx4 v[190:191], off
	ds_read_b128 v[178:181], v152 offset:49152
	ds_read_b128 v[182:185], v152 offset:50176
	ds_read_b128 v[186:189], v152 offset:51200
	ds_read_b128 v[194:197], v152 offset:52224
	ds_read_b128 v[202:205], v152 offset:53248
	ds_read_b128 v[206:209], v152 offset:54272
	ds_read_b128 v[210:213], v152 offset:55296
	ds_read_b128 v[214:217], v152 offset:56320
	s_waitcnt vmcnt(8)
	s_waitcnt lgkmcnt(0)
	s_barrier
; #define PG8_STAGE(bufoff, gbase, voff) do { _Pragma("unroll") for (int _i = 0; _i < 2; ++_i) \
;         __builtin_amdgcn_global_load_lds((const unsigned*)((const char*)(gbase) + (voff)[_i]), (PG8_LAS unsigned*)(lds + (bufoff) + ldsw + _i * 8192), 16, 0, 0); } while (0)
; #define PG8_LDA(dst, b, h) do { _Pragma("unroll") for (int m = 0; m < 4; ++m) _Pragma("unroll") for (int k = 0; k < 2; ++k) dst[m][k] = *(const PG8_LAS bf16x8*)(lds + PG8_SA(b, h) + aoff + m * 2048 + k * 1024); } while (0)
; #define PG8_LDB(dst, b, h) do { _Pragma("unroll") for (int n = 0; n < 2; ++n) _Pragma("unroll") for (int k = 0; k < 2; ++k) dst[n][k] = *(const PG8_LAS bf16x8*)(lds + PG8_SB(b, h) + boff + n * 2048 + k * 1024); } while (0)
; #define PG8_MMA(ai, bj, At, Bt) do { __builtin_amdgcn_s_setprio(1); _Pragma("unroll") for (int m = 0; m < 4; ++m) _Pragma("unroll") for (int n = 0; n < 2; ++n) _Pragma("unroll") for (int k = 0; k < 2; ++k) \
;         acc[ai][bj][m][n] = __builtin_amdgcn_mfma_f32_16x16x32_bf16(Bt[n][k], At[m][k], acc[ai][bj][m][n], 0, 0, 0); __builtin_amdgcn_s_setprio(0); } while (0)
; #define PG8_WAIT_V(n) asm volatile("s_waitcnt vmcnt(" #n ")" ::: "memory")
; template <class Epi, class Sched, bool ALIGN_EPI = false, bool SP2 = false>
; __device__ __forceinline__ void gemm_phase(PG8_LAS unsigned char* lds, const Gemm g, const Sched& S, const Epi& E) {
;     ...
;             PG8_LDB(B0, 0, 0); PG8_LDB(B1, 0, 1); PG8_SCHED; PG8_LDA(At, 0, 0); PG8_STAGE(PG8_SA(1, 1), a1 + hstep, voffA);
;             PG8_WAIT_V(8); PG8_WAIT_L(0); PG8_BAR; PG8_MMA(0, 0, At, B0); PG8_MMA(0, 1, At, B1); PG8_BAR; PG8_SCHED;
;             PG8_LDA(At, 0, 1); PG8_STAGE(PG8_SB(0, 0), b2, voffB); PG8_STAGE(PG8_SB(0, 1), b2 + hstep, voffB); PG8_STAGE(PG8_SA(0, 0), a2, voffA);
;             PG8_WAIT_V(8); PG8_WAIT_L(0); PG8_BAR; PG8_MMA(1, 0, At, B0); PG8_MMA(1, 1, At, B1); PG8_BAR; PG8_SCHED;
;             PG8_LDB(B0, 1, 0); PG8_LDB(B1, 1, 1); PG8_SCHED; PG8_LDA(At, 1, 0); PG8_STAGE(PG8_SA(0, 1), a2 + hstep, voffA);
;             PG8_WAIT_V(8); PG8_WAIT_L(0); PG8_BAR; PG8_MMA(0, 0, At, B0); PG8_MMA(0, 1, At, B1); PG8_BAR; PG8_SCHED;
;             PG8_LDA(At, 1, 1); PG8_STAGE(PG8_SB(1, 0), b3, voffB); PG8_STAGE(PG8_SB(1, 1), b3 + hstep, voffB); PG8_STAGE(PG8_SA(1, 0), a3, voffA);
;             PG8_WAIT_V(8); PG8_WAIT_L(0); PG8_BAR; PG8_MMA(1, 0, At, B0); PG8_MMA(1, 1, At, B1); PG8_BAR; PG8_SCHED;
	s_setprio 1
	s_waitcnt lgkmcnt(0)
	v_mfma_f32_16x16x32_bf16 v[60:63], v[140:143], v[178:181], v[60:63]
	v_mfma_f32_16x16x32_bf16 v[52:55], v[154:157], v[178:181], v[52:55]
	v_mfma_f32_16x16x32_bf16 v[44:47], v[140:143], v[186:189], v[44:47]
	v_mfma_f32_16x16x32_bf16 v[36:39], v[154:157], v[186:189], v[36:39]
	v_mfma_f32_16x16x32_bf16 v[28:31], v[140:143], v[202:205], v[28:31]
	v_mfma_f32_16x16x32_bf16 v[20:23], v[154:157], v[202:205], v[20:23]
	v_mfma_f32_16x16x32_bf16 v[12:15], v[140:143], v[210:213], v[12:15]
	v_mfma_f32_16x16x32_bf16 v[4:7], v[154:157], v[210:213], v[4:7]
	v_mfma_f32_16x16x32_bf16 v[60:63], v[144:147], v[182:185], v[60:63]
	v_mfma_f32_16x16x32_bf16 v[52:55], v[158:161], v[182:185], v[52:55]
	v_mfma_f32_16x16x32_bf16 v[44:47], v[144:147], v[194:197], v[44:47]
	v_mfma_f32_16x16x32_bf16 v[36:39], v[158:161], v[194:197], v[36:39]
	v_mfma_f32_16x16x32_bf16 v[28:31], v[144:147], v[206:209], v[28:31]
	v_mfma_f32_16x16x32_bf16 v[20:23], v[158:161], v[206:209], v[20:23]
	v_mfma_f32_16x16x32_bf16 v[12:15], v[144:147], v[214:217], v[12:15]
	v_mfma_f32_16x16x32_bf16 v[4:7], v[158:161], v[214:217], v[4:7]
	s_setprio 0
	s_setprio 1
	v_mfma_f32_16x16x32_bf16 v[56:59], v[162:165], v[178:181], v[56:59]
	v_mfma_f32_16x16x32_bf16 v[48:51], v[170:173], v[178:181], v[48:51]
	v_mfma_f32_16x16x32_bf16 v[40:43], v[162:165], v[186:189], v[40:43]
	v_mfma_f32_16x16x32_bf16 v[32:35], v[170:173], v[186:189], v[32:35]
	v_mfma_f32_16x16x32_bf16 v[24:27], v[162:165], v[202:205], v[24:27]
	v_mfma_f32_16x16x32_bf16 v[16:19], v[170:173], v[202:205], v[16:19]
	v_mfma_f32_16x16x32_bf16 v[8:11], v[162:165], v[210:213], v[8:11]
	v_mfma_f32_16x16x32_bf16 v[0:3], v[170:173], v[210:213], v[0:3]
	v_mfma_f32_16x16x32_bf16 v[56:59], v[166:169], v[182:185], v[56:59]
	v_mfma_f32_16x16x32_bf16 v[48:51], v[174:177], v[182:185], v[48:51]
	v_mfma_f32_16x16x32_bf16 v[40:43], v[166:169], v[194:197], v[40:43]
	v_mfma_f32_16x16x32_bf16 v[32:35], v[174:177], v[194:197], v[32:35]
	v_mfma_f32_16x16x32_bf16 v[24:27], v[166:169], v[206:209], v[24:27]
	s_barrier
	s_setprio 2
	v_mfma_f32_16x16x32_bf16 v[16:19], v[174:177], v[206:209], v[16:19]
	v_mfma_f32_16x16x32_bf16 v[8:11], v[166:169], v[214:217], v[8:11]
	v_mfma_f32_16x16x32_bf16 v[0:3], v[174:177], v[214:217], v[0:3]
	s_setprio 0
	s_add_i32 s64, s64, 2
	s_add_u32 s0, s0, 0x100
	s_addc_u32 s1, s1, 0
	s_add_u32 s62, s62, 0x100
	s_addc_u32 s63, s63, 0
	s_cmp_gt_u32 s64, 29
	s_branch .LBB0_730
.LBB0_730:
	v_lshl_add_u64 v[190:191], s[0:1], 0, v[136:137]
	s_add_i32 m0, s31, 0xc000
	s_nop 0
	global_load_lds_dwordx4 v[190:191], off
	s_add_i32 m0, s31, 0xe000
	v_lshl_add_u64 v[190:191], s[0:1], 0, v[138:139]
	global_load_lds_dwordx4 v[190:191], off
	s_add_u32 s10, s0, 0xfff80080
	s_addc_u32 s11, s1, -1
	s_add_i32 s24, 0, 0x10000
	s_cmp_eq_u32 s64, 28
	s_cselect_b32 s13, s49, s11
	s_cselect_b32 s12, s60, s10
	s_cselect_b32 s11, s47, s63
	s_cselect_b32 s10, s61, s62
	s_add_i32 s25, 0, 0x14000
	v_add_u32_e32 v148, 0x10000, v151
	ds_read_b128 v[140:143], v148
	ds_read_b128 v[144:147], v148 offset:1024
	ds_read_b128 v[154:157], v148 offset:2048
	ds_read_b128 v[158:161], v148 offset:3072
	v_add_u32_e32 v148, 0x14000, v151
	ds_read_b128 v[162:165], v148
	ds_read_b128 v[166:169], v148 offset:1024
	ds_read_b128 v[170:173], v148 offset:2048
	ds_read_b128 v[174:177], v148 offset:3072
	ds_read_b128 v[178:181], v152
	ds_read_b128 v[182:185], v152 offset:1024
	ds_read_b128 v[186:189], v152 offset:2048
	ds_read_b128 v[194:197], v152 offset:3072
	ds_read_b128 v[202:205], v152 offset:4096
	ds_read_b128 v[206:209], v152 offset:5120
	ds_read_b128 v[210:213], v152 offset:6144
	ds_read_b128 v[214:217], v152 offset:7168
	s_waitcnt vmcnt(8)
	s_waitcnt lgkmcnt(0)
	s_barrier
	s_setprio 1
	s_waitcnt lgkmcnt(0)
	v_mfma_f32_16x16x32_bf16 v[124:127], v[140:143], v[178:181], v[124:127]
	v_mfma_f32_16x16x32_bf16 v[112:115], v[154:157], v[178:181], v[112:115]
	v_mfma_f32_16x16x32_bf16 v[108:111], v[140:143], v[186:189], v[108:111]
	v_mfma_f32_16x16x32_bf16 v[100:103], v[154:157], v[186:189], v[100:103]
	v_mfma_f32_16x16x32_bf16 v[92:95], v[140:143], v[202:205], v[92:95]
	v_mfma_f32_16x16x32_bf16 v[84:87], v[154:157], v[202:205], v[84:87]
	v_mfma_f32_16x16x32_bf16 v[76:79], v[140:143], v[210:213], v[76:79]
	v_mfma_f32_16x16x32_bf16 v[68:71], v[154:157], v[210:213], v[68:71]
	v_mfma_f32_16x16x32_bf16 v[124:127], v[144:147], v[182:185], v[124:127]
	v_mfma_f32_16x16x32_bf16 v[112:115], v[158:161], v[182:185], v[112:115]
	v_mfma_f32_16x16x32_bf16 v[108:111], v[144:147], v[194:197], v[108:111]
	v_mfma_f32_16x16x32_bf16 v[100:103], v[158:161], v[194:197], v[100:103]
	v_mfma_f32_16x16x32_bf16 v[92:95], v[144:147], v[206:209], v[92:95]
	v_mfma_f32_16x16x32_bf16 v[84:87], v[158:161], v[206:209], v[84:87]
	v_mfma_f32_16x16x32_bf16 v[76:79], v[144:147], v[214:217], v[76:79]
	v_mfma_f32_16x16x32_bf16 v[68:71], v[158:161], v[214:217], v[68:71]
	s_setprio 0
	s_setprio 1
	v_mfma_f32_16x16x32_bf16 v[120:123], v[162:165], v[178:181], v[120:123]
	v_mfma_f32_16x16x32_bf16 v[116:119], v[170:173], v[178:181], v[116:119]
	v_mfma_f32_16x16x32_bf16 v[104:107], v[162:165], v[186:189], v[104:107]
	v_mfma_f32_16x16x32_bf16 v[96:99], v[170:173], v[186:189], v[96:99]
	v_mfma_f32_16x16x32_bf16 v[88:91], v[162:165], v[202:205], v[88:91]
	v_mfma_f32_16x16x32_bf16 v[80:83], v[170:173], v[202:205], v[80:83]
	v_mfma_f32_16x16x32_bf16 v[72:75], v[162:165], v[210:213], v[72:75]
	v_mfma_f32_16x16x32_bf16 v[64:67], v[170:173], v[210:213], v[64:67]
	v_mfma_f32_16x16x32_bf16 v[120:123], v[166:169], v[182:185], v[120:123]
	v_mfma_f32_16x16x32_bf16 v[116:119], v[174:177], v[182:185], v[116:119]
	v_mfma_f32_16x16x32_bf16 v[104:107], v[166:169], v[194:197], v[104:107]
	v_mfma_f32_16x16x32_bf16 v[96:99], v[174:177], v[194:197], v[96:99]
	v_mfma_f32_16x16x32_bf16 v[88:91], v[166:169], v[206:209], v[88:91]
	s_barrier
; #define PG8_STAGE(bufoff, gbase, voff) do { _Pragma("unroll") for (int _i = 0; _i < 2; ++_i) \
;         __builtin_amdgcn_global_load_lds((const unsigned*)((const char*)(gbase) + (voff)[_i]), (PG8_LAS unsigned*)(lds + (bufoff) + ldsw + _i * 8192), 16, 0, 0); } while (0)
; #define PG8_LDA(dst, b, h) do { _Pragma("unroll") for (int m = 0; m < 4; ++m) _Pragma("unroll") for (int k = 0; k < 2; ++k) dst[m][k] = *(const PG8_LAS bf16x8*)(lds + PG8_SA(b, h) + aoff + m * 2048 + k * 1024); } while (0)
; #define PG8_LDB(dst, b, h) do { _Pragma("unroll") for (int n = 0; n < 2; ++n) _Pragma("unroll") for (int k = 0; k < 2; ++k) dst[n][k] = *(const PG8_LAS bf16x8*)(lds + PG8_SB(b, h) + boff + n * 2048 + k * 1024); } while (0)
; #define PG8_MMA(ai, bj, At, Bt) do { __builtin_amdgcn_s_setprio(1); _Pragma("unroll") for (int m = 0; m < 4; ++m) _Pragma("unroll") for (int n = 0; n < 2; ++n) _Pragma("unroll") for (int k = 0; k < 2; ++k) \
;         acc[ai][bj][m][n] = __builtin_amdgcn_mfma_f32_16x16x32_bf16(Bt[n][k], At[m][k], acc[ai][bj][m][n], 0, 0, 0); __builtin_amdgcn_s_setprio(0); } while (0)
; #define PG8_WAIT_V(n) asm volatile("s_waitcnt vmcnt(" #n ")" ::: "memory")
; #define PG8_WAIT_L(n) asm volatile("s_waitcnt lgkmcnt(" #n ")" ::: "memory")
; #define PG8_BAR __builtin_amdgcn_s_barrier()
; #define PG8_SCHED __builtin_amdgcn_sched_barrier(0)
; template <class Epi, class Sched, bool ALIGN_EPI = false, bool SP2 = false>
; __device__ __forceinline__ void gemm_phase(PG8_LAS unsigned char* lds, const Gemm g, const Sched& S, const Epi& E) {
;     ...
;             PG8_WAIT_V(8); PG8_WAIT_L(0); PG8_BAR; PG8_MMA(0, 0, At, B0); PG8_MMA(0, 1, At, B1); PG8_BAR; PG8_SCHED;
;             PG8_LDA(At, 0, 1); PG8_STAGE(PG8_SB(0, 0), b2, voffB); PG8_STAGE(PG8_SB(0, 1), b2 + hstep, voffB); PG8_STAGE(PG8_SA(0, 0), a2, voffA);
;             PG8_WAIT_V(8); PG8_WAIT_L(0); PG8_BAR; PG8_MMA(1, 0, At, B0); PG8_MMA(1, 1, At, B1); PG8_BAR; PG8_SCHED;
;             PG8_LDB(B0, 1, 0); PG8_LDB(B1, 1, 1); PG8_SCHED; PG8_LDA(At, 1, 0); PG8_STAGE(PG8_SA(0, 1), a2 + hstep, voffA);
;             PG8_WAIT_V(8); PG8_WAIT_L(0); PG8_BAR; PG8_MMA(0, 0, At, B0); PG8_MMA(0, 1, At, B1); PG8_BAR; PG8_SCHED;
	s_setprio 2
	v_mfma_f32_16x16x32_bf16 v[80:83], v[174:177], v[206:209], v[80:83]
	v_mfma_f32_16x16x32_bf16 v[72:75], v[166:169], v[214:217], v[72:75]
	v_mfma_f32_16x16x32_bf16 v[64:67], v[174:177], v[214:217], v[64:67]
	s_setprio 0
	s_add_i32 s24, s24, s30
	v_lshl_add_u64 v[190:191], s[10:11], 0, v[132:133]
	s_mov_b32 m0, s24
	s_nop 0
	global_load_lds_dwordx4 v[190:191], off
	s_add_i32 m0, s24, 0x2000
	s_add_u32 s66, s10, 0x80000
	v_lshl_add_u64 v[218:219], s[10:11], 0, v[128:129]
	s_addc_u32 s67, s11, 0
	s_add_i32 s24, s25, s30
	global_load_lds_dwordx4 v[218:219], off
	v_lshl_add_u64 v[220:221], s[66:67], 0, v[132:133]
	s_mov_b32 m0, s24
	v_lshl_add_u64 v[230:231], s[12:13], 0, v[130:131]
	global_load_lds_dwordx4 v[220:221], off
	s_add_i32 m0, s24, 0x2000
	v_lshl_add_u64 v[220:221], s[66:67], 0, v[128:129]
	global_load_lds_dwordx4 v[220:221], off
	s_mov_b32 m0, s31
	v_lshl_add_u64 v[220:221], s[12:13], 0, v[134:135]
	global_load_lds_dwordx4 v[220:221], off
	s_mov_b32 m0, s34
	s_nop 0
	global_load_lds_dwordx4 v[230:231], off
	ds_read_b128 v[178:181], v152 offset:16384
	ds_read_b128 v[182:185], v152 offset:17408
	ds_read_b128 v[186:189], v152 offset:18432
	ds_read_b128 v[194:197], v152 offset:19456
	ds_read_b128 v[202:205], v152 offset:20480
	ds_read_b128 v[206:209], v152 offset:21504
	ds_read_b128 v[210:213], v152 offset:22528
	ds_read_b128 v[214:217], v152 offset:23552
	s_waitcnt vmcnt(8)
	s_waitcnt lgkmcnt(0)
	s_barrier
	s_setprio 1
	s_waitcnt lgkmcnt(0)
	v_mfma_f32_16x16x32_bf16 v[60:63], v[140:143], v[178:181], v[60:63]
	v_mfma_f32_16x16x32_bf16 v[52:55], v[154:157], v[178:181], v[52:55]
	v_mfma_f32_16x16x32_bf16 v[44:47], v[140:143], v[186:189], v[44:47]
	v_mfma_f32_16x16x32_bf16 v[36:39], v[154:157], v[186:189], v[36:39]
	v_mfma_f32_16x16x32_bf16 v[28:31], v[140:143], v[202:205], v[28:31]
	v_mfma_f32_16x16x32_bf16 v[20:23], v[154:157], v[202:205], v[20:23]
	v_mfma_f32_16x16x32_bf16 v[12:15], v[140:143], v[210:213], v[12:15]
	v_mfma_f32_16x16x32_bf16 v[4:7], v[154:157], v[210:213], v[4:7]
	v_mfma_f32_16x16x32_bf16 v[60:63], v[144:147], v[182:185], v[60:63]
	v_mfma_f32_16x16x32_bf16 v[52:55], v[158:161], v[182:185], v[52:55]
	v_mfma_f32_16x16x32_bf16 v[44:47], v[144:147], v[194:197], v[44:47]
	v_mfma_f32_16x16x32_bf16 v[36:39], v[158:161], v[194:197], v[36:39]
	v_mfma_f32_16x16x32_bf16 v[28:31], v[144:147], v[206:209], v[28:31]
	v_mfma_f32_16x16x32_bf16 v[20:23], v[158:161], v[206:209], v[20:23]
	v_mfma_f32_16x16x32_bf16 v[12:15], v[144:147], v[214:217], v[12:15]
	v_mfma_f32_16x16x32_bf16 v[4:7], v[158:161], v[214:217], v[4:7]
	s_setprio 0
	s_setprio 1
	v_mfma_f32_16x16x32_bf16 v[56:59], v[162:165], v[178:181], v[56:59]
	v_mfma_f32_16x16x32_bf16 v[48:51], v[170:173], v[178:181], v[48:51]
	v_mfma_f32_16x16x32_bf16 v[40:43], v[162:165], v[186:189], v[40:43]
	v_mfma_f32_16x16x32_bf16 v[32:35], v[170:173], v[186:189], v[32:35]
	v_mfma_f32_16x16x32_bf16 v[24:27], v[162:165], v[202:205], v[24:27]
	v_mfma_f32_16x16x32_bf16 v[16:19], v[170:173], v[202:205], v[16:19]
	v_mfma_f32_16x16x32_bf16 v[8:11], v[162:165], v[210:213], v[8:11]
	v_mfma_f32_16x16x32_bf16 v[0:3], v[170:173], v[210:213], v[0:3]
	v_mfma_f32_16x16x32_bf16 v[56:59], v[166:169], v[182:185], v[56:59]
	v_mfma_f32_16x16x32_bf16 v[48:51], v[174:177], v[182:185], v[48:51]
	v_mfma_f32_16x16x32_bf16 v[40:43], v[166:169], v[194:197], v[40:43]
	v_mfma_f32_16x16x32_bf16 v[32:35], v[174:177], v[194:197], v[32:35]
	v_mfma_f32_16x16x32_bf16 v[24:27], v[166:169], v[206:209], v[24:27]
	s_barrier
	s_setprio 2
	v_mfma_f32_16x16x32_bf16 v[16:19], v[174:177], v[206:209], v[16:19]
	v_mfma_f32_16x16x32_bf16 v[8:11], v[166:169], v[214:217], v[8:11]
	v_mfma_f32_16x16x32_bf16 v[0:3], v[174:177], v[214:217], v[0:3]
	s_setprio 0
	s_add_i32 s24, 0, 0x18000
	s_add_i32 s25, 0, 0x1c000
	s_add_u32 s12, s12, 0x80000
	s_addc_u32 s13, s13, 0
	s_mov_b32 m0, s36
	v_lshl_add_u64 v[232:233], s[12:13], 0, v[134:135]
	global_load_lds_dwordx4 v[232:233], off
	s_mov_b32 m0, s37
	v_lshl_add_u64 v[232:233], s[12:13], 0, v[130:131]
	global_load_lds_dwordx4 v[232:233], off
	v_add_u32_e32 v148, 0x18000, v151
	ds_read_b128 v[140:143], v148
	ds_read_b128 v[144:147], v148 offset:1024
	ds_read_b128 v[154:157], v148 offset:2048
	ds_read_b128 v[158:161], v148 offset:3072
	v_add_u32_e32 v148, 0x1c000, v151
	ds_read_b128 v[162:165], v148
	ds_read_b128 v[166:169], v148 offset:1024
	ds_read_b128 v[170:173], v148 offset:2048
	ds_read_b128 v[174:177], v148 offset:3072
	ds_read_b128 v[178:181], v152 offset:32768
	ds_read_b128 v[182:185], v152 offset:33792
	ds_read_b128 v[186:189], v152 offset:34816
	ds_read_b128 v[194:197], v152 offset:35840
	ds_read_b128 v[202:205], v152 offset:36864
	ds_read_b128 v[206:209], v152 offset:37888
	ds_read_b128 v[210:213], v152 offset:38912
	ds_read_b128 v[214:217], v152 offset:39936
	s_waitcnt vmcnt(8)
	s_waitcnt lgkmcnt(0)
	s_barrier
; #define PG8_STAGE(bufoff, gbase, voff) do { _Pragma("unroll") for (int _i = 0; _i < 2; ++_i) \
;         __builtin_amdgcn_global_load_lds((const unsigned*)((const char*)(gbase) + (voff)[_i]), (PG8_LAS unsigned*)(lds + (bufoff) + ldsw + _i * 8192), 16, 0, 0); } while (0)
; #define PG8_LDA(dst, b, h) do { _Pragma("unroll") for (int m = 0; m < 4; ++m) _Pragma("unroll") for (int k = 0; k < 2; ++k) dst[m][k] = *(const PG8_LAS bf16x8*)(lds + PG8_SA(b, h) + aoff + m * 2048 + k * 1024); } while (0)
; #define PG8_MMA(ai, bj, At, Bt) do { __builtin_amdgcn_s_setprio(1); _Pragma("unroll") for (int m = 0; m < 4; ++m) _Pragma("unroll") for (int n = 0; n < 2; ++n) _Pragma("unroll") for (int k = 0; k < 2; ++k) \
;         acc[ai][bj][m][n] = __builtin_amdgcn_mfma_f32_16x16x32_bf16(Bt[n][k], At[m][k], acc[ai][bj][m][n], 0, 0, 0); __builtin_amdgcn_s_setprio(0); } while (0)
; #define PG8_WAIT_V(n) asm volatile("s_waitcnt vmcnt(" #n ")" ::: "memory")
; #define PG8_WAIT_L(n) asm volatile("s_waitcnt lgkmcnt(" #n ")" ::: "memory")
; #define PG8_BAR __builtin_amdgcn_s_barrier()
; #define PG8_SCHED __builtin_amdgcn_sched_barrier(0)
; template <class Epi, class Sched, bool ALIGN_EPI = false, bool SP2 = false>
; __device__ __forceinline__ void gemm_phase(PG8_LAS unsigned char* lds, const Gemm g, const Sched& S, const Epi& E) {
;     ...
;             PG8_WAIT_V(8); PG8_WAIT_L(0); PG8_BAR; PG8_MMA(0, 0, At, B0); PG8_MMA(0, 1, At, B1); PG8_BAR; PG8_SCHED;
;             PG8_LDA(At, 1, 1); PG8_STAGE(PG8_SB(1, 0), b3, voffB); PG8_STAGE(PG8_SB(1, 1), b3 + hstep, voffB); PG8_STAGE(PG8_SA(1, 0), a3, voffA);
;             PG8_WAIT_V(8); PG8_WAIT_L(0); PG8_BAR; PG8_MMA(1, 0, At, B0); PG8_MMA(1, 1, At, B1); PG8_BAR; PG8_SCHED;
	s_setprio 1
	s_waitcnt lgkmcnt(0)
	v_mfma_f32_16x16x32_bf16 v[124:127], v[140:143], v[178:181], v[124:127]
	v_mfma_f32_16x16x32_bf16 v[112:115], v[154:157], v[178:181], v[112:115]
	v_mfma_f32_16x16x32_bf16 v[108:111], v[140:143], v[186:189], v[108:111]
	v_mfma_f32_16x16x32_bf16 v[100:103], v[154:157], v[186:189], v[100:103]
	v_mfma_f32_16x16x32_bf16 v[92:95], v[140:143], v[202:205], v[92:95]
	v_mfma_f32_16x16x32_bf16 v[84:87], v[154:157], v[202:205], v[84:87]
	v_mfma_f32_16x16x32_bf16 v[76:79], v[140:143], v[210:213], v[76:79]
	v_mfma_f32_16x16x32_bf16 v[68:71], v[154:157], v[210:213], v[68:71]
	v_mfma_f32_16x16x32_bf16 v[124:127], v[144:147], v[182:185], v[124:127]
	v_mfma_f32_16x16x32_bf16 v[112:115], v[158:161], v[182:185], v[112:115]
	v_mfma_f32_16x16x32_bf16 v[108:111], v[144:147], v[194:197], v[108:111]
	v_mfma_f32_16x16x32_bf16 v[100:103], v[158:161], v[194:197], v[100:103]
	v_mfma_f32_16x16x32_bf16 v[92:95], v[144:147], v[206:209], v[92:95]
	v_mfma_f32_16x16x32_bf16 v[84:87], v[158:161], v[206:209], v[84:87]
	v_mfma_f32_16x16x32_bf16 v[76:79], v[144:147], v[214:217], v[76:79]
	v_mfma_f32_16x16x32_bf16 v[68:71], v[158:161], v[214:217], v[68:71]
	s_setprio 0
	s_setprio 1
	v_mfma_f32_16x16x32_bf16 v[120:123], v[162:165], v[178:181], v[120:123]
	v_mfma_f32_16x16x32_bf16 v[116:119], v[170:173], v[178:181], v[116:119]
	v_mfma_f32_16x16x32_bf16 v[104:107], v[162:165], v[186:189], v[104:107]
	v_mfma_f32_16x16x32_bf16 v[96:99], v[170:173], v[186:189], v[96:99]
	v_mfma_f32_16x16x32_bf16 v[88:91], v[162:165], v[202:205], v[88:91]
	v_mfma_f32_16x16x32_bf16 v[80:83], v[170:173], v[202:205], v[80:83]
	v_mfma_f32_16x16x32_bf16 v[72:75], v[162:165], v[210:213], v[72:75]
	v_mfma_f32_16x16x32_bf16 v[64:67], v[170:173], v[210:213], v[64:67]
	v_mfma_f32_16x16x32_bf16 v[120:123], v[166:169], v[182:185], v[120:123]
	v_mfma_f32_16x16x32_bf16 v[116:119], v[174:177], v[182:185], v[116:119]
	v_mfma_f32_16x16x32_bf16 v[104:107], v[166:169], v[194:197], v[104:107]
	v_mfma_f32_16x16x32_bf16 v[96:99], v[174:177], v[194:197], v[96:99]
	v_mfma_f32_16x16x32_bf16 v[88:91], v[166:169], v[206:209], v[88:91]
	s_barrier
	s_setprio 2
	v_mfma_f32_16x16x32_bf16 v[80:83], v[174:177], v[206:209], v[80:83]
	v_mfma_f32_16x16x32_bf16 v[72:75], v[166:169], v[214:217], v[72:75]
	v_mfma_f32_16x16x32_bf16 v[64:67], v[174:177], v[214:217], v[64:67]
	s_setprio 0
	s_add_i32 s12, s24, s30
	v_lshl_add_u64 v[190:191], v[190:191], 0, s[16:17]
	s_mov_b32 m0, s12
	s_nop 0
	global_load_lds_dwordx4 v[190:191], off
	s_add_i32 m0, s12, 0x2000
	s_add_u32 s10, s10, 0x80080
	v_lshl_add_u64 v[190:191], v[218:219], 0, s[16:17]
	s_addc_u32 s11, s11, 0
	s_add_i32 s12, s25, s30
	global_load_lds_dwordx4 v[190:191], off
	s_mov_b32 m0, s12
	v_lshl_add_u64 v[190:191], s[10:11], 0, v[132:133]
	global_load_lds_dwordx4 v[190:191], off
	s_add_i32 m0, s12, 0x2000
	v_lshl_add_u64 v[190:191], s[10:11], 0, v[128:129]
	global_load_lds_dwordx4 v[190:191], off
	s_mov_b32 m0, s56
	v_lshl_add_u64 v[190:191], v[220:221], 0, s[16:17]
	global_load_lds_dwordx4 v[190:191], off
	s_mov_b32 m0, s57
	v_lshl_add_u64 v[190:191], v[230:231], 0, s[16:17]
	global_load_lds_dwordx4 v[190:191], off
	ds_read_b128 v[178:181], v152 offset:49152
	ds_read_b128 v[182:185], v152 offset:50176
	ds_read_b128 v[186:189], v152 offset:51200
	ds_read_b128 v[194:197], v152 offset:52224
	ds_read_b128 v[202:205], v152 offset:53248
	ds_read_b128 v[206:209], v152 offset:54272
	ds_read_b128 v[210:213], v152 offset:55296
	ds_read_b128 v[214:217], v152 offset:56320
	s_waitcnt vmcnt(8)
	s_waitcnt lgkmcnt(0)
	s_barrier
	s_setprio 1
	s_waitcnt lgkmcnt(0)
	v_mfma_f32_16x16x32_bf16 v[60:63], v[140:143], v[178:181], v[60:63]
	v_mfma_f32_16x16x32_bf16 v[52:55], v[154:157], v[178:181], v[52:55]
	v_mfma_f32_16x16x32_bf16 v[44:47], v[140:143], v[186:189], v[44:47]
	v_mfma_f32_16x16x32_bf16 v[36:39], v[154:157], v[186:189], v[36:39]
	v_mfma_f32_16x16x32_bf16 v[28:31], v[140:143], v[202:205], v[28:31]
	v_mfma_f32_16x16x32_bf16 v[20:23], v[154:157], v[202:205], v[20:23]
	v_mfma_f32_16x16x32_bf16 v[12:15], v[140:143], v[210:213], v[12:15]
	v_mfma_f32_16x16x32_bf16 v[4:7], v[154:157], v[210:213], v[4:7]
	v_mfma_f32_16x16x32_bf16 v[60:63], v[144:147], v[182:185], v[60:63]
	v_mfma_f32_16x16x32_bf16 v[52:55], v[158:161], v[182:185], v[52:55]
	v_mfma_f32_16x16x32_bf16 v[44:47], v[144:147], v[194:197], v[44:47]
	v_mfma_f32_16x16x32_bf16 v[36:39], v[158:161], v[194:197], v[36:39]
	v_mfma_f32_16x16x32_bf16 v[28:31], v[144:147], v[206:209], v[28:31]
	v_mfma_f32_16x16x32_bf16 v[20:23], v[158:161], v[206:209], v[20:23]
	v_mfma_f32_16x16x32_bf16 v[12:15], v[144:147], v[214:217], v[12:15]
	v_mfma_f32_16x16x32_bf16 v[4:7], v[158:161], v[214:217], v[4:7]
	s_setprio 0
	s_setprio 1
	v_mfma_f32_16x16x32_bf16 v[56:59], v[162:165], v[178:181], v[56:59]
	v_mfma_f32_16x16x32_bf16 v[48:51], v[170:173], v[178:181], v[48:51]
	v_mfma_f32_16x16x32_bf16 v[40:43], v[162:165], v[186:189], v[40:43]
	v_mfma_f32_16x16x32_bf16 v[32:35], v[170:173], v[186:189], v[32:35]
	v_mfma_f32_16x16x32_bf16 v[24:27], v[162:165], v[202:205], v[24:27]
	v_mfma_f32_16x16x32_bf16 v[16:19], v[170:173], v[202:205], v[16:19]
	v_mfma_f32_16x16x32_bf16 v[8:11], v[162:165], v[210:213], v[8:11]
	v_mfma_f32_16x16x32_bf16 v[0:3], v[170:173], v[210:213], v[0:3]
	v_mfma_f32_16x16x32_bf16 v[56:59], v[166:169], v[182:185], v[56:59]
	v_mfma_f32_16x16x32_bf16 v[48:51], v[174:177], v[182:185], v[48:51]
	v_mfma_f32_16x16x32_bf16 v[40:43], v[166:169], v[194:197], v[40:43]
	v_mfma_f32_16x16x32_bf16 v[32:35], v[174:177], v[194:197], v[32:35]
	v_mfma_f32_16x16x32_bf16 v[24:27], v[166:169], v[206:209], v[24:27]
	s_barrier
	s_setprio 2
	v_mfma_f32_16x16x32_bf16 v[16:19], v[174:177], v[206:209], v[16:19]
	v_mfma_f32_16x16x32_bf16 v[8:11], v[166:169], v[214:217], v[8:11]
	v_mfma_f32_16x16x32_bf16 v[0:3], v[174:177], v[214:217], v[0:3]
	s_setprio 0
	s_add_i32 s64, s64, 2
	s_add_u32 s0, s0, 0x100
	s_addc_u32 s1, s1, 0
	s_add_u32 s62, s62, 0x100
	s_addc_u32 s63, s63, 0
	s_cmp_gt_u32 s64, 29
	s_cbranch_scc0 .LBB0_730
	s_and_b64 vcc, exec, s[44:45]
	s_cbranch_vccz .LBB0_733
	s_barrier

; #define PG8_STAGE(bufoff, gbase, voff) do { _Pragma("unroll") for (int _i = 0; _i < 2; ++_i) \
;         __builtin_amdgcn_global_load_lds((const unsigned*)((const char*)(gbase) + (voff)[_i]), (PG8_LAS unsigned*)(lds + (bufoff) + ldsw + _i * 8192), 16, 0, 0); } while (0)
; #define PG8_LDA(dst, b, h) do { _Pragma("unroll") for (int m = 0; m < 4; ++m) _Pragma("unroll") for (int k = 0; k < 2; ++k) dst[m][k] = *(const PG8_LAS bf16x8*)(lds + PG8_SA(b, h) + aoff + m * 2048 + k * 1024); } while (0)
; #define PG8_LDB(dst, b, h) do { _Pragma("unroll") for (int n = 0; n < 2; ++n) _Pragma("unroll") for (int k = 0; k < 2; ++k) dst[n][k] = *(const PG8_LAS bf16x8*)(lds + PG8_SB(b, h) + boff + n * 2048 + k * 1024); } while (0)
; #define PG8_MMA(ai, bj, At, Bt) do { __builtin_amdgcn_s_setprio(1); _Pragma("unroll") for (int m = 0; m < 4; ++m) _Pragma("unroll") for (int n = 0; n < 2; ++n) _Pragma("unroll") for (int k = 0; k < 2; ++k) \
;         acc[ai][bj][m][n] = __builtin_amdgcn_mfma_f32_16x16x32_bf16(Bt[n][k], At[m][k], acc[ai][bj][m][n], 0, 0, 0); __builtin_amdgcn_s_setprio(0); } while (0)
; #define PG8_WAIT_V(n) asm volatile("s_waitcnt vmcnt(" #n ")" ::: "memory")
; #define PG8_WAIT_L(n) asm volatile("s_waitcnt lgkmcnt(" #n ")" ::: "memory")
; template <class Epi, class Sched, bool ALIGN_EPI = false, bool SP2 = false>
; __device__ __forceinline__ void gemm_phase(PG8_LAS unsigned char* lds, const Gemm g, const Sched& S, const Epi& E) {
;     ...
;             const bool last = (t == nt - 2);
;             const char* a1 = cA + (size_t)(t + 1) * kstep;
;             const char* a2 = last ? nA : cA + (size_t)(t + 2) * kstep; const char* b2 = last ? nB : cB + (size_t)(t + 2) * kstep;
;             const char* a3 = a2 + kstep; const char* b3 = b2 + kstep;
;             if (last && has_next) S.a_ready(nxt);
;             if constexpr (SP2) {
;             PG8_LDB(B0, 0, 0); PG8_LDB(B1, 0, 1); PG8_SCHED; PG8_LDA(At, 0, 0); PG8_STAGE(PG8_SA(1, 1), a1 + hstep, voffA);
;             PG8_WAIT_V(8); PG8_WAIT_L(0); PG8_BAR; PG8_MMA(0, 0, At, B0); PG8_MMA(0, 1, At, B1); PG8_BAR; PG8_SCHED;
;             PG8_LDA(At, 0, 1); PG8_STAGE(PG8_SB(0, 0), b2, voffB); PG8_STAGE(PG8_SB(0, 1), b2 + hstep, voffB); PG8_STAGE(PG8_SA(0, 0), a2, voffA);
;             PG8_WAIT_V(8); PG8_WAIT_L(0); PG8_BAR; PG8_MMA(1, 0, At, B0); PG8_MMA(1, 1, At, B1); PG8_BAR; PG8_SCHED;
.LBB0_816:
	s_add_u32 s59, s30, 0x100
	s_addc_u32 s60, s31, 0
	s_mov_b32 s61, -2
	s_waitcnt lgkmcnt(0)
	v_lshl_add_u64 v[168:169], s[18:19], 0, v[160:161]
	s_add_i32 m0, s2, 0xc000
	global_load_lds_dwordx4 v[168:169], off
	s_add_i32 m0, s2, 0xe000
	v_lshl_add_u64 v[168:169], s[18:19], 0, v[162:163]
	global_load_lds_dwordx4 v[168:169], off
	s_add_u32 s30, s18, 0x100
	s_addc_u32 s31, s19, 0
	s_add_i32 s24, 0, 0x10000
	s_cmpk_eq_i32 s61, 0x54
	s_cselect_b32 s39, s5, s31
	s_cselect_b32 s38, s4, s30
	s_cselect_b32 s37, s15, s60
	s_cselect_b32 s36, s14, s59
	s_add_i32 s25, 0, 0x14000
	s_waitcnt vmcnt(8)
	s_waitcnt lgkmcnt(0)
	s_barrier
	s_setprio 1
	s_waitcnt lgkmcnt(0)
	v_mfma_f32_16x16x32_bf16 v[124:127], v[128:131], v[178:181], 0
	v_mfma_f32_16x16x32_bf16 v[120:123], v[136:139], v[178:181], 0
	v_mfma_f32_16x16x32_bf16 v[108:111], v[128:131], v[186:189], 0
	v_mfma_f32_16x16x32_bf16 v[104:107], v[136:139], v[186:189], 0
	v_mfma_f32_16x16x32_bf16 v[92:95], v[128:131], v[202:205], 0
	v_mfma_f32_16x16x32_bf16 v[88:91], v[136:139], v[202:205], 0
	v_mfma_f32_16x16x32_bf16 v[76:79], v[128:131], v[210:213], 0
	v_mfma_f32_16x16x32_bf16 v[72:75], v[136:139], v[210:213], 0
	v_mfma_f32_16x16x32_bf16 v[124:127], v[132:135], v[182:185], v[124:127]
	v_mfma_f32_16x16x32_bf16 v[120:123], v[140:143], v[182:185], v[120:123]
	v_mfma_f32_16x16x32_bf16 v[108:111], v[132:135], v[194:197], v[108:111]
	v_mfma_f32_16x16x32_bf16 v[104:107], v[140:143], v[194:197], v[104:107]
	v_mfma_f32_16x16x32_bf16 v[92:95], v[132:135], v[206:209], v[92:95]
	v_mfma_f32_16x16x32_bf16 v[88:91], v[140:143], v[206:209], v[88:91]
	v_mfma_f32_16x16x32_bf16 v[76:79], v[132:135], v[214:217], v[76:79]
	v_mfma_f32_16x16x32_bf16 v[72:75], v[140:143], v[214:217], v[72:75]
	s_setprio 0
	s_setprio 1
	v_mfma_f32_16x16x32_bf16 v[116:119], v[144:147], v[178:181], 0
	v_mfma_f32_16x16x32_bf16 v[112:115], v[164:167], v[178:181], 0
	v_mfma_f32_16x16x32_bf16 v[100:103], v[144:147], v[186:189], 0
	v_mfma_f32_16x16x32_bf16 v[96:99], v[164:167], v[186:189], 0
	v_mfma_f32_16x16x32_bf16 v[84:87], v[144:147], v[202:205], 0
	v_mfma_f32_16x16x32_bf16 v[80:83], v[164:167], v[202:205], 0
	v_mfma_f32_16x16x32_bf16 v[68:71], v[144:147], v[210:213], 0
	v_mfma_f32_16x16x32_bf16 v[64:67], v[164:167], v[210:213], 0
	v_mfma_f32_16x16x32_bf16 v[116:119], v[148:151], v[182:185], v[116:119]
	v_mfma_f32_16x16x32_bf16 v[112:115], v[174:177], v[182:185], v[112:115]
	v_mfma_f32_16x16x32_bf16 v[100:103], v[148:151], v[194:197], v[100:103]
	v_mfma_f32_16x16x32_bf16 v[96:99], v[174:177], v[194:197], v[96:99]
	v_mfma_f32_16x16x32_bf16 v[84:87], v[148:151], v[206:209], v[84:87]
	s_barrier
	s_setprio 2
	v_mfma_f32_16x16x32_bf16 v[80:83], v[174:177], v[206:209], v[80:83]
	v_mfma_f32_16x16x32_bf16 v[68:71], v[148:151], v[214:217], v[68:71]
	v_mfma_f32_16x16x32_bf16 v[64:67], v[174:177], v[214:217], v[64:67]
	s_setprio 0
	s_add_i32 s18, s24, s43
	v_lshl_add_u64 v[168:169], s[36:37], 0, v[156:157]
	s_mov_b32 m0, s18
	s_nop 0
	global_load_lds_dwordx4 v[168:169], off
	s_add_i32 m0, s18, 0x2000
	s_add_u32 s18, s36, 0x160000
	v_lshl_add_u64 v[190:191], s[36:37], 0, v[152:153]
	s_addc_u32 s19, s37, 0
	s_add_i32 s24, s25, s43
	global_load_lds_dwordx4 v[190:191], off
	v_lshl_add_u64 v[218:219], s[18:19], 0, v[156:157]
	s_mov_b32 m0, s24
	v_lshl_add_u64 v[220:221], s[38:39], 0, v[154:155]
	global_load_lds_dwordx4 v[218:219], off
	s_add_i32 m0, s24, 0x2000
	v_lshl_add_u64 v[218:219], s[18:19], 0, v[152:153]
	global_load_lds_dwordx4 v[218:219], off
	s_mov_b32 m0, s2
	v_lshl_add_u64 v[218:219], s[38:39], 0, v[158:159]
	global_load_lds_dwordx4 v[218:219], off
	s_mov_b32 m0, s44
	s_nop 0
	global_load_lds_dwordx4 v[220:221], off
	ds_read_b128 v[178:181], v173 offset:16384
	ds_read_b128 v[182:185], v173 offset:17408
	ds_read_b128 v[186:189], v173 offset:18432
	ds_read_b128 v[194:197], v173 offset:19456
	ds_read_b128 v[202:205], v173 offset:20480
	ds_read_b128 v[206:209], v173 offset:21504
	ds_read_b128 v[210:213], v173 offset:22528
	ds_read_b128 v[214:217], v173 offset:23552
	s_waitcnt vmcnt(8)
	s_waitcnt lgkmcnt(0)
	s_barrier
	s_setprio 1
	s_waitcnt lgkmcnt(0)
	v_mfma_f32_16x16x32_bf16 v[60:63], v[128:131], v[178:181], 0
	v_mfma_f32_16x16x32_bf16 v[56:59], v[136:139], v[178:181], 0
	v_mfma_f32_16x16x32_bf16 v[44:47], v[128:131], v[186:189], 0
	v_mfma_f32_16x16x32_bf16 v[40:43], v[136:139], v[186:189], 0
	v_mfma_f32_16x16x32_bf16 v[28:31], v[128:131], v[202:205], 0
	v_mfma_f32_16x16x32_bf16 v[24:27], v[136:139], v[202:205], 0
	v_mfma_f32_16x16x32_bf16 v[12:15], v[128:131], v[210:213], 0
	v_mfma_f32_16x16x32_bf16 v[8:11], v[136:139], v[210:213], 0
	v_mfma_f32_16x16x32_bf16 v[60:63], v[132:135], v[182:185], v[60:63]
	v_mfma_f32_16x16x32_bf16 v[56:59], v[140:143], v[182:185], v[56:59]
	v_mfma_f32_16x16x32_bf16 v[44:47], v[132:135], v[194:197], v[44:47]
	v_mfma_f32_16x16x32_bf16 v[40:43], v[140:143], v[194:197], v[40:43]
	v_mfma_f32_16x16x32_bf16 v[28:31], v[132:135], v[206:209], v[28:31]
	v_mfma_f32_16x16x32_bf16 v[24:27], v[140:143], v[206:209], v[24:27]
	v_mfma_f32_16x16x32_bf16 v[12:15], v[132:135], v[214:217], v[12:15]
	v_mfma_f32_16x16x32_bf16 v[8:11], v[140:143], v[214:217], v[8:11]
	s_setprio 0
	s_setprio 1
	v_mfma_f32_16x16x32_bf16 v[52:55], v[144:147], v[178:181], 0
	v_mfma_f32_16x16x32_bf16 v[48:51], v[164:167], v[178:181], 0
	v_mfma_f32_16x16x32_bf16 v[36:39], v[144:147], v[186:189], 0
	v_mfma_f32_16x16x32_bf16 v[32:35], v[164:167], v[186:189], 0
	v_mfma_f32_16x16x32_bf16 v[20:23], v[144:147], v[202:205], 0
	v_mfma_f32_16x16x32_bf16 v[16:19], v[164:167], v[202:205], 0
	v_mfma_f32_16x16x32_bf16 v[4:7], v[144:147], v[210:213], 0
	v_mfma_f32_16x16x32_bf16 v[0:3], v[164:167], v[210:213], 0
	v_mfma_f32_16x16x32_bf16 v[52:55], v[148:151], v[182:185], v[52:55]
	v_mfma_f32_16x16x32_bf16 v[48:51], v[174:177], v[182:185], v[48:51]
	v_mfma_f32_16x16x32_bf16 v[36:39], v[148:151], v[194:197], v[36:39]
	v_mfma_f32_16x16x32_bf16 v[32:35], v[174:177], v[194:197], v[32:35]
	v_mfma_f32_16x16x32_bf16 v[20:23], v[148:151], v[206:209], v[20:23]
	s_barrier
; #define PG8_STAGE(bufoff, gbase, voff) do { _Pragma("unroll") for (int _i = 0; _i < 2; ++_i) \
;         __builtin_amdgcn_global_load_lds((const unsigned*)((const char*)(gbase) + (voff)[_i]), (PG8_LAS unsigned*)(lds + (bufoff) + ldsw + _i * 8192), 16, 0, 0); } while (0)
; #define PG8_LDA(dst, b, h) do { _Pragma("unroll") for (int m = 0; m < 4; ++m) _Pragma("unroll") for (int k = 0; k < 2; ++k) dst[m][k] = *(const PG8_LAS bf16x8*)(lds + PG8_SA(b, h) + aoff + m * 2048 + k * 1024); } while (0)
; #define PG8_LDB(dst, b, h) do { _Pragma("unroll") for (int n = 0; n < 2; ++n) _Pragma("unroll") for (int k = 0; k < 2; ++k) dst[n][k] = *(const PG8_LAS bf16x8*)(lds + PG8_SB(b, h) + boff + n * 2048 + k * 1024); } while (0)
; #define PG8_MMA(ai, bj, At, Bt) do { __builtin_amdgcn_s_setprio(1); _Pragma("unroll") for (int m = 0; m < 4; ++m) _Pragma("unroll") for (int n = 0; n < 2; ++n) _Pragma("unroll") for (int k = 0; k < 2; ++k) \
;         acc[ai][bj][m][n] = __builtin_amdgcn_mfma_f32_16x16x32_bf16(Bt[n][k], At[m][k], acc[ai][bj][m][n], 0, 0, 0); __builtin_amdgcn_s_setprio(0); } while (0)
; #define PG8_WAIT_V(n) asm volatile("s_waitcnt vmcnt(" #n ")" ::: "memory")
; #define PG8_WAIT_L(n) asm volatile("s_waitcnt lgkmcnt(" #n ")" ::: "memory")
; #define PG8_BAR __builtin_amdgcn_s_barrier()
; #define PG8_SCHED __builtin_amdgcn_sched_barrier(0)
; template <class Epi, class Sched, bool ALIGN_EPI = false, bool SP2 = false>
; __device__ __forceinline__ void gemm_phase(PG8_LAS unsigned char* lds, const Gemm g, const Sched& S, const Epi& E) {
;     ...
;             PG8_WAIT_V(8); PG8_WAIT_L(0); PG8_BAR; PG8_MMA(1, 0, At, B0); PG8_MMA(1, 1, At, B1); PG8_BAR; PG8_SCHED;
;             PG8_LDB(B0, 1, 0); PG8_LDB(B1, 1, 1); PG8_SCHED; PG8_LDA(At, 1, 0); PG8_STAGE(PG8_SA(0, 1), a2 + hstep, voffA);
;             PG8_WAIT_V(8); PG8_WAIT_L(0); PG8_BAR; PG8_MMA(0, 0, At, B0); PG8_MMA(0, 1, At, B1); PG8_BAR; PG8_SCHED;
;             PG8_LDA(At, 1, 1); PG8_STAGE(PG8_SB(1, 0), b3, voffB); PG8_STAGE(PG8_SB(1, 1), b3 + hstep, voffB); PG8_STAGE(PG8_SA(1, 0), a3, voffA);
	s_setprio 2
	v_mfma_f32_16x16x32_bf16 v[16:19], v[174:177], v[206:209], v[16:19]
	v_mfma_f32_16x16x32_bf16 v[4:7], v[148:151], v[214:217], v[4:7]
	v_mfma_f32_16x16x32_bf16 v[0:3], v[174:177], v[214:217], v[0:3]
	s_setprio 0
	s_add_i32 s24, 0, 0x18000
	s_add_i32 s25, 0, 0x1c000
	s_add_u32 s18, s38, 0x160000
	s_addc_u32 s19, s39, 0
	s_mov_b32 m0, s45
	v_lshl_add_u64 v[230:231], s[18:19], 0, v[158:159]
	global_load_lds_dwordx4 v[230:231], off
	s_mov_b32 m0, s46
	v_lshl_add_u64 v[230:231], s[18:19], 0, v[154:155]
	global_load_lds_dwordx4 v[230:231], off
	v_add_u32_e32 v140, 0x18000, v172
	v_add_u32_e32 v174, 0x1c000, v172
	ds_read_b128 v[128:131], v140
	ds_read_b128 v[132:135], v140 offset:1024
	ds_read_b128 v[136:139], v140 offset:2048
	ds_read_b128 v[140:143], v140 offset:3072
	ds_read_b128 v[144:147], v174
	ds_read_b128 v[148:151], v174 offset:1024
	ds_read_b128 v[164:167], v174 offset:2048
	ds_read_b128 v[174:177], v174 offset:3072
	ds_read_b128 v[178:181], v173 offset:32768
	ds_read_b128 v[182:185], v173 offset:33792
	ds_read_b128 v[186:189], v173 offset:34816
	ds_read_b128 v[194:197], v173 offset:35840
	ds_read_b128 v[202:205], v173 offset:36864
	ds_read_b128 v[206:209], v173 offset:37888
	ds_read_b128 v[210:213], v173 offset:38912
	ds_read_b128 v[214:217], v173 offset:39936
	s_waitcnt vmcnt(8)
	s_waitcnt lgkmcnt(0)
	s_barrier
	s_setprio 1
	s_waitcnt lgkmcnt(0)
	v_mfma_f32_16x16x32_bf16 v[124:127], v[128:131], v[178:181], v[124:127]
	v_mfma_f32_16x16x32_bf16 v[120:123], v[136:139], v[178:181], v[120:123]
	v_mfma_f32_16x16x32_bf16 v[108:111], v[128:131], v[186:189], v[108:111]
	v_mfma_f32_16x16x32_bf16 v[104:107], v[136:139], v[186:189], v[104:107]
	v_mfma_f32_16x16x32_bf16 v[92:95], v[128:131], v[202:205], v[92:95]
	v_mfma_f32_16x16x32_bf16 v[88:91], v[136:139], v[202:205], v[88:91]
	v_mfma_f32_16x16x32_bf16 v[76:79], v[128:131], v[210:213], v[76:79]
	v_mfma_f32_16x16x32_bf16 v[72:75], v[136:139], v[210:213], v[72:75]
	v_mfma_f32_16x16x32_bf16 v[124:127], v[132:135], v[182:185], v[124:127]
	v_mfma_f32_16x16x32_bf16 v[120:123], v[140:143], v[182:185], v[120:123]
	v_mfma_f32_16x16x32_bf16 v[108:111], v[132:135], v[194:197], v[108:111]
	v_mfma_f32_16x16x32_bf16 v[104:107], v[140:143], v[194:197], v[104:107]
	v_mfma_f32_16x16x32_bf16 v[92:95], v[132:135], v[206:209], v[92:95]
	v_mfma_f32_16x16x32_bf16 v[88:91], v[140:143], v[206:209], v[88:91]
	v_mfma_f32_16x16x32_bf16 v[76:79], v[132:135], v[214:217], v[76:79]
	v_mfma_f32_16x16x32_bf16 v[72:75], v[140:143], v[214:217], v[72:75]
	s_setprio 0
	s_setprio 1
	v_mfma_f32_16x16x32_bf16 v[116:119], v[144:147], v[178:181], v[116:119]
	v_mfma_f32_16x16x32_bf16 v[112:115], v[164:167], v[178:181], v[112:115]
	v_mfma_f32_16x16x32_bf16 v[100:103], v[144:147], v[186:189], v[100:103]
	v_mfma_f32_16x16x32_bf16 v[96:99], v[164:167], v[186:189], v[96:99]
	v_mfma_f32_16x16x32_bf16 v[84:87], v[144:147], v[202:205], v[84:87]
	v_mfma_f32_16x16x32_bf16 v[80:83], v[164:167], v[202:205], v[80:83]
	v_mfma_f32_16x16x32_bf16 v[68:71], v[144:147], v[210:213], v[68:71]
	v_mfma_f32_16x16x32_bf16 v[64:67], v[164:167], v[210:213], v[64:67]
	v_mfma_f32_16x16x32_bf16 v[116:119], v[148:151], v[182:185], v[116:119]
	v_mfma_f32_16x16x32_bf16 v[112:115], v[174:177], v[182:185], v[112:115]
	v_mfma_f32_16x16x32_bf16 v[100:103], v[148:151], v[194:197], v[100:103]
	v_mfma_f32_16x16x32_bf16 v[96:99], v[174:177], v[194:197], v[96:99]
	v_mfma_f32_16x16x32_bf16 v[84:87], v[148:151], v[206:209], v[84:87]
	s_barrier
	s_setprio 2
	v_mfma_f32_16x16x32_bf16 v[80:83], v[174:177], v[206:209], v[80:83]
	v_mfma_f32_16x16x32_bf16 v[68:71], v[148:151], v[214:217], v[68:71]
	v_mfma_f32_16x16x32_bf16 v[64:67], v[174:177], v[214:217], v[64:67]
	s_setprio 0
	s_add_i32 s18, s24, s43
	v_lshl_add_u64 v[168:169], v[168:169], 0, s[16:17]
	s_mov_b32 m0, s18
	s_nop 0
	global_load_lds_dwordx4 v[168:169], off
	s_add_i32 m0, s18, 0x2000
	s_add_u32 s18, s36, 0x160080
	v_lshl_add_u64 v[168:169], v[190:191], 0, s[16:17]
	s_addc_u32 s19, s37, 0
	s_add_i32 s24, s25, s43
	global_load_lds_dwordx4 v[168:169], off
	s_mov_b32 m0, s24
	v_lshl_add_u64 v[168:169], s[18:19], 0, v[156:157]
	global_load_lds_dwordx4 v[168:169], off
	s_add_i32 m0, s24, 0x2000
	v_lshl_add_u64 v[168:169], s[18:19], 0, v[152:153]
	global_load_lds_dwordx4 v[168:169], off
	s_mov_b32 m0, s51
	v_lshl_add_u64 v[168:169], v[218:219], 0, s[16:17]
	global_load_lds_dwordx4 v[168:169], off
	s_mov_b32 m0, s52
	v_lshl_add_u64 v[168:169], v[220:221], 0, s[16:17]
	global_load_lds_dwordx4 v[168:169], off
	ds_read_b128 v[178:181], v173 offset:49152
	ds_read_b128 v[182:185], v173 offset:50176
	ds_read_b128 v[186:189], v173 offset:51200
	ds_read_b128 v[194:197], v173 offset:52224
	ds_read_b128 v[202:205], v173 offset:53248
	ds_read_b128 v[206:209], v173 offset:54272
	ds_read_b128 v[210:213], v173 offset:55296
	ds_read_b128 v[214:217], v173 offset:56320
	s_waitcnt vmcnt(8)
	s_waitcnt lgkmcnt(0)
	s_barrier
; #define PG8_STAGE(bufoff, gbase, voff) do { _Pragma("unroll") for (int _i = 0; _i < 2; ++_i) \
;         __builtin_amdgcn_global_load_lds((const unsigned*)((const char*)(gbase) + (voff)[_i]), (PG8_LAS unsigned*)(lds + (bufoff) + ldsw + _i * 8192), 16, 0, 0); } while (0)
; #define PG8_LDA(dst, b, h) do { _Pragma("unroll") for (int m = 0; m < 4; ++m) _Pragma("unroll") for (int k = 0; k < 2; ++k) dst[m][k] = *(const PG8_LAS bf16x8*)(lds + PG8_SA(b, h) + aoff + m * 2048 + k * 1024); } while (0)
; #define PG8_LDB(dst, b, h) do { _Pragma("unroll") for (int n = 0; n < 2; ++n) _Pragma("unroll") for (int k = 0; k < 2; ++k) dst[n][k] = *(const PG8_LAS bf16x8*)(lds + PG8_SB(b, h) + boff + n * 2048 + k * 1024); } while (0)
; #define PG8_MMA(ai, bj, At, Bt) do { __builtin_amdgcn_s_setprio(1); _Pragma("unroll") for (int m = 0; m < 4; ++m) _Pragma("unroll") for (int n = 0; n < 2; ++n) _Pragma("unroll") for (int k = 0; k < 2; ++k) \
;         acc[ai][bj][m][n] = __builtin_amdgcn_mfma_f32_16x16x32_bf16(Bt[n][k], At[m][k], acc[ai][bj][m][n], 0, 0, 0); __builtin_amdgcn_s_setprio(0); } while (0)
; #define PG8_WAIT_V(n) asm volatile("s_waitcnt vmcnt(" #n ")" ::: "memory")
; template <class Epi, class Sched, bool ALIGN_EPI = false, bool SP2 = false>
; __device__ __forceinline__ void gemm_phase(PG8_LAS unsigned char* lds, const Gemm g, const Sched& S, const Epi& E) {
;     ...
;             PG8_LDB(B0, 0, 0); PG8_LDB(B1, 0, 1); PG8_SCHED; PG8_LDA(At, 0, 0); PG8_STAGE(PG8_SA(1, 1), a1 + hstep, voffA);
;             PG8_WAIT_V(8); PG8_WAIT_L(0); PG8_BAR; PG8_MMA(0, 0, At, B0); PG8_MMA(0, 1, At, B1); PG8_BAR; PG8_SCHED;
;             PG8_LDA(At, 0, 1); PG8_STAGE(PG8_SB(0, 0), b2, voffB); PG8_STAGE(PG8_SB(0, 1), b2 + hstep, voffB); PG8_STAGE(PG8_SA(0, 0), a2, voffA);
;             PG8_WAIT_V(8); PG8_WAIT_L(0); PG8_BAR; PG8_MMA(1, 0, At, B0); PG8_MMA(1, 1, At, B1); PG8_BAR; PG8_SCHED;
;             PG8_LDB(B0, 1, 0); PG8_LDB(B1, 1, 1); PG8_SCHED; PG8_LDA(At, 1, 0); PG8_STAGE(PG8_SA(0, 1), a2 + hstep, voffA);
;             PG8_WAIT_V(8); PG8_WAIT_L(0); PG8_BAR; PG8_MMA(0, 0, At, B0); PG8_MMA(0, 1, At, B1); PG8_BAR; PG8_SCHED;
;             PG8_LDA(At, 1, 1); PG8_STAGE(PG8_SB(1, 0), b3, voffB); PG8_STAGE(PG8_SB(1, 1), b3 + hstep, voffB); PG8_STAGE(PG8_SA(1, 0), a3, voffA);
;             PG8_WAIT_V(8); PG8_WAIT_L(0); PG8_BAR; PG8_MMA(1, 0, At, B0); PG8_MMA(1, 1, At, B1); PG8_BAR; PG8_SCHED;
	s_setprio 1
	s_waitcnt lgkmcnt(0)
	v_mfma_f32_16x16x32_bf16 v[60:63], v[128:131], v[178:181], v[60:63]
	v_mfma_f32_16x16x32_bf16 v[56:59], v[136:139], v[178:181], v[56:59]
	v_mfma_f32_16x16x32_bf16 v[44:47], v[128:131], v[186:189], v[44:47]
	v_mfma_f32_16x16x32_bf16 v[40:43], v[136:139], v[186:189], v[40:43]
	v_mfma_f32_16x16x32_bf16 v[28:31], v[128:131], v[202:205], v[28:31]
	v_mfma_f32_16x16x32_bf16 v[24:27], v[136:139], v[202:205], v[24:27]
	v_mfma_f32_16x16x32_bf16 v[12:15], v[128:131], v[210:213], v[12:15]
	v_mfma_f32_16x16x32_bf16 v[8:11], v[136:139], v[210:213], v[8:11]
	v_mfma_f32_16x16x32_bf16 v[60:63], v[132:135], v[182:185], v[60:63]
	v_mfma_f32_16x16x32_bf16 v[56:59], v[140:143], v[182:185], v[56:59]
	v_mfma_f32_16x16x32_bf16 v[44:47], v[132:135], v[194:197], v[44:47]
	v_mfma_f32_16x16x32_bf16 v[40:43], v[140:143], v[194:197], v[40:43]
	v_mfma_f32_16x16x32_bf16 v[28:31], v[132:135], v[206:209], v[28:31]
	v_mfma_f32_16x16x32_bf16 v[24:27], v[140:143], v[206:209], v[24:27]
	v_mfma_f32_16x16x32_bf16 v[12:15], v[132:135], v[214:217], v[12:15]
	v_mfma_f32_16x16x32_bf16 v[8:11], v[140:143], v[214:217], v[8:11]
	s_setprio 0
	s_setprio 1
	v_mfma_f32_16x16x32_bf16 v[52:55], v[144:147], v[178:181], v[52:55]
	v_mfma_f32_16x16x32_bf16 v[48:51], v[164:167], v[178:181], v[48:51]
	v_mfma_f32_16x16x32_bf16 v[36:39], v[144:147], v[186:189], v[36:39]
	v_mfma_f32_16x16x32_bf16 v[32:35], v[164:167], v[186:189], v[32:35]
	v_mfma_f32_16x16x32_bf16 v[20:23], v[144:147], v[202:205], v[20:23]
	v_mfma_f32_16x16x32_bf16 v[16:19], v[164:167], v[202:205], v[16:19]
	v_mfma_f32_16x16x32_bf16 v[4:7], v[144:147], v[210:213], v[4:7]
	v_mfma_f32_16x16x32_bf16 v[0:3], v[164:167], v[210:213], v[0:3]
	v_mfma_f32_16x16x32_bf16 v[52:55], v[148:151], v[182:185], v[52:55]
	v_mfma_f32_16x16x32_bf16 v[48:51], v[174:177], v[182:185], v[48:51]
	v_mfma_f32_16x16x32_bf16 v[36:39], v[148:151], v[194:197], v[36:39]
	v_mfma_f32_16x16x32_bf16 v[32:35], v[174:177], v[194:197], v[32:35]
	v_mfma_f32_16x16x32_bf16 v[20:23], v[148:151], v[206:209], v[20:23]
	s_barrier
	s_setprio 2
	v_mfma_f32_16x16x32_bf16 v[16:19], v[174:177], v[206:209], v[16:19]
	v_mfma_f32_16x16x32_bf16 v[4:7], v[148:151], v[214:217], v[4:7]
	v_mfma_f32_16x16x32_bf16 v[0:3], v[174:177], v[214:217], v[0:3]
	s_setprio 0
	s_add_i32 s61, s61, 2
	s_add_u32 s59, s59, 0x100
	s_addc_u32 s60, s60, 0
	s_cmpk_gt_u32 s61, 0x55
	s_mov_b64 s[18:19], s[30:31]
	s_branch .LBB0_817
.LBB0_817:
	v_add_u32_e32 v140, 0x10000, v172
	v_add_u32_e32 v168, 0x14000, v172
	ds_read_b128 v[128:131], v140
	ds_read_b128 v[132:135], v140 offset:1024
	ds_read_b128 v[136:139], v140 offset:2048
	ds_read_b128 v[140:143], v140 offset:3072
	ds_read_b128 v[144:147], v168
	ds_read_b128 v[148:151], v168 offset:1024
	ds_read_b128 v[164:167], v168 offset:2048
	ds_read_b128 v[174:177], v168 offset:3072
	v_lshl_add_u64 v[168:169], s[18:19], 0, v[160:161]
	s_add_i32 m0, s2, 0xc000
	ds_read_b128 v[178:181], v173
	ds_read_b128 v[182:185], v173 offset:1024
	ds_read_b128 v[186:189], v173 offset:2048
	ds_read_b128 v[194:197], v173 offset:3072
	ds_read_b128 v[202:205], v173 offset:4096
	ds_read_b128 v[206:209], v173 offset:5120
	ds_read_b128 v[210:213], v173 offset:6144
	ds_read_b128 v[214:217], v173 offset:7168
	global_load_lds_dwordx4 v[168:169], off
	s_add_i32 m0, s2, 0xe000
	v_lshl_add_u64 v[168:169], s[18:19], 0, v[162:163]
	global_load_lds_dwordx4 v[168:169], off
	s_add_u32 s30, s18, 0x100
	s_addc_u32 s31, s19, 0
	s_add_i32 s24, 0, 0x10000
	s_cmpk_eq_i32 s61, 0x54
	s_cselect_b32 s39, s5, s31
	s_cselect_b32 s38, s4, s30
	s_cselect_b32 s37, s15, s60
	s_cselect_b32 s36, s14, s59
	s_add_i32 s25, 0, 0x14000
	s_waitcnt vmcnt(8)
	s_waitcnt lgkmcnt(0)
	s_barrier
	s_setprio 1
	s_waitcnt lgkmcnt(0)
	v_mfma_f32_16x16x32_bf16 v[124:127], v[128:131], v[178:181], v[124:127]
	v_mfma_f32_16x16x32_bf16 v[120:123], v[136:139], v[178:181], v[120:123]
	v_mfma_f32_16x16x32_bf16 v[108:111], v[128:131], v[186:189], v[108:111]
	v_mfma_f32_16x16x32_bf16 v[104:107], v[136:139], v[186:189], v[104:107]
	v_mfma_f32_16x16x32_bf16 v[92:95], v[128:131], v[202:205], v[92:95]
	v_mfma_f32_16x16x32_bf16 v[88:91], v[136:139], v[202:205], v[88:91]
	v_mfma_f32_16x16x32_bf16 v[76:79], v[128:131], v[210:213], v[76:79]
	v_mfma_f32_16x16x32_bf16 v[72:75], v[136:139], v[210:213], v[72:75]
	v_mfma_f32_16x16x32_bf16 v[124:127], v[132:135], v[182:185], v[124:127]
	v_mfma_f32_16x16x32_bf16 v[120:123], v[140:143], v[182:185], v[120:123]
	v_mfma_f32_16x16x32_bf16 v[108:111], v[132:135], v[194:197], v[108:111]
	v_mfma_f32_16x16x32_bf16 v[104:107], v[140:143], v[194:197], v[104:107]
	v_mfma_f32_16x16x32_bf16 v[92:95], v[132:135], v[206:209], v[92:95]
	v_mfma_f32_16x16x32_bf16 v[88:91], v[140:143], v[206:209], v[88:91]
	v_mfma_f32_16x16x32_bf16 v[76:79], v[132:135], v[214:217], v[76:79]
	v_mfma_f32_16x16x32_bf16 v[72:75], v[140:143], v[214:217], v[72:75]
	s_setprio 0
	s_setprio 1
	v_mfma_f32_16x16x32_bf16 v[116:119], v[144:147], v[178:181], v[116:119]
	v_mfma_f32_16x16x32_bf16 v[112:115], v[164:167], v[178:181], v[112:115]
	v_mfma_f32_16x16x32_bf16 v[100:103], v[144:147], v[186:189], v[100:103]
	v_mfma_f32_16x16x32_bf16 v[96:99], v[164:167], v[186:189], v[96:99]
	v_mfma_f32_16x16x32_bf16 v[84:87], v[144:147], v[202:205], v[84:87]
	v_mfma_f32_16x16x32_bf16 v[80:83], v[164:167], v[202:205], v[80:83]
	v_mfma_f32_16x16x32_bf16 v[68:71], v[144:147], v[210:213], v[68:71]
	v_mfma_f32_16x16x32_bf16 v[64:67], v[164:167], v[210:213], v[64:67]
	v_mfma_f32_16x16x32_bf16 v[116:119], v[148:151], v[182:185], v[116:119]
	v_mfma_f32_16x16x32_bf16 v[112:115], v[174:177], v[182:185], v[112:115]
	v_mfma_f32_16x16x32_bf16 v[100:103], v[148:151], v[194:197], v[100:103]
	v_mfma_f32_16x16x32_bf16 v[96:99], v[174:177], v[194:197], v[96:99]
	v_mfma_f32_16x16x32_bf16 v[84:87], v[148:151], v[206:209], v[84:87]
	s_barrier
; #define PG8_STAGE(bufoff, gbase, voff) do { _Pragma("unroll") for (int _i = 0; _i < 2; ++_i) \
;         __builtin_amdgcn_global_load_lds((const unsigned*)((const char*)(gbase) + (voff)[_i]), (PG8_LAS unsigned*)(lds + (bufoff) + ldsw + _i * 8192), 16, 0, 0); } while (0)
; #define PG8_LDA(dst, b, h) do { _Pragma("unroll") for (int m = 0; m < 4; ++m) _Pragma("unroll") for (int k = 0; k < 2; ++k) dst[m][k] = *(const PG8_LAS bf16x8*)(lds + PG8_SA(b, h) + aoff + m * 2048 + k * 1024); } while (0)
; #define PG8_LDB(dst, b, h) do { _Pragma("unroll") for (int n = 0; n < 2; ++n) _Pragma("unroll") for (int k = 0; k < 2; ++k) dst[n][k] = *(const PG8_LAS bf16x8*)(lds + PG8_SB(b, h) + boff + n * 2048 + k * 1024); } while (0)
; #define PG8_MMA(ai, bj, At, Bt) do { __builtin_amdgcn_s_setprio(1); _Pragma("unroll") for (int m = 0; m < 4; ++m) _Pragma("unroll") for (int n = 0; n < 2; ++n) _Pragma("unroll") for (int k = 0; k < 2; ++k) \
;         acc[ai][bj][m][n] = __builtin_amdgcn_mfma_f32_16x16x32_bf16(Bt[n][k], At[m][k], acc[ai][bj][m][n], 0, 0, 0); __builtin_amdgcn_s_setprio(0); } while (0)
; #define PG8_WAIT_V(n) asm volatile("s_waitcnt vmcnt(" #n ")" ::: "memory")
; #define PG8_WAIT_L(n) asm volatile("s_waitcnt lgkmcnt(" #n ")" ::: "memory")
; #define PG8_BAR __builtin_amdgcn_s_barrier()
; #define PG8_SCHED __builtin_amdgcn_sched_barrier(0)
; template <class Epi, class Sched, bool ALIGN_EPI = false, bool SP2 = false>
; __device__ __forceinline__ void gemm_phase(PG8_LAS unsigned char* lds, const Gemm g, const Sched& S, const Epi& E) {
;     ...
;             PG8_WAIT_V(8); PG8_WAIT_L(0); PG8_BAR; PG8_MMA(0, 0, At, B0); PG8_MMA(0, 1, At, B1); PG8_BAR; PG8_SCHED;
;             PG8_LDA(At, 0, 1); PG8_STAGE(PG8_SB(0, 0), b2, voffB); PG8_STAGE(PG8_SB(0, 1), b2 + hstep, voffB); PG8_STAGE(PG8_SA(0, 0), a2, voffA);
;             PG8_WAIT_V(8); PG8_WAIT_L(0); PG8_BAR; PG8_MMA(1, 0, At, B0); PG8_MMA(1, 1, At, B1); PG8_BAR; PG8_SCHED;
;             PG8_LDB(B0, 1, 0); PG8_LDB(B1, 1, 1); PG8_SCHED; PG8_LDA(At, 1, 0); PG8_STAGE(PG8_SA(0, 1), a2 + hstep, voffA);
;             PG8_WAIT_V(8); PG8_WAIT_L(0); PG8_BAR; PG8_MMA(0, 0, At, B0); PG8_MMA(0, 1, At, B1); PG8_BAR; PG8_SCHED;
	s_setprio 2
	v_mfma_f32_16x16x32_bf16 v[80:83], v[174:177], v[206:209], v[80:83]
	v_mfma_f32_16x16x32_bf16 v[68:71], v[148:151], v[214:217], v[68:71]
	v_mfma_f32_16x16x32_bf16 v[64:67], v[174:177], v[214:217], v[64:67]
	s_setprio 0
	s_add_i32 s18, s24, s43
	v_lshl_add_u64 v[168:169], s[36:37], 0, v[156:157]
	s_mov_b32 m0, s18
	s_nop 0
	global_load_lds_dwordx4 v[168:169], off
	s_add_i32 m0, s18, 0x2000
	s_add_u32 s18, s36, 0x160000
	v_lshl_add_u64 v[190:191], s[36:37], 0, v[152:153]
	s_addc_u32 s19, s37, 0
	s_add_i32 s24, s25, s43
	global_load_lds_dwordx4 v[190:191], off
	v_lshl_add_u64 v[218:219], s[18:19], 0, v[156:157]
	s_mov_b32 m0, s24
	v_lshl_add_u64 v[220:221], s[38:39], 0, v[154:155]
	global_load_lds_dwordx4 v[218:219], off
	s_add_i32 m0, s24, 0x2000
	v_lshl_add_u64 v[218:219], s[18:19], 0, v[152:153]
	global_load_lds_dwordx4 v[218:219], off
	s_mov_b32 m0, s2
	v_lshl_add_u64 v[218:219], s[38:39], 0, v[158:159]
	global_load_lds_dwordx4 v[218:219], off
	s_mov_b32 m0, s44
	s_nop 0
	global_load_lds_dwordx4 v[220:221], off
	ds_read_b128 v[178:181], v173 offset:16384
	ds_read_b128 v[182:185], v173 offset:17408
	ds_read_b128 v[186:189], v173 offset:18432
	ds_read_b128 v[194:197], v173 offset:19456
	ds_read_b128 v[202:205], v173 offset:20480
	ds_read_b128 v[206:209], v173 offset:21504
	ds_read_b128 v[210:213], v173 offset:22528
	ds_read_b128 v[214:217], v173 offset:23552
	s_waitcnt vmcnt(8)
	s_waitcnt lgkmcnt(0)
	s_barrier
	s_setprio 1
	s_waitcnt lgkmcnt(0)
	v_mfma_f32_16x16x32_bf16 v[60:63], v[128:131], v[178:181], v[60:63]
	v_mfma_f32_16x16x32_bf16 v[56:59], v[136:139], v[178:181], v[56:59]
	v_mfma_f32_16x16x32_bf16 v[44:47], v[128:131], v[186:189], v[44:47]
	v_mfma_f32_16x16x32_bf16 v[40:43], v[136:139], v[186:189], v[40:43]
	v_mfma_f32_16x16x32_bf16 v[28:31], v[128:131], v[202:205], v[28:31]
	v_mfma_f32_16x16x32_bf16 v[24:27], v[136:139], v[202:205], v[24:27]
	v_mfma_f32_16x16x32_bf16 v[12:15], v[128:131], v[210:213], v[12:15]
	v_mfma_f32_16x16x32_bf16 v[8:11], v[136:139], v[210:213], v[8:11]
	v_mfma_f32_16x16x32_bf16 v[60:63], v[132:135], v[182:185], v[60:63]
	v_mfma_f32_16x16x32_bf16 v[56:59], v[140:143], v[182:185], v[56:59]
	v_mfma_f32_16x16x32_bf16 v[44:47], v[132:135], v[194:197], v[44:47]
	v_mfma_f32_16x16x32_bf16 v[40:43], v[140:143], v[194:197], v[40:43]
	v_mfma_f32_16x16x32_bf16 v[28:31], v[132:135], v[206:209], v[28:31]
	v_mfma_f32_16x16x32_bf16 v[24:27], v[140:143], v[206:209], v[24:27]
	v_mfma_f32_16x16x32_bf16 v[12:15], v[132:135], v[214:217], v[12:15]
	v_mfma_f32_16x16x32_bf16 v[8:11], v[140:143], v[214:217], v[8:11]
	s_setprio 0
	s_setprio 1
	v_mfma_f32_16x16x32_bf16 v[52:55], v[144:147], v[178:181], v[52:55]
	v_mfma_f32_16x16x32_bf16 v[48:51], v[164:167], v[178:181], v[48:51]
	v_mfma_f32_16x16x32_bf16 v[36:39], v[144:147], v[186:189], v[36:39]
	v_mfma_f32_16x16x32_bf16 v[32:35], v[164:167], v[186:189], v[32:35]
	v_mfma_f32_16x16x32_bf16 v[20:23], v[144:147], v[202:205], v[20:23]
	v_mfma_f32_16x16x32_bf16 v[16:19], v[164:167], v[202:205], v[16:19]
	v_mfma_f32_16x16x32_bf16 v[4:7], v[144:147], v[210:213], v[4:7]
	v_mfma_f32_16x16x32_bf16 v[0:3], v[164:167], v[210:213], v[0:3]
	v_mfma_f32_16x16x32_bf16 v[52:55], v[148:151], v[182:185], v[52:55]
	v_mfma_f32_16x16x32_bf16 v[48:51], v[174:177], v[182:185], v[48:51]
	v_mfma_f32_16x16x32_bf16 v[36:39], v[148:151], v[194:197], v[36:39]
	v_mfma_f32_16x16x32_bf16 v[32:35], v[174:177], v[194:197], v[32:35]
	v_mfma_f32_16x16x32_bf16 v[20:23], v[148:151], v[206:209], v[20:23]
	s_barrier
	s_setprio 2
	v_mfma_f32_16x16x32_bf16 v[16:19], v[174:177], v[206:209], v[16:19]
	v_mfma_f32_16x16x32_bf16 v[4:7], v[148:151], v[214:217], v[4:7]
	v_mfma_f32_16x16x32_bf16 v[0:3], v[174:177], v[214:217], v[0:3]
	s_setprio 0
	s_add_i32 s24, 0, 0x18000
	s_add_i32 s25, 0, 0x1c000
	s_add_u32 s18, s38, 0x160000
	s_addc_u32 s19, s39, 0
	s_mov_b32 m0, s45
	v_lshl_add_u64 v[230:231], s[18:19], 0, v[158:159]
	global_load_lds_dwordx4 v[230:231], off
	s_mov_b32 m0, s46
	v_lshl_add_u64 v[230:231], s[18:19], 0, v[154:155]
	global_load_lds_dwordx4 v[230:231], off
	v_add_u32_e32 v140, 0x18000, v172
	v_add_u32_e32 v174, 0x1c000, v172
	ds_read_b128 v[128:131], v140
	ds_read_b128 v[132:135], v140 offset:1024
	ds_read_b128 v[136:139], v140 offset:2048
	ds_read_b128 v[140:143], v140 offset:3072
	ds_read_b128 v[144:147], v174
	ds_read_b128 v[148:151], v174 offset:1024
	ds_read_b128 v[164:167], v174 offset:2048
	ds_read_b128 v[174:177], v174 offset:3072
	ds_read_b128 v[178:181], v173 offset:32768
	ds_read_b128 v[182:185], v173 offset:33792
	ds_read_b128 v[186:189], v173 offset:34816
	ds_read_b128 v[194:197], v173 offset:35840
	ds_read_b128 v[202:205], v173 offset:36864
	ds_read_b128 v[206:209], v173 offset:37888
	ds_read_b128 v[210:213], v173 offset:38912
	ds_read_b128 v[214:217], v173 offset:39936
	s_waitcnt vmcnt(8)
	s_waitcnt lgkmcnt(0)
	s_barrier
; #define PG8_STAGE(bufoff, gbase, voff) do { _Pragma("unroll") for (int _i = 0; _i < 2; ++_i) \
;         __builtin_amdgcn_global_load_lds((const unsigned*)((const char*)(gbase) + (voff)[_i]), (PG8_LAS unsigned*)(lds + (bufoff) + ldsw + _i * 8192), 16, 0, 0); } while (0)
; #define PG8_LDA(dst, b, h) do { _Pragma("unroll") for (int m = 0; m < 4; ++m) _Pragma("unroll") for (int k = 0; k < 2; ++k) dst[m][k] = *(const PG8_LAS bf16x8*)(lds + PG8_SA(b, h) + aoff + m * 2048 + k * 1024); } while (0)
; #define PG8_MMA(ai, bj, At, Bt) do { __builtin_amdgcn_s_setprio(1); _Pragma("unroll") for (int m = 0; m < 4; ++m) _Pragma("unroll") for (int n = 0; n < 2; ++n) _Pragma("unroll") for (int k = 0; k < 2; ++k) \
;         acc[ai][bj][m][n] = __builtin_amdgcn_mfma_f32_16x16x32_bf16(Bt[n][k], At[m][k], acc[ai][bj][m][n], 0, 0, 0); __builtin_amdgcn_s_setprio(0); } while (0)
; #define PG8_WAIT_V(n) asm volatile("s_waitcnt vmcnt(" #n ")" ::: "memory")
; #define PG8_WAIT_L(n) asm volatile("s_waitcnt lgkmcnt(" #n ")" ::: "memory")
; #define PG8_BAR __builtin_amdgcn_s_barrier()
; #define PG8_SCHED __builtin_amdgcn_sched_barrier(0)
; template <class Epi, class Sched, bool ALIGN_EPI = false, bool SP2 = false>
; __device__ __forceinline__ void gemm_phase(PG8_LAS unsigned char* lds, const Gemm g, const Sched& S, const Epi& E) {
;     ...
;             PG8_WAIT_V(8); PG8_WAIT_L(0); PG8_BAR; PG8_MMA(0, 0, At, B0); PG8_MMA(0, 1, At, B1); PG8_BAR; PG8_SCHED;
;             PG8_LDA(At, 1, 1); PG8_STAGE(PG8_SB(1, 0), b3, voffB); PG8_STAGE(PG8_SB(1, 1), b3 + hstep, voffB); PG8_STAGE(PG8_SA(1, 0), a3, voffA);
;             PG8_WAIT_V(8); PG8_WAIT_L(0); PG8_BAR; PG8_MMA(1, 0, At, B0); PG8_MMA(1, 1, At, B1); PG8_BAR; PG8_SCHED;
	s_setprio 1
	s_waitcnt lgkmcnt(0)
	v_mfma_f32_16x16x32_bf16 v[124:127], v[128:131], v[178:181], v[124:127]
	v_mfma_f32_16x16x32_bf16 v[120:123], v[136:139], v[178:181], v[120:123]
	v_mfma_f32_16x16x32_bf16 v[108:111], v[128:131], v[186:189], v[108:111]
	v_mfma_f32_16x16x32_bf16 v[104:107], v[136:139], v[186:189], v[104:107]
	v_mfma_f32_16x16x32_bf16 v[92:95], v[128:131], v[202:205], v[92:95]
	v_mfma_f32_16x16x32_bf16 v[88:91], v[136:139], v[202:205], v[88:91]
	v_mfma_f32_16x16x32_bf16 v[76:79], v[128:131], v[210:213], v[76:79]
	v_mfma_f32_16x16x32_bf16 v[72:75], v[136:139], v[210:213], v[72:75]
	v_mfma_f32_16x16x32_bf16 v[124:127], v[132:135], v[182:185], v[124:127]
	v_mfma_f32_16x16x32_bf16 v[120:123], v[140:143], v[182:185], v[120:123]
	v_mfma_f32_16x16x32_bf16 v[108:111], v[132:135], v[194:197], v[108:111]
	v_mfma_f32_16x16x32_bf16 v[104:107], v[140:143], v[194:197], v[104:107]
	v_mfma_f32_16x16x32_bf16 v[92:95], v[132:135], v[206:209], v[92:95]
	v_mfma_f32_16x16x32_bf16 v[88:91], v[140:143], v[206:209], v[88:91]
	v_mfma_f32_16x16x32_bf16 v[76:79], v[132:135], v[214:217], v[76:79]
	v_mfma_f32_16x16x32_bf16 v[72:75], v[140:143], v[214:217], v[72:75]
	s_setprio 0
	s_setprio 1
	v_mfma_f32_16x16x32_bf16 v[116:119], v[144:147], v[178:181], v[116:119]
	v_mfma_f32_16x16x32_bf16 v[112:115], v[164:167], v[178:181], v[112:115]
	v_mfma_f32_16x16x32_bf16 v[100:103], v[144:147], v[186:189], v[100:103]
	v_mfma_f32_16x16x32_bf16 v[96:99], v[164:167], v[186:189], v[96:99]
	v_mfma_f32_16x16x32_bf16 v[84:87], v[144:147], v[202:205], v[84:87]
	v_mfma_f32_16x16x32_bf16 v[80:83], v[164:167], v[202:205], v[80:83]
	v_mfma_f32_16x16x32_bf16 v[68:71], v[144:147], v[210:213], v[68:71]
	v_mfma_f32_16x16x32_bf16 v[64:67], v[164:167], v[210:213], v[64:67]
	v_mfma_f32_16x16x32_bf16 v[116:119], v[148:151], v[182:185], v[116:119]
	v_mfma_f32_16x16x32_bf16 v[112:115], v[174:177], v[182:185], v[112:115]
	v_mfma_f32_16x16x32_bf16 v[100:103], v[148:151], v[194:197], v[100:103]
	v_mfma_f32_16x16x32_bf16 v[96:99], v[174:177], v[194:197], v[96:99]
	v_mfma_f32_16x16x32_bf16 v[84:87], v[148:151], v[206:209], v[84:87]
	s_barrier
	s_setprio 2
	v_mfma_f32_16x16x32_bf16 v[80:83], v[174:177], v[206:209], v[80:83]
	v_mfma_f32_16x16x32_bf16 v[68:71], v[148:151], v[214:217], v[68:71]
	v_mfma_f32_16x16x32_bf16 v[64:67], v[174:177], v[214:217], v[64:67]
	s_setprio 0
	s_add_i32 s18, s24, s43
	v_lshl_add_u64 v[168:169], v[168:169], 0, s[16:17]
	s_mov_b32 m0, s18
	s_nop 0
	global_load_lds_dwordx4 v[168:169], off
	s_add_i32 m0, s18, 0x2000
	s_add_u32 s18, s36, 0x160080
	v_lshl_add_u64 v[168:169], v[190:191], 0, s[16:17]
	s_addc_u32 s19, s37, 0
	s_add_i32 s24, s25, s43
	global_load_lds_dwordx4 v[168:169], off
	s_mov_b32 m0, s24
	v_lshl_add_u64 v[168:169], s[18:19], 0, v[156:157]
	global_load_lds_dwordx4 v[168:169], off
	s_add_i32 m0, s24, 0x2000
	v_lshl_add_u64 v[168:169], s[18:19], 0, v[152:153]
	global_load_lds_dwordx4 v[168:169], off
	s_mov_b32 m0, s51
	v_lshl_add_u64 v[168:169], v[218:219], 0, s[16:17]
	global_load_lds_dwordx4 v[168:169], off
	s_mov_b32 m0, s52
	v_lshl_add_u64 v[168:169], v[220:221], 0, s[16:17]
	global_load_lds_dwordx4 v[168:169], off
	ds_read_b128 v[178:181], v173 offset:49152
	ds_read_b128 v[182:185], v173 offset:50176
	ds_read_b128 v[186:189], v173 offset:51200
	ds_read_b128 v[194:197], v173 offset:52224
	ds_read_b128 v[202:205], v173 offset:53248
	ds_read_b128 v[206:209], v173 offset:54272
	ds_read_b128 v[210:213], v173 offset:55296
	ds_read_b128 v[214:217], v173 offset:56320
	s_waitcnt vmcnt(8)
	s_waitcnt lgkmcnt(0)
	s_barrier
	s_setprio 1
	s_waitcnt lgkmcnt(0)
	v_mfma_f32_16x16x32_bf16 v[60:63], v[128:131], v[178:181], v[60:63]
	v_mfma_f32_16x16x32_bf16 v[56:59], v[136:139], v[178:181], v[56:59]
	v_mfma_f32_16x16x32_bf16 v[44:47], v[128:131], v[186:189], v[44:47]
	v_mfma_f32_16x16x32_bf16 v[40:43], v[136:139], v[186:189], v[40:43]
	v_mfma_f32_16x16x32_bf16 v[28:31], v[128:131], v[202:205], v[28:31]
	v_mfma_f32_16x16x32_bf16 v[24:27], v[136:139], v[202:205], v[24:27]
	v_mfma_f32_16x16x32_bf16 v[12:15], v[128:131], v[210:213], v[12:15]
	v_mfma_f32_16x16x32_bf16 v[8:11], v[136:139], v[210:213], v[8:11]
	v_mfma_f32_16x16x32_bf16 v[60:63], v[132:135], v[182:185], v[60:63]
	v_mfma_f32_16x16x32_bf16 v[56:59], v[140:143], v[182:185], v[56:59]
	v_mfma_f32_16x16x32_bf16 v[44:47], v[132:135], v[194:197], v[44:47]
	v_mfma_f32_16x16x32_bf16 v[40:43], v[140:143], v[194:197], v[40:43]
	v_mfma_f32_16x16x32_bf16 v[28:31], v[132:135], v[206:209], v[28:31]
	v_mfma_f32_16x16x32_bf16 v[24:27], v[140:143], v[206:209], v[24:27]
	v_mfma_f32_16x16x32_bf16 v[12:15], v[132:135], v[214:217], v[12:15]
	v_mfma_f32_16x16x32_bf16 v[8:11], v[140:143], v[214:217], v[8:11]
	s_setprio 0
	s_setprio 1
	v_mfma_f32_16x16x32_bf16 v[52:55], v[144:147], v[178:181], v[52:55]
	v_mfma_f32_16x16x32_bf16 v[48:51], v[164:167], v[178:181], v[48:51]
	v_mfma_f32_16x16x32_bf16 v[36:39], v[144:147], v[186:189], v[36:39]
	v_mfma_f32_16x16x32_bf16 v[32:35], v[164:167], v[186:189], v[32:35]
	v_mfma_f32_16x16x32_bf16 v[20:23], v[144:147], v[202:205], v[20:23]
	v_mfma_f32_16x16x32_bf16 v[16:19], v[164:167], v[202:205], v[16:19]
	v_mfma_f32_16x16x32_bf16 v[4:7], v[144:147], v[210:213], v[4:7]
	v_mfma_f32_16x16x32_bf16 v[0:3], v[164:167], v[210:213], v[0:3]
	v_mfma_f32_16x16x32_bf16 v[52:55], v[148:151], v[182:185], v[52:55]
	v_mfma_f32_16x16x32_bf16 v[48:51], v[174:177], v[182:185], v[48:51]
	v_mfma_f32_16x16x32_bf16 v[36:39], v[148:151], v[194:197], v[36:39]
	v_mfma_f32_16x16x32_bf16 v[32:35], v[174:177], v[194:197], v[32:35]
	v_mfma_f32_16x16x32_bf16 v[20:23], v[148:151], v[206:209], v[20:23]
	s_barrier
	s_setprio 2
	v_mfma_f32_16x16x32_bf16 v[16:19], v[174:177], v[206:209], v[16:19]
	v_mfma_f32_16x16x32_bf16 v[4:7], v[148:151], v[214:217], v[4:7]
	v_mfma_f32_16x16x32_bf16 v[0:3], v[174:177], v[214:217], v[0:3]
	s_setprio 0
	s_add_i32 s61, s61, 2
	s_add_u32 s59, s59, 0x100
	s_addc_u32 s60, s60, 0
	s_cmpk_gt_u32 s61, 0x55
	s_mov_b64 s[18:19], s[30:31]
	s_cbranch_scc0 .LBB0_817
	s_and_b64 vcc, exec, s[12:13]
	s_cbranch_vccz .LBB0_820
	s_barrier
